# GEMM MFMA blocks: priority raise moved in front of the barrier, redundant post-barrier lgkmcnt(0) dropped (first MFMA issues right after release)
# baseline (speedup 1.0000x reference)
.LBB0_757:
	s_ashr_i32 s17, s16, 31
	s_lshl_b64 s[18:19], s[16:17], 20
	s_add_u32 s18, s35, s18
	s_addc_u32 s19, s40, s19
	s_and_b64 s[20:21], s[4:5], exec
	s_cselect_b32 s17, s19, s29
	s_cselect_b32 s23, s18, s28
	s_ashr_i32 s15, s14, 31
	s_lshl_b64 s[20:21], s[14:15], 19
	s_add_u32 s20, s38, s20
	s_addc_u32 s21, s39, s21
	s_and_b64 s[30:31], s[4:5], exec
	s_cselect_b32 s15, s21, s27
	s_cselect_b32 s25, s20, s26
	s_add_u32 s52, s26, 0x100
	s_addc_u32 s53, s27, 0
	s_add_u32 s26, s28, 0x80080
	s_addc_u32 s27, s29, 0
	s_mov_b32 s54, -2
	s_waitcnt lgkmcnt(0)
	s_add_u32 s28, s26, 0xfff80080
	s_addc_u32 s29, s27, -1
	s_add_i32 s55, 0, 0x10000
	s_cmp_eq_u32 s54, 12
	s_cselect_b32 s31, s17, s29
	s_cselect_b32 s30, s23, s28
	s_cselect_b32 s29, s15, s53
	s_cselect_b32 s28, s25, s52
	s_add_i32 s58, 0, 0x14000
	v_add_u32_e32 v156, s55, v145
	v_add_u32_e32 v172, s58, v145
	ds_read_b128 v[140:143], v156
	ds_read_b128 v[148:151], v156 offset:1024
	ds_read_b128 v[152:155], v156 offset:2048
	ds_read_b128 v[156:159], v156 offset:3072
	ds_read_b128 v[160:163], v172
	ds_read_b128 v[164:167], v172 offset:1024
	ds_read_b128 v[168:171], v172 offset:2048
	ds_read_b128 v[172:175], v172 offset:3072
	s_add_i32 m0, s42, 0xc000
	ds_read_b128 v[176:179], v147
	ds_read_b128 v[180:183], v147 offset:1024
	ds_read_b128 v[184:187], v147 offset:2048
	ds_read_b128 v[208:211], v147 offset:3072
	ds_read_b128 v[230:233], v147 offset:4096
	ds_read_b128 v[234:237], v147 offset:5120
	ds_read_b128 v[238:241], v147 offset:6144
	ds_read_b128 v[242:245], v147 offset:7168
	global_load_lds_dwordx4 v138, s[26:27]
	s_add_i32 m0, s42, 0xe000
	s_nop 0
	global_load_lds_dwordx4 v136, s[26:27]
	s_waitcnt vmcnt(8)
	s_waitcnt lgkmcnt(0)
	s_setprio 1
	s_barrier
	v_mfma_f32_16x16x32_bf16 v[126:129], v[140:143], v[176:179], 0
	v_mfma_f32_16x16x32_bf16 v[122:125], v[152:155], v[176:179], 0
	v_mfma_f32_16x16x32_bf16 v[108:111], v[140:143], v[184:187], 0
	v_mfma_f32_16x16x32_bf16 v[104:107], v[152:155], v[184:187], 0
	v_mfma_f32_16x16x32_bf16 v[92:95], v[140:143], v[230:233], 0
	v_mfma_f32_16x16x32_bf16 v[88:91], v[152:155], v[230:233], 0
	v_mfma_f32_16x16x32_bf16 v[76:79], v[140:143], v[238:241], 0
	v_mfma_f32_16x16x32_bf16 v[72:75], v[152:155], v[238:241], 0
	v_mfma_f32_16x16x32_bf16 v[126:129], v[148:151], v[180:183], v[126:129]
	v_mfma_f32_16x16x32_bf16 v[122:125], v[156:159], v[180:183], v[122:125]
	v_mfma_f32_16x16x32_bf16 v[108:111], v[148:151], v[208:211], v[108:111]
	v_mfma_f32_16x16x32_bf16 v[104:107], v[156:159], v[208:211], v[104:107]
	v_mfma_f32_16x16x32_bf16 v[92:95], v[148:151], v[234:237], v[92:95]
	v_mfma_f32_16x16x32_bf16 v[88:91], v[156:159], v[234:237], v[88:91]
	v_mfma_f32_16x16x32_bf16 v[76:79], v[148:151], v[242:245], v[76:79]
	v_mfma_f32_16x16x32_bf16 v[72:75], v[156:159], v[242:245], v[72:75]
	s_setprio 0
	s_setprio 1
	v_mfma_f32_16x16x32_bf16 v[118:121], v[160:163], v[176:179], 0
	v_mfma_f32_16x16x32_bf16 v[114:117], v[168:171], v[176:179], 0
	v_mfma_f32_16x16x32_bf16 v[100:103], v[160:163], v[184:187], 0
	v_mfma_f32_16x16x32_bf16 v[96:99], v[168:171], v[184:187], 0
	v_mfma_f32_16x16x32_bf16 v[84:87], v[160:163], v[230:233], 0
	v_mfma_f32_16x16x32_bf16 v[80:83], v[168:171], v[230:233], 0
	v_mfma_f32_16x16x32_bf16 v[68:71], v[160:163], v[238:241], 0
	v_mfma_f32_16x16x32_bf16 v[64:67], v[168:171], v[238:241], 0
	v_mfma_f32_16x16x32_bf16 v[118:121], v[164:167], v[180:183], v[118:121]
	v_mfma_f32_16x16x32_bf16 v[114:117], v[172:175], v[180:183], v[114:117]
	v_mfma_f32_16x16x32_bf16 v[100:103], v[164:167], v[208:211], v[100:103]
	v_mfma_f32_16x16x32_bf16 v[96:99], v[172:175], v[208:211], v[96:99]
	v_mfma_f32_16x16x32_bf16 v[84:87], v[164:167], v[234:237], v[84:87]
	v_mfma_f32_16x16x32_bf16 v[80:83], v[172:175], v[234:237], v[80:83]
	v_mfma_f32_16x16x32_bf16 v[68:71], v[164:167], v[242:245], v[68:71]
	v_mfma_f32_16x16x32_bf16 v[64:67], v[172:175], v[242:245], v[64:67]
	s_setprio 0
	s_barrier
	s_add_i32 s55, s55, s41
	s_mov_b32 m0, s55
	ds_read_b128 v[176:179], v147 offset:16384
	ds_read_b128 v[180:183], v147 offset:17408
	ds_read_b128 v[184:187], v147 offset:18432
	ds_read_b128 v[208:211], v147 offset:19456
	ds_read_b128 v[230:233], v147 offset:20480
	ds_read_b128 v[234:237], v147 offset:21504
	ds_read_b128 v[238:241], v147 offset:22528
	ds_read_b128 v[242:245], v147 offset:23552
	global_load_lds_dwordx4 v112, s[28:29]
	s_add_i32 m0, s55, 0x2000
	s_add_u32 s56, s28, 0x40000
	v_lshl_add_u64 v[212:213], s[28:29], 0, v[134:135]
	s_addc_u32 s57, s29, 0
	s_add_i32 s55, s58, s41
	global_load_lds_dwordx4 v134, s[28:29]
	s_mov_b32 m0, s55
	v_lshl_add_u64 v[246:247], s[30:31], 0, v[132:133]
	global_load_lds_dwordx4 v112, s[56:57]
	s_add_i32 m0, s55, 0x2000
	s_nop 0
	global_load_lds_dwordx4 v134, s[56:57]
	v_lshl_add_u64 v[228:229], s[30:31], 0, v[130:131]
	s_mov_b32 m0, s42
	s_nop 0
	global_load_lds_dwordx4 v130, s[30:31]
	s_mov_b32 m0, s43
	s_nop 0
	global_load_lds_dwordx4 v132, s[30:31]
	s_waitcnt vmcnt(8)
	s_waitcnt lgkmcnt(0)
	s_setprio 1
	s_barrier
	v_mfma_f32_16x16x32_bf16 v[60:63], v[140:143], v[176:179], 0
	v_mfma_f32_16x16x32_bf16 v[56:59], v[152:155], v[176:179], 0
	v_mfma_f32_16x16x32_bf16 v[44:47], v[140:143], v[184:187], 0
	v_mfma_f32_16x16x32_bf16 v[40:43], v[152:155], v[184:187], 0
	v_mfma_f32_16x16x32_bf16 v[28:31], v[140:143], v[230:233], 0
	v_mfma_f32_16x16x32_bf16 v[24:27], v[152:155], v[230:233], 0
	v_mfma_f32_16x16x32_bf16 v[12:15], v[140:143], v[238:241], 0
	v_mfma_f32_16x16x32_bf16 v[8:11], v[152:155], v[238:241], 0
	v_mfma_f32_16x16x32_bf16 v[60:63], v[148:151], v[180:183], v[60:63]
	v_mfma_f32_16x16x32_bf16 v[56:59], v[156:159], v[180:183], v[56:59]
	v_mfma_f32_16x16x32_bf16 v[44:47], v[148:151], v[208:211], v[44:47]
	v_mfma_f32_16x16x32_bf16 v[40:43], v[156:159], v[208:211], v[40:43]
	v_mfma_f32_16x16x32_bf16 v[28:31], v[148:151], v[234:237], v[28:31]
	v_mfma_f32_16x16x32_bf16 v[24:27], v[156:159], v[234:237], v[24:27]
	v_mfma_f32_16x16x32_bf16 v[12:15], v[148:151], v[242:245], v[12:15]
	v_mfma_f32_16x16x32_bf16 v[8:11], v[156:159], v[242:245], v[8:11]
	s_setprio 0
	s_setprio 1
	v_mfma_f32_16x16x32_bf16 v[52:55], v[160:163], v[176:179], 0
	v_mfma_f32_16x16x32_bf16 v[48:51], v[168:171], v[176:179], 0
	v_mfma_f32_16x16x32_bf16 v[36:39], v[160:163], v[184:187], 0
	v_mfma_f32_16x16x32_bf16 v[32:35], v[168:171], v[184:187], 0
	v_mfma_f32_16x16x32_bf16 v[20:23], v[160:163], v[230:233], 0
	v_mfma_f32_16x16x32_bf16 v[16:19], v[168:171], v[230:233], 0
	v_mfma_f32_16x16x32_bf16 v[4:7], v[160:163], v[238:241], 0
	v_mfma_f32_16x16x32_bf16 v[0:3], v[168:171], v[238:241], 0
	v_mfma_f32_16x16x32_bf16 v[52:55], v[164:167], v[180:183], v[52:55]
	v_mfma_f32_16x16x32_bf16 v[48:51], v[172:175], v[180:183], v[48:51]
	v_mfma_f32_16x16x32_bf16 v[36:39], v[164:167], v[208:211], v[36:39]
	v_mfma_f32_16x16x32_bf16 v[32:35], v[172:175], v[208:211], v[32:35]
	v_mfma_f32_16x16x32_bf16 v[20:23], v[164:167], v[234:237], v[20:23]
	v_mfma_f32_16x16x32_bf16 v[16:19], v[172:175], v[234:237], v[16:19]
	v_mfma_f32_16x16x32_bf16 v[4:7], v[164:167], v[242:245], v[4:7]
	v_mfma_f32_16x16x32_bf16 v[0:3], v[172:175], v[242:245], v[0:3]
	s_setprio 0
	s_barrier
	s_add_i32 s55, 0, 0x18000
	s_add_i32 s56, 0, 0x1c000
	v_add_u32_e32 v156, s55, v145
	v_add_u32_e32 v172, s56, v145
	ds_read_b128 v[140:143], v156
	ds_read_b128 v[148:151], v156 offset:1024
	ds_read_b128 v[152:155], v156 offset:2048
	ds_read_b128 v[156:159], v156 offset:3072
	ds_read_b128 v[160:163], v172
	ds_read_b128 v[164:167], v172 offset:1024
	ds_read_b128 v[168:171], v172 offset:2048
	ds_read_b128 v[172:175], v172 offset:3072
	s_add_u32 s30, s30, 0x80000
	s_addc_u32 s31, s31, 0
	s_mov_b32 m0, s44
	ds_read_b128 v[176:179], v147 offset:32768
	ds_read_b128 v[180:183], v147 offset:33792
	ds_read_b128 v[184:187], v147 offset:34816
	ds_read_b128 v[208:211], v147 offset:35840
	ds_read_b128 v[230:233], v147 offset:36864
	ds_read_b128 v[234:237], v147 offset:37888
	ds_read_b128 v[238:241], v147 offset:38912
	ds_read_b128 v[242:245], v147 offset:39936
	global_load_lds_dwordx4 v130, s[30:31]
	s_mov_b32 m0, s45
	s_nop 0
	global_load_lds_dwordx4 v132, s[30:31]
	s_waitcnt vmcnt(8)
	s_waitcnt lgkmcnt(0)
	s_setprio 1
	s_barrier
	v_mfma_f32_16x16x32_bf16 v[126:129], v[140:143], v[176:179], v[126:129]
	v_mfma_f32_16x16x32_bf16 v[122:125], v[152:155], v[176:179], v[122:125]
	v_mfma_f32_16x16x32_bf16 v[108:111], v[140:143], v[184:187], v[108:111]
	v_mfma_f32_16x16x32_bf16 v[104:107], v[152:155], v[184:187], v[104:107]
	v_mfma_f32_16x16x32_bf16 v[92:95], v[140:143], v[230:233], v[92:95]
	v_mfma_f32_16x16x32_bf16 v[88:91], v[152:155], v[230:233], v[88:91]
	v_mfma_f32_16x16x32_bf16 v[76:79], v[140:143], v[238:241], v[76:79]
	v_mfma_f32_16x16x32_bf16 v[72:75], v[152:155], v[238:241], v[72:75]
	v_mfma_f32_16x16x32_bf16 v[126:129], v[148:151], v[180:183], v[126:129]
	v_mfma_f32_16x16x32_bf16 v[122:125], v[156:159], v[180:183], v[122:125]
	v_mfma_f32_16x16x32_bf16 v[108:111], v[148:151], v[208:211], v[108:111]
	v_mfma_f32_16x16x32_bf16 v[104:107], v[156:159], v[208:211], v[104:107]
	v_mfma_f32_16x16x32_bf16 v[92:95], v[148:151], v[234:237], v[92:95]
	v_mfma_f32_16x16x32_bf16 v[88:91], v[156:159], v[234:237], v[88:91]
	v_mfma_f32_16x16x32_bf16 v[76:79], v[148:151], v[242:245], v[76:79]
	v_mfma_f32_16x16x32_bf16 v[72:75], v[156:159], v[242:245], v[72:75]
	s_setprio 0
	s_setprio 1
	v_mfma_f32_16x16x32_bf16 v[118:121], v[160:163], v[176:179], v[118:121]
	v_mfma_f32_16x16x32_bf16 v[114:117], v[168:171], v[176:179], v[114:117]
	v_mfma_f32_16x16x32_bf16 v[100:103], v[160:163], v[184:187], v[100:103]
	v_mfma_f32_16x16x32_bf16 v[96:99], v[168:171], v[184:187], v[96:99]
	v_mfma_f32_16x16x32_bf16 v[84:87], v[160:163], v[230:233], v[84:87]
	v_mfma_f32_16x16x32_bf16 v[80:83], v[168:171], v[230:233], v[80:83]
	v_mfma_f32_16x16x32_bf16 v[68:71], v[160:163], v[238:241], v[68:71]
	v_mfma_f32_16x16x32_bf16 v[64:67], v[168:171], v[238:241], v[64:67]
	v_mfma_f32_16x16x32_bf16 v[118:121], v[164:167], v[180:183], v[118:121]
	v_mfma_f32_16x16x32_bf16 v[114:117], v[172:175], v[180:183], v[114:117]
	v_mfma_f32_16x16x32_bf16 v[100:103], v[164:167], v[208:211], v[100:103]
	v_mfma_f32_16x16x32_bf16 v[96:99], v[172:175], v[208:211], v[96:99]
	v_mfma_f32_16x16x32_bf16 v[84:87], v[164:167], v[234:237], v[84:87]
	v_mfma_f32_16x16x32_bf16 v[80:83], v[172:175], v[234:237], v[80:83]
	v_mfma_f32_16x16x32_bf16 v[68:71], v[164:167], v[242:245], v[68:71]
	v_mfma_f32_16x16x32_bf16 v[64:67], v[172:175], v[242:245], v[64:67]
	s_setprio 0
	s_barrier
	s_add_i32 s30, s55, s41
	s_mov_b32 m0, s30
	ds_read_b128 v[176:179], v147 offset:49152
	ds_read_b128 v[180:183], v147 offset:50176
	ds_read_b128 v[184:187], v147 offset:51200
	ds_read_b128 v[208:211], v147 offset:52224
	ds_read_b128 v[230:233], v147 offset:53248
	ds_read_b128 v[234:237], v147 offset:54272
	ds_read_b128 v[238:241], v147 offset:55296
	ds_read_b128 v[242:245], v147 offset:56320
	s_add_u32 s98, s28, 0x80
	s_addc_u32 s99, s29, 0
	global_load_lds_dwordx4 v112, s[98:99]
	s_add_i32 m0, s30, 0x2000
	s_add_u32 s28, s28, 0x40080
	v_lshl_add_u64 v[188:189], v[212:213], 0, s[96:97]
	s_addc_u32 s29, s29, 0
	s_add_i32 s30, s56, s41
	global_load_lds_dwordx4 v[188:189], off
	s_mov_b32 m0, s30
	s_nop 0
	global_load_lds_dwordx4 v112, s[28:29]
	s_add_i32 m0, s30, 0x2000
	s_nop 0
	global_load_lds_dwordx4 v134, s[28:29]
	v_lshl_add_u64 v[188:189], v[228:229], 0, s[96:97]
	s_mov_b32 m0, s47
	s_nop 0
	global_load_lds_dwordx4 v[188:189], off
	v_lshl_add_u64 v[188:189], v[246:247], 0, s[96:97]
	s_mov_b32 m0, s48
	s_nop 0
	global_load_lds_dwordx4 v[188:189], off
	s_waitcnt vmcnt(8)
	s_waitcnt lgkmcnt(0)
	s_setprio 1
	s_barrier
	v_mfma_f32_16x16x32_bf16 v[60:63], v[140:143], v[176:179], v[60:63]
	v_mfma_f32_16x16x32_bf16 v[56:59], v[152:155], v[176:179], v[56:59]
	v_mfma_f32_16x16x32_bf16 v[44:47], v[140:143], v[184:187], v[44:47]
	v_mfma_f32_16x16x32_bf16 v[40:43], v[152:155], v[184:187], v[40:43]
	v_mfma_f32_16x16x32_bf16 v[28:31], v[140:143], v[230:233], v[28:31]
	v_mfma_f32_16x16x32_bf16 v[24:27], v[152:155], v[230:233], v[24:27]
	v_mfma_f32_16x16x32_bf16 v[12:15], v[140:143], v[238:241], v[12:15]
	v_mfma_f32_16x16x32_bf16 v[8:11], v[152:155], v[238:241], v[8:11]
	v_mfma_f32_16x16x32_bf16 v[60:63], v[148:151], v[180:183], v[60:63]
	v_mfma_f32_16x16x32_bf16 v[56:59], v[156:159], v[180:183], v[56:59]
	v_mfma_f32_16x16x32_bf16 v[44:47], v[148:151], v[208:211], v[44:47]
	v_mfma_f32_16x16x32_bf16 v[40:43], v[156:159], v[208:211], v[40:43]
	v_mfma_f32_16x16x32_bf16 v[28:31], v[148:151], v[234:237], v[28:31]
	v_mfma_f32_16x16x32_bf16 v[24:27], v[156:159], v[234:237], v[24:27]
	v_mfma_f32_16x16x32_bf16 v[12:15], v[148:151], v[242:245], v[12:15]
	v_mfma_f32_16x16x32_bf16 v[8:11], v[156:159], v[242:245], v[8:11]
	s_setprio 0
	s_setprio 1
	v_mfma_f32_16x16x32_bf16 v[52:55], v[160:163], v[176:179], v[52:55]
	v_mfma_f32_16x16x32_bf16 v[48:51], v[168:171], v[176:179], v[48:51]
	v_mfma_f32_16x16x32_bf16 v[36:39], v[160:163], v[184:187], v[36:39]
	v_mfma_f32_16x16x32_bf16 v[32:35], v[168:171], v[184:187], v[32:35]
	v_mfma_f32_16x16x32_bf16 v[20:23], v[160:163], v[230:233], v[20:23]
	v_mfma_f32_16x16x32_bf16 v[16:19], v[168:171], v[230:233], v[16:19]
	v_mfma_f32_16x16x32_bf16 v[4:7], v[160:163], v[238:241], v[4:7]
	v_mfma_f32_16x16x32_bf16 v[0:3], v[168:171], v[238:241], v[0:3]
	v_mfma_f32_16x16x32_bf16 v[52:55], v[164:167], v[180:183], v[52:55]
	v_mfma_f32_16x16x32_bf16 v[48:51], v[172:175], v[180:183], v[48:51]
	v_mfma_f32_16x16x32_bf16 v[36:39], v[164:167], v[208:211], v[36:39]
	v_mfma_f32_16x16x32_bf16 v[32:35], v[172:175], v[208:211], v[32:35]
	v_mfma_f32_16x16x32_bf16 v[20:23], v[164:167], v[234:237], v[20:23]
	v_mfma_f32_16x16x32_bf16 v[16:19], v[172:175], v[234:237], v[16:19]
	v_mfma_f32_16x16x32_bf16 v[4:7], v[164:167], v[242:245], v[4:7]
	v_mfma_f32_16x16x32_bf16 v[0:3], v[172:175], v[242:245], v[0:3]
	s_setprio 0
	s_barrier
	s_add_i32 s54, s54, 2
	s_add_u32 s52, s52, 0x100
	s_addc_u32 s53, s53, 0
	s_add_u32 s26, s26, 0x100
	s_addc_u32 s27, s27, 0
	s_cmp_gt_u32 s54, 13
	s_cbranch_scc0 .LBB0_758
	s_branch .Lpeel_exit_758
.LBB0_758:
	s_add_u32 s28, s26, 0xfff80080
	s_addc_u32 s29, s27, -1
	s_add_i32 s55, 0, 0x10000
	s_cmp_eq_u32 s54, 12
	s_cselect_b32 s31, s17, s29
	s_cselect_b32 s30, s23, s28
	s_cselect_b32 s29, s15, s53
	s_cselect_b32 s28, s25, s52
	s_add_i32 s58, 0, 0x14000
	v_add_u32_e32 v156, s55, v145
	v_add_u32_e32 v172, s58, v145
	ds_read_b128 v[140:143], v156
	ds_read_b128 v[148:151], v156 offset:1024
	ds_read_b128 v[152:155], v156 offset:2048
	ds_read_b128 v[156:159], v156 offset:3072
	ds_read_b128 v[160:163], v172
	ds_read_b128 v[164:167], v172 offset:1024
	ds_read_b128 v[168:171], v172 offset:2048
	ds_read_b128 v[172:175], v172 offset:3072
	s_add_i32 m0, s42, 0xc000
	ds_read_b128 v[176:179], v147
	ds_read_b128 v[180:183], v147 offset:1024
	ds_read_b128 v[184:187], v147 offset:2048
	ds_read_b128 v[208:211], v147 offset:3072
	ds_read_b128 v[230:233], v147 offset:4096
	ds_read_b128 v[234:237], v147 offset:5120
	ds_read_b128 v[238:241], v147 offset:6144
	ds_read_b128 v[242:245], v147 offset:7168
	global_load_lds_dwordx4 v138, s[26:27]
	s_add_i32 m0, s42, 0xe000
	s_nop 0
	global_load_lds_dwordx4 v136, s[26:27]
	s_waitcnt vmcnt(8)
	s_waitcnt lgkmcnt(0)
	s_setprio 1
	s_barrier
	v_mfma_f32_16x16x32_bf16 v[126:129], v[140:143], v[176:179], v[126:129]
	v_mfma_f32_16x16x32_bf16 v[122:125], v[152:155], v[176:179], v[122:125]
	v_mfma_f32_16x16x32_bf16 v[108:111], v[140:143], v[184:187], v[108:111]
	v_mfma_f32_16x16x32_bf16 v[104:107], v[152:155], v[184:187], v[104:107]
	v_mfma_f32_16x16x32_bf16 v[92:95], v[140:143], v[230:233], v[92:95]
	v_mfma_f32_16x16x32_bf16 v[88:91], v[152:155], v[230:233], v[88:91]
	v_mfma_f32_16x16x32_bf16 v[76:79], v[140:143], v[238:241], v[76:79]
	v_mfma_f32_16x16x32_bf16 v[72:75], v[152:155], v[238:241], v[72:75]
	v_mfma_f32_16x16x32_bf16 v[126:129], v[148:151], v[180:183], v[126:129]
	v_mfma_f32_16x16x32_bf16 v[122:125], v[156:159], v[180:183], v[122:125]
	v_mfma_f32_16x16x32_bf16 v[108:111], v[148:151], v[208:211], v[108:111]
	v_mfma_f32_16x16x32_bf16 v[104:107], v[156:159], v[208:211], v[104:107]
	v_mfma_f32_16x16x32_bf16 v[92:95], v[148:151], v[234:237], v[92:95]
	v_mfma_f32_16x16x32_bf16 v[88:91], v[156:159], v[234:237], v[88:91]
	v_mfma_f32_16x16x32_bf16 v[76:79], v[148:151], v[242:245], v[76:79]
	v_mfma_f32_16x16x32_bf16 v[72:75], v[156:159], v[242:245], v[72:75]
	s_setprio 0
	s_setprio 1
	v_mfma_f32_16x16x32_bf16 v[118:121], v[160:163], v[176:179], v[118:121]
	v_mfma_f32_16x16x32_bf16 v[114:117], v[168:171], v[176:179], v[114:117]
	v_mfma_f32_16x16x32_bf16 v[100:103], v[160:163], v[184:187], v[100:103]
	v_mfma_f32_16x16x32_bf16 v[96:99], v[168:171], v[184:187], v[96:99]
	v_mfma_f32_16x16x32_bf16 v[84:87], v[160:163], v[230:233], v[84:87]
	v_mfma_f32_16x16x32_bf16 v[80:83], v[168:171], v[230:233], v[80:83]
	v_mfma_f32_16x16x32_bf16 v[68:71], v[160:163], v[238:241], v[68:71]
	v_mfma_f32_16x16x32_bf16 v[64:67], v[168:171], v[238:241], v[64:67]
	v_mfma_f32_16x16x32_bf16 v[118:121], v[164:167], v[180:183], v[118:121]
	v_mfma_f32_16x16x32_bf16 v[114:117], v[172:175], v[180:183], v[114:117]
	v_mfma_f32_16x16x32_bf16 v[100:103], v[164:167], v[208:211], v[100:103]
	v_mfma_f32_16x16x32_bf16 v[96:99], v[172:175], v[208:211], v[96:99]
	v_mfma_f32_16x16x32_bf16 v[84:87], v[164:167], v[234:237], v[84:87]
	v_mfma_f32_16x16x32_bf16 v[80:83], v[172:175], v[234:237], v[80:83]
	v_mfma_f32_16x16x32_bf16 v[68:71], v[164:167], v[242:245], v[68:71]
	v_mfma_f32_16x16x32_bf16 v[64:67], v[172:175], v[242:245], v[64:67]
	s_setprio 0
	s_barrier
	s_add_i32 s55, s55, s41
	s_mov_b32 m0, s55
	ds_read_b128 v[176:179], v147 offset:16384
	ds_read_b128 v[180:183], v147 offset:17408
	ds_read_b128 v[184:187], v147 offset:18432
	ds_read_b128 v[208:211], v147 offset:19456
	ds_read_b128 v[230:233], v147 offset:20480
	ds_read_b128 v[234:237], v147 offset:21504
	ds_read_b128 v[238:241], v147 offset:22528
	ds_read_b128 v[242:245], v147 offset:23552
	global_load_lds_dwordx4 v112, s[28:29]
	s_add_i32 m0, s55, 0x2000
	s_add_u32 s56, s28, 0x40000
	v_lshl_add_u64 v[212:213], s[28:29], 0, v[134:135]
	s_addc_u32 s57, s29, 0
	s_add_i32 s55, s58, s41
	global_load_lds_dwordx4 v134, s[28:29]
	s_mov_b32 m0, s55
	v_lshl_add_u64 v[246:247], s[30:31], 0, v[132:133]
	global_load_lds_dwordx4 v112, s[56:57]
	s_add_i32 m0, s55, 0x2000
	s_nop 0
	global_load_lds_dwordx4 v134, s[56:57]
	v_lshl_add_u64 v[228:229], s[30:31], 0, v[130:131]
	s_mov_b32 m0, s42
	s_nop 0
	global_load_lds_dwordx4 v130, s[30:31]
	s_mov_b32 m0, s43
	s_nop 0
	global_load_lds_dwordx4 v132, s[30:31]
	s_waitcnt vmcnt(8)
	s_waitcnt lgkmcnt(0)
	s_setprio 1
	s_barrier
	v_mfma_f32_16x16x32_bf16 v[60:63], v[140:143], v[176:179], v[60:63]
	v_mfma_f32_16x16x32_bf16 v[56:59], v[152:155], v[176:179], v[56:59]
	v_mfma_f32_16x16x32_bf16 v[44:47], v[140:143], v[184:187], v[44:47]
	v_mfma_f32_16x16x32_bf16 v[40:43], v[152:155], v[184:187], v[40:43]
	v_mfma_f32_16x16x32_bf16 v[28:31], v[140:143], v[230:233], v[28:31]
	v_mfma_f32_16x16x32_bf16 v[24:27], v[152:155], v[230:233], v[24:27]
	v_mfma_f32_16x16x32_bf16 v[12:15], v[140:143], v[238:241], v[12:15]
	v_mfma_f32_16x16x32_bf16 v[8:11], v[152:155], v[238:241], v[8:11]
	v_mfma_f32_16x16x32_bf16 v[60:63], v[148:151], v[180:183], v[60:63]
	v_mfma_f32_16x16x32_bf16 v[56:59], v[156:159], v[180:183], v[56:59]
	v_mfma_f32_16x16x32_bf16 v[44:47], v[148:151], v[208:211], v[44:47]
	v_mfma_f32_16x16x32_bf16 v[40:43], v[156:159], v[208:211], v[40:43]
	v_mfma_f32_16x16x32_bf16 v[28:31], v[148:151], v[234:237], v[28:31]
	v_mfma_f32_16x16x32_bf16 v[24:27], v[156:159], v[234:237], v[24:27]
	v_mfma_f32_16x16x32_bf16 v[12:15], v[148:151], v[242:245], v[12:15]
	v_mfma_f32_16x16x32_bf16 v[8:11], v[156:159], v[242:245], v[8:11]
	s_setprio 0
	s_setprio 1
	v_mfma_f32_16x16x32_bf16 v[52:55], v[160:163], v[176:179], v[52:55]
	v_mfma_f32_16x16x32_bf16 v[48:51], v[168:171], v[176:179], v[48:51]
	v_mfma_f32_16x16x32_bf16 v[36:39], v[160:163], v[184:187], v[36:39]
	v_mfma_f32_16x16x32_bf16 v[32:35], v[168:171], v[184:187], v[32:35]
	v_mfma_f32_16x16x32_bf16 v[20:23], v[160:163], v[230:233], v[20:23]
	v_mfma_f32_16x16x32_bf16 v[16:19], v[168:171], v[230:233], v[16:19]
	v_mfma_f32_16x16x32_bf16 v[4:7], v[160:163], v[238:241], v[4:7]
	v_mfma_f32_16x16x32_bf16 v[0:3], v[168:171], v[238:241], v[0:3]
	v_mfma_f32_16x16x32_bf16 v[52:55], v[164:167], v[180:183], v[52:55]
	v_mfma_f32_16x16x32_bf16 v[48:51], v[172:175], v[180:183], v[48:51]
	v_mfma_f32_16x16x32_bf16 v[36:39], v[164:167], v[208:211], v[36:39]
	v_mfma_f32_16x16x32_bf16 v[32:35], v[172:175], v[208:211], v[32:35]
	v_mfma_f32_16x16x32_bf16 v[20:23], v[164:167], v[234:237], v[20:23]
	v_mfma_f32_16x16x32_bf16 v[16:19], v[172:175], v[234:237], v[16:19]
	v_mfma_f32_16x16x32_bf16 v[4:7], v[164:167], v[242:245], v[4:7]
	v_mfma_f32_16x16x32_bf16 v[0:3], v[172:175], v[242:245], v[0:3]
	s_setprio 0
	s_barrier
	s_add_i32 s55, 0, 0x18000
	s_add_i32 s56, 0, 0x1c000
	v_add_u32_e32 v156, s55, v145
	v_add_u32_e32 v172, s56, v145
	ds_read_b128 v[140:143], v156
	ds_read_b128 v[148:151], v156 offset:1024
	ds_read_b128 v[152:155], v156 offset:2048
	ds_read_b128 v[156:159], v156 offset:3072
	ds_read_b128 v[160:163], v172
	ds_read_b128 v[164:167], v172 offset:1024
	ds_read_b128 v[168:171], v172 offset:2048
	ds_read_b128 v[172:175], v172 offset:3072
	s_add_u32 s30, s30, 0x80000
	s_addc_u32 s31, s31, 0
	s_mov_b32 m0, s44
	ds_read_b128 v[176:179], v147 offset:32768
	ds_read_b128 v[180:183], v147 offset:33792
	ds_read_b128 v[184:187], v147 offset:34816
	ds_read_b128 v[208:211], v147 offset:35840
	ds_read_b128 v[230:233], v147 offset:36864
	ds_read_b128 v[234:237], v147 offset:37888
	ds_read_b128 v[238:241], v147 offset:38912
	ds_read_b128 v[242:245], v147 offset:39936
	global_load_lds_dwordx4 v130, s[30:31]
	s_mov_b32 m0, s45
	s_nop 0
	global_load_lds_dwordx4 v132, s[30:31]
	s_waitcnt vmcnt(8)
	s_waitcnt lgkmcnt(0)
	s_setprio 1
	s_barrier
	v_mfma_f32_16x16x32_bf16 v[126:129], v[140:143], v[176:179], v[126:129]
	v_mfma_f32_16x16x32_bf16 v[122:125], v[152:155], v[176:179], v[122:125]
	v_mfma_f32_16x16x32_bf16 v[108:111], v[140:143], v[184:187], v[108:111]
	v_mfma_f32_16x16x32_bf16 v[104:107], v[152:155], v[184:187], v[104:107]
	v_mfma_f32_16x16x32_bf16 v[92:95], v[140:143], v[230:233], v[92:95]
	v_mfma_f32_16x16x32_bf16 v[88:91], v[152:155], v[230:233], v[88:91]
	v_mfma_f32_16x16x32_bf16 v[76:79], v[140:143], v[238:241], v[76:79]
	v_mfma_f32_16x16x32_bf16 v[72:75], v[152:155], v[238:241], v[72:75]
	v_mfma_f32_16x16x32_bf16 v[126:129], v[148:151], v[180:183], v[126:129]
	v_mfma_f32_16x16x32_bf16 v[122:125], v[156:159], v[180:183], v[122:125]
	v_mfma_f32_16x16x32_bf16 v[108:111], v[148:151], v[208:211], v[108:111]
	v_mfma_f32_16x16x32_bf16 v[104:107], v[156:159], v[208:211], v[104:107]
	v_mfma_f32_16x16x32_bf16 v[92:95], v[148:151], v[234:237], v[92:95]
	v_mfma_f32_16x16x32_bf16 v[88:91], v[156:159], v[234:237], v[88:91]
	v_mfma_f32_16x16x32_bf16 v[76:79], v[148:151], v[242:245], v[76:79]
	v_mfma_f32_16x16x32_bf16 v[72:75], v[156:159], v[242:245], v[72:75]
	s_setprio 0
	s_setprio 1
	v_mfma_f32_16x16x32_bf16 v[118:121], v[160:163], v[176:179], v[118:121]
	v_mfma_f32_16x16x32_bf16 v[114:117], v[168:171], v[176:179], v[114:117]
	v_mfma_f32_16x16x32_bf16 v[100:103], v[160:163], v[184:187], v[100:103]
	v_mfma_f32_16x16x32_bf16 v[96:99], v[168:171], v[184:187], v[96:99]
	v_mfma_f32_16x16x32_bf16 v[84:87], v[160:163], v[230:233], v[84:87]
	v_mfma_f32_16x16x32_bf16 v[80:83], v[168:171], v[230:233], v[80:83]
	v_mfma_f32_16x16x32_bf16 v[68:71], v[160:163], v[238:241], v[68:71]
	v_mfma_f32_16x16x32_bf16 v[64:67], v[168:171], v[238:241], v[64:67]
	v_mfma_f32_16x16x32_bf16 v[118:121], v[164:167], v[180:183], v[118:121]
	v_mfma_f32_16x16x32_bf16 v[114:117], v[172:175], v[180:183], v[114:117]
	v_mfma_f32_16x16x32_bf16 v[100:103], v[164:167], v[208:211], v[100:103]
	v_mfma_f32_16x16x32_bf16 v[96:99], v[172:175], v[208:211], v[96:99]
	v_mfma_f32_16x16x32_bf16 v[84:87], v[164:167], v[234:237], v[84:87]
	v_mfma_f32_16x16x32_bf16 v[80:83], v[172:175], v[234:237], v[80:83]
	v_mfma_f32_16x16x32_bf16 v[68:71], v[164:167], v[242:245], v[68:71]
	v_mfma_f32_16x16x32_bf16 v[64:67], v[172:175], v[242:245], v[64:67]
	s_setprio 0
	s_barrier
	s_add_i32 s30, s55, s41
	s_mov_b32 m0, s30
	ds_read_b128 v[176:179], v147 offset:49152
	ds_read_b128 v[180:183], v147 offset:50176
	ds_read_b128 v[184:187], v147 offset:51200
	ds_read_b128 v[208:211], v147 offset:52224
	ds_read_b128 v[230:233], v147 offset:53248
	ds_read_b128 v[234:237], v147 offset:54272
	ds_read_b128 v[238:241], v147 offset:55296
	ds_read_b128 v[242:245], v147 offset:56320
	s_add_u32 s98, s28, 0x80
	s_addc_u32 s99, s29, 0
	global_load_lds_dwordx4 v112, s[98:99]
	s_add_i32 m0, s30, 0x2000
	s_add_u32 s28, s28, 0x40080
	v_lshl_add_u64 v[188:189], v[212:213], 0, s[96:97]
	s_addc_u32 s29, s29, 0
	s_add_i32 s30, s56, s41
	global_load_lds_dwordx4 v[188:189], off
	s_mov_b32 m0, s30
	s_nop 0
	global_load_lds_dwordx4 v112, s[28:29]
	s_add_i32 m0, s30, 0x2000
	s_nop 0
	global_load_lds_dwordx4 v134, s[28:29]
	v_lshl_add_u64 v[188:189], v[228:229], 0, s[96:97]
	s_mov_b32 m0, s47
	s_nop 0
	global_load_lds_dwordx4 v[188:189], off
	v_lshl_add_u64 v[188:189], v[246:247], 0, s[96:97]
	s_mov_b32 m0, s48
	s_nop 0
	global_load_lds_dwordx4 v[188:189], off
	s_waitcnt vmcnt(8)
	s_waitcnt lgkmcnt(0)
	s_setprio 1
	s_barrier
	v_mfma_f32_16x16x32_bf16 v[60:63], v[140:143], v[176:179], v[60:63]
	v_mfma_f32_16x16x32_bf16 v[56:59], v[152:155], v[176:179], v[56:59]
	v_mfma_f32_16x16x32_bf16 v[44:47], v[140:143], v[184:187], v[44:47]
	v_mfma_f32_16x16x32_bf16 v[40:43], v[152:155], v[184:187], v[40:43]
	v_mfma_f32_16x16x32_bf16 v[28:31], v[140:143], v[230:233], v[28:31]
	v_mfma_f32_16x16x32_bf16 v[24:27], v[152:155], v[230:233], v[24:27]
	v_mfma_f32_16x16x32_bf16 v[12:15], v[140:143], v[238:241], v[12:15]
	v_mfma_f32_16x16x32_bf16 v[8:11], v[152:155], v[238:241], v[8:11]
	v_mfma_f32_16x16x32_bf16 v[60:63], v[148:151], v[180:183], v[60:63]
	v_mfma_f32_16x16x32_bf16 v[56:59], v[156:159], v[180:183], v[56:59]
	v_mfma_f32_16x16x32_bf16 v[44:47], v[148:151], v[208:211], v[44:47]
	v_mfma_f32_16x16x32_bf16 v[40:43], v[156:159], v[208:211], v[40:43]
	v_mfma_f32_16x16x32_bf16 v[28:31], v[148:151], v[234:237], v[28:31]
	v_mfma_f32_16x16x32_bf16 v[24:27], v[156:159], v[234:237], v[24:27]
	v_mfma_f32_16x16x32_bf16 v[12:15], v[148:151], v[242:245], v[12:15]
	v_mfma_f32_16x16x32_bf16 v[8:11], v[156:159], v[242:245], v[8:11]
	s_setprio 0
	s_setprio 1
	v_mfma_f32_16x16x32_bf16 v[52:55], v[160:163], v[176:179], v[52:55]
	v_mfma_f32_16x16x32_bf16 v[48:51], v[168:171], v[176:179], v[48:51]
	v_mfma_f32_16x16x32_bf16 v[36:39], v[160:163], v[184:187], v[36:39]
	v_mfma_f32_16x16x32_bf16 v[32:35], v[168:171], v[184:187], v[32:35]
	v_mfma_f32_16x16x32_bf16 v[20:23], v[160:163], v[230:233], v[20:23]
	v_mfma_f32_16x16x32_bf16 v[16:19], v[168:171], v[230:233], v[16:19]
	v_mfma_f32_16x16x32_bf16 v[4:7], v[160:163], v[238:241], v[4:7]
	v_mfma_f32_16x16x32_bf16 v[0:3], v[168:171], v[238:241], v[0:3]
	v_mfma_f32_16x16x32_bf16 v[52:55], v[164:167], v[180:183], v[52:55]
	v_mfma_f32_16x16x32_bf16 v[48:51], v[172:175], v[180:183], v[48:51]
	v_mfma_f32_16x16x32_bf16 v[36:39], v[164:167], v[208:211], v[36:39]
	v_mfma_f32_16x16x32_bf16 v[32:35], v[172:175], v[208:211], v[32:35]
	v_mfma_f32_16x16x32_bf16 v[20:23], v[164:167], v[234:237], v[20:23]
	v_mfma_f32_16x16x32_bf16 v[16:19], v[172:175], v[234:237], v[16:19]
	v_mfma_f32_16x16x32_bf16 v[4:7], v[164:167], v[242:245], v[4:7]
	v_mfma_f32_16x16x32_bf16 v[0:3], v[172:175], v[242:245], v[0:3]
	s_setprio 0
	s_barrier
	s_add_i32 s54, s54, 2
	s_add_u32 s52, s52, 0x100
	s_addc_u32 s53, s53, 0
	s_add_u32 s26, s26, 0x100
	s_addc_u32 s27, s27, 0
	s_cmp_gt_u32 s54, 13
	s_cbranch_scc0 .LBB0_758

.LBB0_803:
	s_ashr_i32 s15, s14, 31
	s_lshl_b64 s[18:19], s[14:15], 20
	s_add_u32 s18, s38, s18
	s_addc_u32 s19, s39, s19
	s_and_b64 s[0:1], s[0:1], exec
	s_cselect_b32 s15, s19, s25
	s_cselect_b32 s21, s18, s24
	s_add_u32 s50, s24, 0x100
	s_addc_u32 s51, s25, 0
	s_mov_b32 s52, -2
	s_waitcnt lgkmcnt(0)
	s_add_u32 s0, s22, 0x100
	s_addc_u32 s1, s23, 0
	s_add_i32 s53, 0, 0x10000
	s_cmp_eq_u32 s52, 28
	s_cselect_b32 s27, s17, s1
	s_cselect_b32 s26, s16, s0
	s_cselect_b32 s25, s15, s51
	s_cselect_b32 s24, s21, s50
	s_add_i32 s54, 0, 0x14000
	v_add_u32_e32 v156, s53, v145
	v_add_u32_e32 v172, s54, v145
	ds_read_b128 v[140:143], v156
	ds_read_b128 v[148:151], v156 offset:1024
	ds_read_b128 v[152:155], v156 offset:2048
	ds_read_b128 v[156:159], v156 offset:3072
	ds_read_b128 v[160:163], v172
	ds_read_b128 v[164:167], v172 offset:1024
	ds_read_b128 v[168:171], v172 offset:2048
	ds_read_b128 v[172:175], v172 offset:3072
	s_add_i32 m0, s31, 0xc000
	ds_read_b128 v[176:179], v147
	ds_read_b128 v[180:183], v147 offset:1024
	ds_read_b128 v[184:187], v147 offset:2048
	ds_read_b128 v[208:211], v147 offset:3072
	ds_read_b128 v[230:233], v147 offset:4096
	ds_read_b128 v[234:237], v147 offset:5120
	ds_read_b128 v[238:241], v147 offset:6144
	ds_read_b128 v[242:245], v147 offset:7168
	global_load_lds_dwordx4 v138, s[22:23]
	s_add_i32 m0, s31, 0xe000
	s_nop 0
	global_load_lds_dwordx4 v136, s[22:23]
	s_waitcnt vmcnt(8)
	s_waitcnt lgkmcnt(0)
	s_setprio 1
	s_barrier
	v_mfma_f32_16x16x32_bf16 v[126:129], v[140:143], v[176:179], 0
	v_mfma_f32_16x16x32_bf16 v[122:125], v[152:155], v[176:179], 0
	v_mfma_f32_16x16x32_bf16 v[108:111], v[140:143], v[184:187], 0
	v_mfma_f32_16x16x32_bf16 v[104:107], v[152:155], v[184:187], 0
	v_mfma_f32_16x16x32_bf16 v[92:95], v[140:143], v[230:233], 0
	v_mfma_f32_16x16x32_bf16 v[88:91], v[152:155], v[230:233], 0
	v_mfma_f32_16x16x32_bf16 v[76:79], v[140:143], v[238:241], 0
	v_mfma_f32_16x16x32_bf16 v[72:75], v[152:155], v[238:241], 0
	v_mfma_f32_16x16x32_bf16 v[126:129], v[148:151], v[180:183], v[126:129]
	v_mfma_f32_16x16x32_bf16 v[122:125], v[156:159], v[180:183], v[122:125]
	v_mfma_f32_16x16x32_bf16 v[108:111], v[148:151], v[208:211], v[108:111]
	v_mfma_f32_16x16x32_bf16 v[104:107], v[156:159], v[208:211], v[104:107]
	v_mfma_f32_16x16x32_bf16 v[92:95], v[148:151], v[234:237], v[92:95]
	v_mfma_f32_16x16x32_bf16 v[88:91], v[156:159], v[234:237], v[88:91]
	v_mfma_f32_16x16x32_bf16 v[76:79], v[148:151], v[242:245], v[76:79]
	v_mfma_f32_16x16x32_bf16 v[72:75], v[156:159], v[242:245], v[72:75]
	s_setprio 0
	s_setprio 1
	v_mfma_f32_16x16x32_bf16 v[118:121], v[160:163], v[176:179], 0
	v_mfma_f32_16x16x32_bf16 v[114:117], v[168:171], v[176:179], 0
	v_mfma_f32_16x16x32_bf16 v[100:103], v[160:163], v[184:187], 0
	v_mfma_f32_16x16x32_bf16 v[96:99], v[168:171], v[184:187], 0
	v_mfma_f32_16x16x32_bf16 v[84:87], v[160:163], v[230:233], 0
	v_mfma_f32_16x16x32_bf16 v[80:83], v[168:171], v[230:233], 0
	v_mfma_f32_16x16x32_bf16 v[68:71], v[160:163], v[238:241], 0
	v_mfma_f32_16x16x32_bf16 v[64:67], v[168:171], v[238:241], 0
	v_mfma_f32_16x16x32_bf16 v[118:121], v[164:167], v[180:183], v[118:121]
	v_mfma_f32_16x16x32_bf16 v[114:117], v[172:175], v[180:183], v[114:117]
	v_mfma_f32_16x16x32_bf16 v[100:103], v[164:167], v[208:211], v[100:103]
	v_mfma_f32_16x16x32_bf16 v[96:99], v[172:175], v[208:211], v[96:99]
	v_mfma_f32_16x16x32_bf16 v[84:87], v[164:167], v[234:237], v[84:87]
	v_mfma_f32_16x16x32_bf16 v[80:83], v[172:175], v[234:237], v[80:83]
	v_mfma_f32_16x16x32_bf16 v[68:71], v[164:167], v[242:245], v[68:71]
	v_mfma_f32_16x16x32_bf16 v[64:67], v[172:175], v[242:245], v[64:67]
	s_setprio 0
	s_barrier
	s_add_i32 s22, s53, s30
	s_mov_b32 m0, s22
	ds_read_b128 v[176:179], v147 offset:16384
	ds_read_b128 v[180:183], v147 offset:17408
	ds_read_b128 v[184:187], v147 offset:18432
	ds_read_b128 v[208:211], v147 offset:19456
	ds_read_b128 v[230:233], v147 offset:20480
	ds_read_b128 v[234:237], v147 offset:21504
	ds_read_b128 v[238:241], v147 offset:22528
	ds_read_b128 v[242:245], v147 offset:23552
	global_load_lds_dwordx4 v112, s[24:25]
	s_add_i32 m0, s22, 0x2000
	s_add_u32 s22, s24, 0x80000
	v_lshl_add_u64 v[212:213], s[24:25], 0, v[134:135]
	s_addc_u32 s23, s25, 0
	s_add_i32 s53, s54, s30
	global_load_lds_dwordx4 v134, s[24:25]
	s_mov_b32 m0, s53
	s_nop 0
	global_load_lds_dwordx4 v112, s[22:23]
	s_add_i32 m0, s53, 0x2000
	s_nop 0
	global_load_lds_dwordx4 v134, s[22:23]
	s_mov_b32 m0, s31
	s_nop 0
	global_load_lds_dwordx4 v130, s[26:27]
	s_mov_b32 m0, s35
	s_nop 0
	global_load_lds_dwordx4 v132, s[26:27]
	s_waitcnt vmcnt(8)
	s_waitcnt lgkmcnt(0)
	s_setprio 1
	s_barrier
	v_mfma_f32_16x16x32_bf16 v[60:63], v[140:143], v[176:179], 0
	v_mfma_f32_16x16x32_bf16 v[56:59], v[152:155], v[176:179], 0
	v_mfma_f32_16x16x32_bf16 v[44:47], v[140:143], v[184:187], 0
	v_mfma_f32_16x16x32_bf16 v[40:43], v[152:155], v[184:187], 0
	v_mfma_f32_16x16x32_bf16 v[28:31], v[140:143], v[230:233], 0
	v_mfma_f32_16x16x32_bf16 v[24:27], v[152:155], v[230:233], 0
	v_mfma_f32_16x16x32_bf16 v[12:15], v[140:143], v[238:241], 0
	v_mfma_f32_16x16x32_bf16 v[8:11], v[152:155], v[238:241], 0
	v_mfma_f32_16x16x32_bf16 v[60:63], v[148:151], v[180:183], v[60:63]
	v_mfma_f32_16x16x32_bf16 v[56:59], v[156:159], v[180:183], v[56:59]
	v_mfma_f32_16x16x32_bf16 v[44:47], v[148:151], v[208:211], v[44:47]
	v_mfma_f32_16x16x32_bf16 v[40:43], v[156:159], v[208:211], v[40:43]
	v_mfma_f32_16x16x32_bf16 v[28:31], v[148:151], v[234:237], v[28:31]
	v_mfma_f32_16x16x32_bf16 v[24:27], v[156:159], v[234:237], v[24:27]
	v_mfma_f32_16x16x32_bf16 v[12:15], v[148:151], v[242:245], v[12:15]
	v_mfma_f32_16x16x32_bf16 v[8:11], v[156:159], v[242:245], v[8:11]
	s_setprio 0
	s_setprio 1
	v_mfma_f32_16x16x32_bf16 v[52:55], v[160:163], v[176:179], 0
	v_mfma_f32_16x16x32_bf16 v[48:51], v[168:171], v[176:179], 0
	v_mfma_f32_16x16x32_bf16 v[36:39], v[160:163], v[184:187], 0
	v_mfma_f32_16x16x32_bf16 v[32:35], v[168:171], v[184:187], 0
	v_mfma_f32_16x16x32_bf16 v[20:23], v[160:163], v[230:233], 0
	v_mfma_f32_16x16x32_bf16 v[16:19], v[168:171], v[230:233], 0
	v_mfma_f32_16x16x32_bf16 v[4:7], v[160:163], v[238:241], 0
	v_mfma_f32_16x16x32_bf16 v[0:3], v[168:171], v[238:241], 0
	v_mfma_f32_16x16x32_bf16 v[52:55], v[164:167], v[180:183], v[52:55]
	v_mfma_f32_16x16x32_bf16 v[48:51], v[172:175], v[180:183], v[48:51]
	v_mfma_f32_16x16x32_bf16 v[36:39], v[164:167], v[208:211], v[36:39]
	v_mfma_f32_16x16x32_bf16 v[32:35], v[172:175], v[208:211], v[32:35]
	v_mfma_f32_16x16x32_bf16 v[20:23], v[164:167], v[234:237], v[20:23]
	v_mfma_f32_16x16x32_bf16 v[16:19], v[172:175], v[234:237], v[16:19]
	v_mfma_f32_16x16x32_bf16 v[4:7], v[164:167], v[242:245], v[4:7]
	v_mfma_f32_16x16x32_bf16 v[0:3], v[172:175], v[242:245], v[0:3]
	s_setprio 0
	s_barrier
	s_add_i32 s53, 0, 0x18000
	s_add_i32 s54, 0, 0x1c000
	v_add_u32_e32 v156, s53, v145
	v_add_u32_e32 v172, s54, v145
	ds_read_b128 v[140:143], v156
	ds_read_b128 v[148:151], v156 offset:1024
	ds_read_b128 v[152:155], v156 offset:2048
	ds_read_b128 v[156:159], v156 offset:3072
	ds_read_b128 v[160:163], v172
	ds_read_b128 v[164:167], v172 offset:1024
	ds_read_b128 v[168:171], v172 offset:2048
	ds_read_b128 v[172:175], v172 offset:3072
	s_add_u32 s22, s26, 0x120000
	s_addc_u32 s23, s27, 0
	s_mov_b32 m0, s40
	ds_read_b128 v[176:179], v147 offset:32768
	ds_read_b128 v[180:183], v147 offset:33792
	ds_read_b128 v[184:187], v147 offset:34816
	ds_read_b128 v[208:211], v147 offset:35840
	ds_read_b128 v[230:233], v147 offset:36864
	ds_read_b128 v[234:237], v147 offset:37888
	ds_read_b128 v[238:241], v147 offset:38912
	ds_read_b128 v[242:245], v147 offset:39936
	global_load_lds_dwordx4 v130, s[22:23]
	s_mov_b32 m0, s41
	s_nop 0
	global_load_lds_dwordx4 v132, s[22:23]
	s_waitcnt vmcnt(8)
	s_waitcnt lgkmcnt(0)
	s_setprio 1
	s_barrier
	v_mfma_f32_16x16x32_bf16 v[126:129], v[140:143], v[176:179], v[126:129]
	v_mfma_f32_16x16x32_bf16 v[122:125], v[152:155], v[176:179], v[122:125]
	v_mfma_f32_16x16x32_bf16 v[108:111], v[140:143], v[184:187], v[108:111]
	v_mfma_f32_16x16x32_bf16 v[104:107], v[152:155], v[184:187], v[104:107]
	v_mfma_f32_16x16x32_bf16 v[92:95], v[140:143], v[230:233], v[92:95]
	v_mfma_f32_16x16x32_bf16 v[88:91], v[152:155], v[230:233], v[88:91]
	v_mfma_f32_16x16x32_bf16 v[76:79], v[140:143], v[238:241], v[76:79]
	v_mfma_f32_16x16x32_bf16 v[72:75], v[152:155], v[238:241], v[72:75]
	v_mfma_f32_16x16x32_bf16 v[126:129], v[148:151], v[180:183], v[126:129]
	v_mfma_f32_16x16x32_bf16 v[122:125], v[156:159], v[180:183], v[122:125]
	v_mfma_f32_16x16x32_bf16 v[108:111], v[148:151], v[208:211], v[108:111]
	v_mfma_f32_16x16x32_bf16 v[104:107], v[156:159], v[208:211], v[104:107]
	v_mfma_f32_16x16x32_bf16 v[92:95], v[148:151], v[234:237], v[92:95]
	v_mfma_f32_16x16x32_bf16 v[88:91], v[156:159], v[234:237], v[88:91]
	v_mfma_f32_16x16x32_bf16 v[76:79], v[148:151], v[242:245], v[76:79]
	v_mfma_f32_16x16x32_bf16 v[72:75], v[156:159], v[242:245], v[72:75]
	s_setprio 0
	s_setprio 1
	v_mfma_f32_16x16x32_bf16 v[118:121], v[160:163], v[176:179], v[118:121]
	v_mfma_f32_16x16x32_bf16 v[114:117], v[168:171], v[176:179], v[114:117]
	v_mfma_f32_16x16x32_bf16 v[100:103], v[160:163], v[184:187], v[100:103]
	v_mfma_f32_16x16x32_bf16 v[96:99], v[168:171], v[184:187], v[96:99]
	v_mfma_f32_16x16x32_bf16 v[84:87], v[160:163], v[230:233], v[84:87]
	v_mfma_f32_16x16x32_bf16 v[80:83], v[168:171], v[230:233], v[80:83]
	v_mfma_f32_16x16x32_bf16 v[68:71], v[160:163], v[238:241], v[68:71]
	v_mfma_f32_16x16x32_bf16 v[64:67], v[168:171], v[238:241], v[64:67]
	v_mfma_f32_16x16x32_bf16 v[118:121], v[164:167], v[180:183], v[118:121]
	v_mfma_f32_16x16x32_bf16 v[114:117], v[172:175], v[180:183], v[114:117]
	v_mfma_f32_16x16x32_bf16 v[100:103], v[164:167], v[208:211], v[100:103]
	v_mfma_f32_16x16x32_bf16 v[96:99], v[172:175], v[208:211], v[96:99]
	v_mfma_f32_16x16x32_bf16 v[84:87], v[164:167], v[234:237], v[84:87]
	v_mfma_f32_16x16x32_bf16 v[80:83], v[172:175], v[234:237], v[80:83]
	v_mfma_f32_16x16x32_bf16 v[68:71], v[164:167], v[242:245], v[68:71]
	v_mfma_f32_16x16x32_bf16 v[64:67], v[172:175], v[242:245], v[64:67]
	s_setprio 0
	s_barrier
	s_add_i32 s22, s53, s30
	s_mov_b32 m0, s22
	ds_read_b128 v[176:179], v147 offset:49152
	ds_read_b128 v[180:183], v147 offset:50176
	ds_read_b128 v[184:187], v147 offset:51200
	ds_read_b128 v[208:211], v147 offset:52224
	ds_read_b128 v[230:233], v147 offset:53248
	ds_read_b128 v[234:237], v147 offset:54272
	ds_read_b128 v[238:241], v147 offset:55296
	ds_read_b128 v[242:245], v147 offset:56320
	s_add_u32 s98, s24, 0x80
	s_addc_u32 s99, s25, 0
	global_load_lds_dwordx4 v112, s[98:99]
	s_add_i32 m0, s22, 0x2000
	s_add_u32 s22, s24, 0x80080
	v_lshl_add_u64 v[188:189], v[212:213], 0, s[96:97]
	s_addc_u32 s23, s25, 0
	s_add_i32 s24, s54, s30
	global_load_lds_dwordx4 v[188:189], off
	s_mov_b32 m0, s24
	s_nop 0
	global_load_lds_dwordx4 v112, s[22:23]
	s_add_i32 m0, s24, 0x2000
	s_nop 0
	global_load_lds_dwordx4 v134, s[22:23]
	s_mov_b32 m0, s43
	s_nop 0
	s_add_u32 s98, s26, 0x80
	s_addc_u32 s99, s27, 0
	global_load_lds_dwordx4 v130, s[98:99]
	s_mov_b32 m0, s44
	s_nop 0
	s_add_u32 s98, s26, 0x80
	s_addc_u32 s99, s27, 0
	global_load_lds_dwordx4 v132, s[98:99]
	s_waitcnt vmcnt(8)
	s_waitcnt lgkmcnt(0)
	s_setprio 1
	s_barrier
	v_mfma_f32_16x16x32_bf16 v[60:63], v[140:143], v[176:179], v[60:63]
	v_mfma_f32_16x16x32_bf16 v[56:59], v[152:155], v[176:179], v[56:59]
	v_mfma_f32_16x16x32_bf16 v[44:47], v[140:143], v[184:187], v[44:47]
	v_mfma_f32_16x16x32_bf16 v[40:43], v[152:155], v[184:187], v[40:43]
	v_mfma_f32_16x16x32_bf16 v[28:31], v[140:143], v[230:233], v[28:31]
	v_mfma_f32_16x16x32_bf16 v[24:27], v[152:155], v[230:233], v[24:27]
	v_mfma_f32_16x16x32_bf16 v[12:15], v[140:143], v[238:241], v[12:15]
	v_mfma_f32_16x16x32_bf16 v[8:11], v[152:155], v[238:241], v[8:11]
	v_mfma_f32_16x16x32_bf16 v[60:63], v[148:151], v[180:183], v[60:63]
	v_mfma_f32_16x16x32_bf16 v[56:59], v[156:159], v[180:183], v[56:59]
	v_mfma_f32_16x16x32_bf16 v[44:47], v[148:151], v[208:211], v[44:47]
	v_mfma_f32_16x16x32_bf16 v[40:43], v[156:159], v[208:211], v[40:43]
	v_mfma_f32_16x16x32_bf16 v[28:31], v[148:151], v[234:237], v[28:31]
	v_mfma_f32_16x16x32_bf16 v[24:27], v[156:159], v[234:237], v[24:27]
	v_mfma_f32_16x16x32_bf16 v[12:15], v[148:151], v[242:245], v[12:15]
	v_mfma_f32_16x16x32_bf16 v[8:11], v[156:159], v[242:245], v[8:11]
	s_setprio 0
	s_setprio 1
	v_mfma_f32_16x16x32_bf16 v[52:55], v[160:163], v[176:179], v[52:55]
	v_mfma_f32_16x16x32_bf16 v[48:51], v[168:171], v[176:179], v[48:51]
	v_mfma_f32_16x16x32_bf16 v[36:39], v[160:163], v[184:187], v[36:39]
	v_mfma_f32_16x16x32_bf16 v[32:35], v[168:171], v[184:187], v[32:35]
	v_mfma_f32_16x16x32_bf16 v[20:23], v[160:163], v[230:233], v[20:23]
	v_mfma_f32_16x16x32_bf16 v[16:19], v[168:171], v[230:233], v[16:19]
	v_mfma_f32_16x16x32_bf16 v[4:7], v[160:163], v[238:241], v[4:7]
	v_mfma_f32_16x16x32_bf16 v[0:3], v[168:171], v[238:241], v[0:3]
	v_mfma_f32_16x16x32_bf16 v[52:55], v[164:167], v[180:183], v[52:55]
	v_mfma_f32_16x16x32_bf16 v[48:51], v[172:175], v[180:183], v[48:51]
	v_mfma_f32_16x16x32_bf16 v[36:39], v[164:167], v[208:211], v[36:39]
	v_mfma_f32_16x16x32_bf16 v[32:35], v[172:175], v[208:211], v[32:35]
	v_mfma_f32_16x16x32_bf16 v[20:23], v[164:167], v[234:237], v[20:23]
	v_mfma_f32_16x16x32_bf16 v[16:19], v[172:175], v[234:237], v[16:19]
	v_mfma_f32_16x16x32_bf16 v[4:7], v[164:167], v[242:245], v[4:7]
	v_mfma_f32_16x16x32_bf16 v[0:3], v[172:175], v[242:245], v[0:3]
	s_setprio 0
	s_barrier
	s_add_i32 s52, s52, 2
	s_add_u32 s50, s50, 0x100
	s_addc_u32 s51, s51, 0
	s_cmp_gt_u32 s52, 29
	s_mov_b64 s[22:23], s[0:1]
	s_cbranch_scc0 .LBB0_804
	s_branch .Lpeel_exit_804
.LBB0_804:
	s_add_u32 s0, s22, 0x100
	s_addc_u32 s1, s23, 0
	s_add_i32 s53, 0, 0x10000
	s_cmp_eq_u32 s52, 28
	s_cselect_b32 s27, s17, s1
	s_cselect_b32 s26, s16, s0
	s_cselect_b32 s25, s15, s51
	s_cselect_b32 s24, s21, s50
	s_add_i32 s54, 0, 0x14000
	v_add_u32_e32 v156, s53, v145
	v_add_u32_e32 v172, s54, v145
	ds_read_b128 v[140:143], v156
	ds_read_b128 v[148:151], v156 offset:1024
	ds_read_b128 v[152:155], v156 offset:2048
	ds_read_b128 v[156:159], v156 offset:3072
	ds_read_b128 v[160:163], v172
	ds_read_b128 v[164:167], v172 offset:1024
	ds_read_b128 v[168:171], v172 offset:2048
	ds_read_b128 v[172:175], v172 offset:3072
	s_add_i32 m0, s31, 0xc000
	ds_read_b128 v[176:179], v147
	ds_read_b128 v[180:183], v147 offset:1024
	ds_read_b128 v[184:187], v147 offset:2048
	ds_read_b128 v[208:211], v147 offset:3072
	ds_read_b128 v[230:233], v147 offset:4096
	ds_read_b128 v[234:237], v147 offset:5120
	ds_read_b128 v[238:241], v147 offset:6144
	ds_read_b128 v[242:245], v147 offset:7168
	global_load_lds_dwordx4 v138, s[22:23]
	s_add_i32 m0, s31, 0xe000
	s_nop 0
	global_load_lds_dwordx4 v136, s[22:23]
	s_waitcnt vmcnt(8)
	s_waitcnt lgkmcnt(0)
	s_setprio 1
	s_barrier
	v_mfma_f32_16x16x32_bf16 v[126:129], v[140:143], v[176:179], v[126:129]
	v_mfma_f32_16x16x32_bf16 v[122:125], v[152:155], v[176:179], v[122:125]
	v_mfma_f32_16x16x32_bf16 v[108:111], v[140:143], v[184:187], v[108:111]
	v_mfma_f32_16x16x32_bf16 v[104:107], v[152:155], v[184:187], v[104:107]
	v_mfma_f32_16x16x32_bf16 v[92:95], v[140:143], v[230:233], v[92:95]
	v_mfma_f32_16x16x32_bf16 v[88:91], v[152:155], v[230:233], v[88:91]
	v_mfma_f32_16x16x32_bf16 v[76:79], v[140:143], v[238:241], v[76:79]
	v_mfma_f32_16x16x32_bf16 v[72:75], v[152:155], v[238:241], v[72:75]
	v_mfma_f32_16x16x32_bf16 v[126:129], v[148:151], v[180:183], v[126:129]
	v_mfma_f32_16x16x32_bf16 v[122:125], v[156:159], v[180:183], v[122:125]
	v_mfma_f32_16x16x32_bf16 v[108:111], v[148:151], v[208:211], v[108:111]
	v_mfma_f32_16x16x32_bf16 v[104:107], v[156:159], v[208:211], v[104:107]
	v_mfma_f32_16x16x32_bf16 v[92:95], v[148:151], v[234:237], v[92:95]
	v_mfma_f32_16x16x32_bf16 v[88:91], v[156:159], v[234:237], v[88:91]
	v_mfma_f32_16x16x32_bf16 v[76:79], v[148:151], v[242:245], v[76:79]
	v_mfma_f32_16x16x32_bf16 v[72:75], v[156:159], v[242:245], v[72:75]
	s_setprio 0
	s_setprio 1
	v_mfma_f32_16x16x32_bf16 v[118:121], v[160:163], v[176:179], v[118:121]
	v_mfma_f32_16x16x32_bf16 v[114:117], v[168:171], v[176:179], v[114:117]
	v_mfma_f32_16x16x32_bf16 v[100:103], v[160:163], v[184:187], v[100:103]
	v_mfma_f32_16x16x32_bf16 v[96:99], v[168:171], v[184:187], v[96:99]
	v_mfma_f32_16x16x32_bf16 v[84:87], v[160:163], v[230:233], v[84:87]
	v_mfma_f32_16x16x32_bf16 v[80:83], v[168:171], v[230:233], v[80:83]
	v_mfma_f32_16x16x32_bf16 v[68:71], v[160:163], v[238:241], v[68:71]
	v_mfma_f32_16x16x32_bf16 v[64:67], v[168:171], v[238:241], v[64:67]
	v_mfma_f32_16x16x32_bf16 v[118:121], v[164:167], v[180:183], v[118:121]
	v_mfma_f32_16x16x32_bf16 v[114:117], v[172:175], v[180:183], v[114:117]
	v_mfma_f32_16x16x32_bf16 v[100:103], v[164:167], v[208:211], v[100:103]
	v_mfma_f32_16x16x32_bf16 v[96:99], v[172:175], v[208:211], v[96:99]
	v_mfma_f32_16x16x32_bf16 v[84:87], v[164:167], v[234:237], v[84:87]
	v_mfma_f32_16x16x32_bf16 v[80:83], v[172:175], v[234:237], v[80:83]
	v_mfma_f32_16x16x32_bf16 v[68:71], v[164:167], v[242:245], v[68:71]
	v_mfma_f32_16x16x32_bf16 v[64:67], v[172:175], v[242:245], v[64:67]
	s_setprio 0
	s_barrier
	s_add_i32 s22, s53, s30
	s_mov_b32 m0, s22
	ds_read_b128 v[176:179], v147 offset:16384
	ds_read_b128 v[180:183], v147 offset:17408
	ds_read_b128 v[184:187], v147 offset:18432
	ds_read_b128 v[208:211], v147 offset:19456
	ds_read_b128 v[230:233], v147 offset:20480
	ds_read_b128 v[234:237], v147 offset:21504
	ds_read_b128 v[238:241], v147 offset:22528
	ds_read_b128 v[242:245], v147 offset:23552
	global_load_lds_dwordx4 v112, s[24:25]
	s_add_i32 m0, s22, 0x2000
	s_add_u32 s22, s24, 0x80000
	v_lshl_add_u64 v[212:213], s[24:25], 0, v[134:135]
	s_addc_u32 s23, s25, 0
	s_add_i32 s53, s54, s30
	global_load_lds_dwordx4 v134, s[24:25]
	s_mov_b32 m0, s53
	s_nop 0
	global_load_lds_dwordx4 v112, s[22:23]
	s_add_i32 m0, s53, 0x2000
	s_nop 0
	global_load_lds_dwordx4 v134, s[22:23]
	s_mov_b32 m0, s31
	s_nop 0
	global_load_lds_dwordx4 v130, s[26:27]
	s_mov_b32 m0, s35
	s_nop 0
	global_load_lds_dwordx4 v132, s[26:27]
	s_waitcnt vmcnt(8)
	s_waitcnt lgkmcnt(0)
	s_setprio 1
	s_barrier
	v_mfma_f32_16x16x32_bf16 v[60:63], v[140:143], v[176:179], v[60:63]
	v_mfma_f32_16x16x32_bf16 v[56:59], v[152:155], v[176:179], v[56:59]
	v_mfma_f32_16x16x32_bf16 v[44:47], v[140:143], v[184:187], v[44:47]
	v_mfma_f32_16x16x32_bf16 v[40:43], v[152:155], v[184:187], v[40:43]
	v_mfma_f32_16x16x32_bf16 v[28:31], v[140:143], v[230:233], v[28:31]
	v_mfma_f32_16x16x32_bf16 v[24:27], v[152:155], v[230:233], v[24:27]
	v_mfma_f32_16x16x32_bf16 v[12:15], v[140:143], v[238:241], v[12:15]
	v_mfma_f32_16x16x32_bf16 v[8:11], v[152:155], v[238:241], v[8:11]
	v_mfma_f32_16x16x32_bf16 v[60:63], v[148:151], v[180:183], v[60:63]
	v_mfma_f32_16x16x32_bf16 v[56:59], v[156:159], v[180:183], v[56:59]
	v_mfma_f32_16x16x32_bf16 v[44:47], v[148:151], v[208:211], v[44:47]
	v_mfma_f32_16x16x32_bf16 v[40:43], v[156:159], v[208:211], v[40:43]
	v_mfma_f32_16x16x32_bf16 v[28:31], v[148:151], v[234:237], v[28:31]
	v_mfma_f32_16x16x32_bf16 v[24:27], v[156:159], v[234:237], v[24:27]
	v_mfma_f32_16x16x32_bf16 v[12:15], v[148:151], v[242:245], v[12:15]
	v_mfma_f32_16x16x32_bf16 v[8:11], v[156:159], v[242:245], v[8:11]
	s_setprio 0
	s_setprio 1
	v_mfma_f32_16x16x32_bf16 v[52:55], v[160:163], v[176:179], v[52:55]
	v_mfma_f32_16x16x32_bf16 v[48:51], v[168:171], v[176:179], v[48:51]
	v_mfma_f32_16x16x32_bf16 v[36:39], v[160:163], v[184:187], v[36:39]
	v_mfma_f32_16x16x32_bf16 v[32:35], v[168:171], v[184:187], v[32:35]
	v_mfma_f32_16x16x32_bf16 v[20:23], v[160:163], v[230:233], v[20:23]
	v_mfma_f32_16x16x32_bf16 v[16:19], v[168:171], v[230:233], v[16:19]
	v_mfma_f32_16x16x32_bf16 v[4:7], v[160:163], v[238:241], v[4:7]
	v_mfma_f32_16x16x32_bf16 v[0:3], v[168:171], v[238:241], v[0:3]
	v_mfma_f32_16x16x32_bf16 v[52:55], v[164:167], v[180:183], v[52:55]
	v_mfma_f32_16x16x32_bf16 v[48:51], v[172:175], v[180:183], v[48:51]
	v_mfma_f32_16x16x32_bf16 v[36:39], v[164:167], v[208:211], v[36:39]
	v_mfma_f32_16x16x32_bf16 v[32:35], v[172:175], v[208:211], v[32:35]
	v_mfma_f32_16x16x32_bf16 v[20:23], v[164:167], v[234:237], v[20:23]
	v_mfma_f32_16x16x32_bf16 v[16:19], v[172:175], v[234:237], v[16:19]
	v_mfma_f32_16x16x32_bf16 v[4:7], v[164:167], v[242:245], v[4:7]
	v_mfma_f32_16x16x32_bf16 v[0:3], v[172:175], v[242:245], v[0:3]
	s_setprio 0
	s_barrier
	s_add_i32 s53, 0, 0x18000
	s_add_i32 s54, 0, 0x1c000
	v_add_u32_e32 v156, s53, v145
	v_add_u32_e32 v172, s54, v145
	ds_read_b128 v[140:143], v156
	ds_read_b128 v[148:151], v156 offset:1024
	ds_read_b128 v[152:155], v156 offset:2048
	ds_read_b128 v[156:159], v156 offset:3072
	ds_read_b128 v[160:163], v172
	ds_read_b128 v[164:167], v172 offset:1024
	ds_read_b128 v[168:171], v172 offset:2048
	ds_read_b128 v[172:175], v172 offset:3072
	s_add_u32 s22, s26, 0x120000
	s_addc_u32 s23, s27, 0
	s_mov_b32 m0, s40
	ds_read_b128 v[176:179], v147 offset:32768
	ds_read_b128 v[180:183], v147 offset:33792
	ds_read_b128 v[184:187], v147 offset:34816
	ds_read_b128 v[208:211], v147 offset:35840
	ds_read_b128 v[230:233], v147 offset:36864
	ds_read_b128 v[234:237], v147 offset:37888
	ds_read_b128 v[238:241], v147 offset:38912
	ds_read_b128 v[242:245], v147 offset:39936
	global_load_lds_dwordx4 v130, s[22:23]
	s_mov_b32 m0, s41
	s_nop 0
	global_load_lds_dwordx4 v132, s[22:23]
	s_waitcnt vmcnt(8)
	s_waitcnt lgkmcnt(0)
	s_setprio 1
	s_barrier
	v_mfma_f32_16x16x32_bf16 v[126:129], v[140:143], v[176:179], v[126:129]
	v_mfma_f32_16x16x32_bf16 v[122:125], v[152:155], v[176:179], v[122:125]
	v_mfma_f32_16x16x32_bf16 v[108:111], v[140:143], v[184:187], v[108:111]
	v_mfma_f32_16x16x32_bf16 v[104:107], v[152:155], v[184:187], v[104:107]
	v_mfma_f32_16x16x32_bf16 v[92:95], v[140:143], v[230:233], v[92:95]
	v_mfma_f32_16x16x32_bf16 v[88:91], v[152:155], v[230:233], v[88:91]
	v_mfma_f32_16x16x32_bf16 v[76:79], v[140:143], v[238:241], v[76:79]
	v_mfma_f32_16x16x32_bf16 v[72:75], v[152:155], v[238:241], v[72:75]
	v_mfma_f32_16x16x32_bf16 v[126:129], v[148:151], v[180:183], v[126:129]
	v_mfma_f32_16x16x32_bf16 v[122:125], v[156:159], v[180:183], v[122:125]
	v_mfma_f32_16x16x32_bf16 v[108:111], v[148:151], v[208:211], v[108:111]
	v_mfma_f32_16x16x32_bf16 v[104:107], v[156:159], v[208:211], v[104:107]
	v_mfma_f32_16x16x32_bf16 v[92:95], v[148:151], v[234:237], v[92:95]
	v_mfma_f32_16x16x32_bf16 v[88:91], v[156:159], v[234:237], v[88:91]
	v_mfma_f32_16x16x32_bf16 v[76:79], v[148:151], v[242:245], v[76:79]
	v_mfma_f32_16x16x32_bf16 v[72:75], v[156:159], v[242:245], v[72:75]
	s_setprio 0
	s_setprio 1
	v_mfma_f32_16x16x32_bf16 v[118:121], v[160:163], v[176:179], v[118:121]
	v_mfma_f32_16x16x32_bf16 v[114:117], v[168:171], v[176:179], v[114:117]
	v_mfma_f32_16x16x32_bf16 v[100:103], v[160:163], v[184:187], v[100:103]
	v_mfma_f32_16x16x32_bf16 v[96:99], v[168:171], v[184:187], v[96:99]
	v_mfma_f32_16x16x32_bf16 v[84:87], v[160:163], v[230:233], v[84:87]
	v_mfma_f32_16x16x32_bf16 v[80:83], v[168:171], v[230:233], v[80:83]
	v_mfma_f32_16x16x32_bf16 v[68:71], v[160:163], v[238:241], v[68:71]
	v_mfma_f32_16x16x32_bf16 v[64:67], v[168:171], v[238:241], v[64:67]
	v_mfma_f32_16x16x32_bf16 v[118:121], v[164:167], v[180:183], v[118:121]
	v_mfma_f32_16x16x32_bf16 v[114:117], v[172:175], v[180:183], v[114:117]
	v_mfma_f32_16x16x32_bf16 v[100:103], v[164:167], v[208:211], v[100:103]
	v_mfma_f32_16x16x32_bf16 v[96:99], v[172:175], v[208:211], v[96:99]
	v_mfma_f32_16x16x32_bf16 v[84:87], v[164:167], v[234:237], v[84:87]
	v_mfma_f32_16x16x32_bf16 v[80:83], v[172:175], v[234:237], v[80:83]
	v_mfma_f32_16x16x32_bf16 v[68:71], v[164:167], v[242:245], v[68:71]
	v_mfma_f32_16x16x32_bf16 v[64:67], v[172:175], v[242:245], v[64:67]
	s_setprio 0
	s_barrier
	s_add_i32 s22, s53, s30
	s_mov_b32 m0, s22
	ds_read_b128 v[176:179], v147 offset:49152
	ds_read_b128 v[180:183], v147 offset:50176
	ds_read_b128 v[184:187], v147 offset:51200
	ds_read_b128 v[208:211], v147 offset:52224
	ds_read_b128 v[230:233], v147 offset:53248
	ds_read_b128 v[234:237], v147 offset:54272
	ds_read_b128 v[238:241], v147 offset:55296
	ds_read_b128 v[242:245], v147 offset:56320
	s_add_u32 s98, s24, 0x80
	s_addc_u32 s99, s25, 0
	global_load_lds_dwordx4 v112, s[98:99]
	s_add_i32 m0, s22, 0x2000
	s_add_u32 s22, s24, 0x80080
	v_lshl_add_u64 v[188:189], v[212:213], 0, s[96:97]
	s_addc_u32 s23, s25, 0
	s_add_i32 s24, s54, s30
	global_load_lds_dwordx4 v[188:189], off
	s_mov_b32 m0, s24
	s_nop 0
	global_load_lds_dwordx4 v112, s[22:23]
	s_add_i32 m0, s24, 0x2000
	s_nop 0
	global_load_lds_dwordx4 v134, s[22:23]
	s_mov_b32 m0, s43
	s_nop 0
	s_add_u32 s98, s26, 0x80
	s_addc_u32 s99, s27, 0
	global_load_lds_dwordx4 v130, s[98:99]
	s_mov_b32 m0, s44
	s_nop 0
	s_add_u32 s98, s26, 0x80
	s_addc_u32 s99, s27, 0
	global_load_lds_dwordx4 v132, s[98:99]
	s_waitcnt vmcnt(8)
	s_waitcnt lgkmcnt(0)
	s_setprio 1
	s_barrier
	v_mfma_f32_16x16x32_bf16 v[60:63], v[140:143], v[176:179], v[60:63]
	v_mfma_f32_16x16x32_bf16 v[56:59], v[152:155], v[176:179], v[56:59]
	v_mfma_f32_16x16x32_bf16 v[44:47], v[140:143], v[184:187], v[44:47]
	v_mfma_f32_16x16x32_bf16 v[40:43], v[152:155], v[184:187], v[40:43]
	v_mfma_f32_16x16x32_bf16 v[28:31], v[140:143], v[230:233], v[28:31]
	v_mfma_f32_16x16x32_bf16 v[24:27], v[152:155], v[230:233], v[24:27]
	v_mfma_f32_16x16x32_bf16 v[12:15], v[140:143], v[238:241], v[12:15]
	v_mfma_f32_16x16x32_bf16 v[8:11], v[152:155], v[238:241], v[8:11]
	v_mfma_f32_16x16x32_bf16 v[60:63], v[148:151], v[180:183], v[60:63]
	v_mfma_f32_16x16x32_bf16 v[56:59], v[156:159], v[180:183], v[56:59]
	v_mfma_f32_16x16x32_bf16 v[44:47], v[148:151], v[208:211], v[44:47]
	v_mfma_f32_16x16x32_bf16 v[40:43], v[156:159], v[208:211], v[40:43]
	v_mfma_f32_16x16x32_bf16 v[28:31], v[148:151], v[234:237], v[28:31]
	v_mfma_f32_16x16x32_bf16 v[24:27], v[156:159], v[234:237], v[24:27]
	v_mfma_f32_16x16x32_bf16 v[12:15], v[148:151], v[242:245], v[12:15]
	v_mfma_f32_16x16x32_bf16 v[8:11], v[156:159], v[242:245], v[8:11]
	s_setprio 0
	s_setprio 1
	v_mfma_f32_16x16x32_bf16 v[52:55], v[160:163], v[176:179], v[52:55]
	v_mfma_f32_16x16x32_bf16 v[48:51], v[168:171], v[176:179], v[48:51]
	v_mfma_f32_16x16x32_bf16 v[36:39], v[160:163], v[184:187], v[36:39]
	v_mfma_f32_16x16x32_bf16 v[32:35], v[168:171], v[184:187], v[32:35]
	v_mfma_f32_16x16x32_bf16 v[20:23], v[160:163], v[230:233], v[20:23]
	v_mfma_f32_16x16x32_bf16 v[16:19], v[168:171], v[230:233], v[16:19]
	v_mfma_f32_16x16x32_bf16 v[4:7], v[160:163], v[238:241], v[4:7]
	v_mfma_f32_16x16x32_bf16 v[0:3], v[168:171], v[238:241], v[0:3]
	v_mfma_f32_16x16x32_bf16 v[52:55], v[164:167], v[180:183], v[52:55]
	v_mfma_f32_16x16x32_bf16 v[48:51], v[172:175], v[180:183], v[48:51]
	v_mfma_f32_16x16x32_bf16 v[36:39], v[164:167], v[208:211], v[36:39]
	v_mfma_f32_16x16x32_bf16 v[32:35], v[172:175], v[208:211], v[32:35]
	v_mfma_f32_16x16x32_bf16 v[20:23], v[164:167], v[234:237], v[20:23]
	v_mfma_f32_16x16x32_bf16 v[16:19], v[172:175], v[234:237], v[16:19]
	v_mfma_f32_16x16x32_bf16 v[4:7], v[164:167], v[242:245], v[4:7]
	v_mfma_f32_16x16x32_bf16 v[0:3], v[172:175], v[242:245], v[0:3]
	s_setprio 0
	s_barrier
	s_add_i32 s52, s52, 2
	s_add_u32 s50, s50, 0x100
	s_addc_u32 s51, s51, 0
	s_cmp_gt_u32 s52, 29
	s_mov_b64 s[22:23], s[0:1]
	s_cbranch_scc0 .LBB0_804

.LBB0_1136:
	s_add_u32 s48, s18, 0x100
	s_addc_u32 s49, s19, 0
	s_mov_b32 s50, -2
	s_waitcnt lgkmcnt(0)
	s_add_u32 s18, s16, 0x100
	s_addc_u32 s19, s17, 0
	s_add_i32 s51, 0, 0x10000
	s_cmp_eq_u32 s50, 40
	s_cselect_b32 s23, s1, s19
	s_cselect_b32 s22, s0, s18
	s_cselect_b32 s21, s15, s49
	s_cselect_b32 s20, s14, s48
	s_add_i32 s52, 0, 0x14000
	v_add_u32_e32 v156, s51, v145
	v_add_u32_e32 v172, s52, v145
	ds_read_b128 v[140:143], v156
	ds_read_b128 v[148:151], v156 offset:1024
	ds_read_b128 v[152:155], v156 offset:2048
	ds_read_b128 v[156:159], v156 offset:3072
	ds_read_b128 v[160:163], v172
	ds_read_b128 v[164:167], v172 offset:1024
	ds_read_b128 v[168:171], v172 offset:2048
	ds_read_b128 v[172:175], v172 offset:3072
	s_add_i32 m0, s31, 0xc000
	ds_read_b128 v[176:179], v147
	ds_read_b128 v[180:183], v147 offset:1024
	ds_read_b128 v[184:187], v147 offset:2048
	ds_read_b128 v[208:211], v147 offset:3072
	ds_read_b128 v[230:233], v147 offset:4096
	ds_read_b128 v[234:237], v147 offset:5120
	ds_read_b128 v[238:241], v147 offset:6144
	ds_read_b128 v[242:245], v147 offset:7168
	global_load_lds_dwordx4 v138, s[16:17]
	s_add_i32 m0, s31, 0xe000
	s_nop 0
	global_load_lds_dwordx4 v136, s[16:17]
	s_waitcnt vmcnt(8)
	s_waitcnt lgkmcnt(0)
	s_setprio 1
	s_barrier
	v_mfma_f32_16x16x32_bf16 v[126:129], v[140:143], v[176:179], 0
	v_mfma_f32_16x16x32_bf16 v[122:125], v[152:155], v[176:179], 0
	v_mfma_f32_16x16x32_bf16 v[108:111], v[140:143], v[184:187], 0
	v_mfma_f32_16x16x32_bf16 v[104:107], v[152:155], v[184:187], 0
	v_mfma_f32_16x16x32_bf16 v[92:95], v[140:143], v[230:233], 0
	v_mfma_f32_16x16x32_bf16 v[88:91], v[152:155], v[230:233], 0
	v_mfma_f32_16x16x32_bf16 v[76:79], v[140:143], v[238:241], 0
	v_mfma_f32_16x16x32_bf16 v[72:75], v[152:155], v[238:241], 0
	v_mfma_f32_16x16x32_bf16 v[126:129], v[148:151], v[180:183], v[126:129]
	v_mfma_f32_16x16x32_bf16 v[122:125], v[156:159], v[180:183], v[122:125]
	v_mfma_f32_16x16x32_bf16 v[108:111], v[148:151], v[208:211], v[108:111]
	v_mfma_f32_16x16x32_bf16 v[104:107], v[156:159], v[208:211], v[104:107]
	v_mfma_f32_16x16x32_bf16 v[92:95], v[148:151], v[234:237], v[92:95]
	v_mfma_f32_16x16x32_bf16 v[88:91], v[156:159], v[234:237], v[88:91]
	v_mfma_f32_16x16x32_bf16 v[76:79], v[148:151], v[242:245], v[76:79]
	v_mfma_f32_16x16x32_bf16 v[72:75], v[156:159], v[242:245], v[72:75]
	s_setprio 0
	s_setprio 1
	v_mfma_f32_16x16x32_bf16 v[118:121], v[160:163], v[176:179], 0
	v_mfma_f32_16x16x32_bf16 v[114:117], v[168:171], v[176:179], 0
	v_mfma_f32_16x16x32_bf16 v[100:103], v[160:163], v[184:187], 0
	v_mfma_f32_16x16x32_bf16 v[96:99], v[168:171], v[184:187], 0
	v_mfma_f32_16x16x32_bf16 v[84:87], v[160:163], v[230:233], 0
	v_mfma_f32_16x16x32_bf16 v[80:83], v[168:171], v[230:233], 0
	v_mfma_f32_16x16x32_bf16 v[68:71], v[160:163], v[238:241], 0
	v_mfma_f32_16x16x32_bf16 v[64:67], v[168:171], v[238:241], 0
	v_mfma_f32_16x16x32_bf16 v[118:121], v[164:167], v[180:183], v[118:121]
	v_mfma_f32_16x16x32_bf16 v[114:117], v[172:175], v[180:183], v[114:117]
	v_mfma_f32_16x16x32_bf16 v[100:103], v[164:167], v[208:211], v[100:103]
	v_mfma_f32_16x16x32_bf16 v[96:99], v[172:175], v[208:211], v[96:99]
	v_mfma_f32_16x16x32_bf16 v[84:87], v[164:167], v[234:237], v[84:87]
	v_mfma_f32_16x16x32_bf16 v[80:83], v[172:175], v[234:237], v[80:83]
	v_mfma_f32_16x16x32_bf16 v[68:71], v[164:167], v[242:245], v[68:71]
	v_mfma_f32_16x16x32_bf16 v[64:67], v[172:175], v[242:245], v[64:67]
	s_setprio 0
	s_barrier
	s_add_i32 s16, s51, s30
	s_mov_b32 m0, s16
	ds_read_b128 v[176:179], v147 offset:16384
	ds_read_b128 v[180:183], v147 offset:17408
	ds_read_b128 v[184:187], v147 offset:18432
	ds_read_b128 v[208:211], v147 offset:19456
	ds_read_b128 v[230:233], v147 offset:20480
	ds_read_b128 v[234:237], v147 offset:21504
	ds_read_b128 v[238:241], v147 offset:22528
	ds_read_b128 v[242:245], v147 offset:23552
	global_load_lds_dwordx4 v112, s[20:21]
	s_add_i32 m0, s16, 0x2000
	s_add_u32 s16, s20, 0xb0000
	v_lshl_add_u64 v[212:213], s[20:21], 0, v[134:135]
	s_addc_u32 s17, s21, 0
	s_add_i32 s51, s52, s30
	global_load_lds_dwordx4 v134, s[20:21]
	s_mov_b32 m0, s51
	s_nop 0
	global_load_lds_dwordx4 v112, s[16:17]
	s_add_i32 m0, s51, 0x2000
	s_nop 0
	global_load_lds_dwordx4 v134, s[16:17]
	s_mov_b32 m0, s31
	s_nop 0
	global_load_lds_dwordx4 v130, s[22:23]
	s_mov_b32 m0, s35
	s_nop 0
	global_load_lds_dwordx4 v132, s[22:23]
	s_waitcnt vmcnt(8)
	s_waitcnt lgkmcnt(0)
	s_setprio 1
	s_barrier
	v_mfma_f32_16x16x32_bf16 v[60:63], v[140:143], v[176:179], 0
	v_mfma_f32_16x16x32_bf16 v[56:59], v[152:155], v[176:179], 0
	v_mfma_f32_16x16x32_bf16 v[44:47], v[140:143], v[184:187], 0
	v_mfma_f32_16x16x32_bf16 v[40:43], v[152:155], v[184:187], 0
	v_mfma_f32_16x16x32_bf16 v[28:31], v[140:143], v[230:233], 0
	v_mfma_f32_16x16x32_bf16 v[24:27], v[152:155], v[230:233], 0
	v_mfma_f32_16x16x32_bf16 v[12:15], v[140:143], v[238:241], 0
	v_mfma_f32_16x16x32_bf16 v[8:11], v[152:155], v[238:241], 0
	v_mfma_f32_16x16x32_bf16 v[60:63], v[148:151], v[180:183], v[60:63]
	v_mfma_f32_16x16x32_bf16 v[56:59], v[156:159], v[180:183], v[56:59]
	v_mfma_f32_16x16x32_bf16 v[44:47], v[148:151], v[208:211], v[44:47]
	v_mfma_f32_16x16x32_bf16 v[40:43], v[156:159], v[208:211], v[40:43]
	v_mfma_f32_16x16x32_bf16 v[28:31], v[148:151], v[234:237], v[28:31]
	v_mfma_f32_16x16x32_bf16 v[24:27], v[156:159], v[234:237], v[24:27]
	v_mfma_f32_16x16x32_bf16 v[12:15], v[148:151], v[242:245], v[12:15]
	v_mfma_f32_16x16x32_bf16 v[8:11], v[156:159], v[242:245], v[8:11]
	s_setprio 0
	s_setprio 1
	v_mfma_f32_16x16x32_bf16 v[52:55], v[160:163], v[176:179], 0
	v_mfma_f32_16x16x32_bf16 v[48:51], v[168:171], v[176:179], 0
	v_mfma_f32_16x16x32_bf16 v[36:39], v[160:163], v[184:187], 0
	v_mfma_f32_16x16x32_bf16 v[32:35], v[168:171], v[184:187], 0
	v_mfma_f32_16x16x32_bf16 v[20:23], v[160:163], v[230:233], 0
	v_mfma_f32_16x16x32_bf16 v[16:19], v[168:171], v[230:233], 0
	v_mfma_f32_16x16x32_bf16 v[4:7], v[160:163], v[238:241], 0
	v_mfma_f32_16x16x32_bf16 v[0:3], v[168:171], v[238:241], 0
	v_mfma_f32_16x16x32_bf16 v[52:55], v[164:167], v[180:183], v[52:55]
	v_mfma_f32_16x16x32_bf16 v[48:51], v[172:175], v[180:183], v[48:51]
	v_mfma_f32_16x16x32_bf16 v[36:39], v[164:167], v[208:211], v[36:39]
	v_mfma_f32_16x16x32_bf16 v[32:35], v[172:175], v[208:211], v[32:35]
	v_mfma_f32_16x16x32_bf16 v[20:23], v[164:167], v[234:237], v[20:23]
	v_mfma_f32_16x16x32_bf16 v[16:19], v[172:175], v[234:237], v[16:19]
	v_mfma_f32_16x16x32_bf16 v[4:7], v[164:167], v[242:245], v[4:7]
	v_mfma_f32_16x16x32_bf16 v[0:3], v[172:175], v[242:245], v[0:3]
	s_setprio 0
	s_barrier
	s_add_i32 s51, 0, 0x18000
	s_add_i32 s52, 0, 0x1c000
	v_add_u32_e32 v156, s51, v145
	v_add_u32_e32 v172, s52, v145
	ds_read_b128 v[140:143], v156
	ds_read_b128 v[148:151], v156 offset:1024
	ds_read_b128 v[152:155], v156 offset:2048
	ds_read_b128 v[156:159], v156 offset:3072
	ds_read_b128 v[160:163], v172
	ds_read_b128 v[164:167], v172 offset:1024
	ds_read_b128 v[168:171], v172 offset:2048
	ds_read_b128 v[172:175], v172 offset:3072
	s_add_u32 s16, s22, 0xb0000
	s_addc_u32 s17, s23, 0
	s_mov_b32 m0, s36
	ds_read_b128 v[176:179], v147 offset:32768
	ds_read_b128 v[180:183], v147 offset:33792
	ds_read_b128 v[184:187], v147 offset:34816
	ds_read_b128 v[208:211], v147 offset:35840
	ds_read_b128 v[230:233], v147 offset:36864
	ds_read_b128 v[234:237], v147 offset:37888
	ds_read_b128 v[238:241], v147 offset:38912
	ds_read_b128 v[242:245], v147 offset:39936
	global_load_lds_dwordx4 v130, s[16:17]
	s_mov_b32 m0, s37
	s_nop 0
	global_load_lds_dwordx4 v132, s[16:17]
	s_waitcnt vmcnt(8)
	s_waitcnt lgkmcnt(0)
	s_setprio 1
	s_barrier
	v_mfma_f32_16x16x32_bf16 v[126:129], v[140:143], v[176:179], v[126:129]
	v_mfma_f32_16x16x32_bf16 v[122:125], v[152:155], v[176:179], v[122:125]
	v_mfma_f32_16x16x32_bf16 v[108:111], v[140:143], v[184:187], v[108:111]
	v_mfma_f32_16x16x32_bf16 v[104:107], v[152:155], v[184:187], v[104:107]
	v_mfma_f32_16x16x32_bf16 v[92:95], v[140:143], v[230:233], v[92:95]
	v_mfma_f32_16x16x32_bf16 v[88:91], v[152:155], v[230:233], v[88:91]
	v_mfma_f32_16x16x32_bf16 v[76:79], v[140:143], v[238:241], v[76:79]
	v_mfma_f32_16x16x32_bf16 v[72:75], v[152:155], v[238:241], v[72:75]
	v_mfma_f32_16x16x32_bf16 v[126:129], v[148:151], v[180:183], v[126:129]
	v_mfma_f32_16x16x32_bf16 v[122:125], v[156:159], v[180:183], v[122:125]
	v_mfma_f32_16x16x32_bf16 v[108:111], v[148:151], v[208:211], v[108:111]
	v_mfma_f32_16x16x32_bf16 v[104:107], v[156:159], v[208:211], v[104:107]
	v_mfma_f32_16x16x32_bf16 v[92:95], v[148:151], v[234:237], v[92:95]
	v_mfma_f32_16x16x32_bf16 v[88:91], v[156:159], v[234:237], v[88:91]
	v_mfma_f32_16x16x32_bf16 v[76:79], v[148:151], v[242:245], v[76:79]
	v_mfma_f32_16x16x32_bf16 v[72:75], v[156:159], v[242:245], v[72:75]
	s_setprio 0
	s_setprio 1
	v_mfma_f32_16x16x32_bf16 v[118:121], v[160:163], v[176:179], v[118:121]
	v_mfma_f32_16x16x32_bf16 v[114:117], v[168:171], v[176:179], v[114:117]
	v_mfma_f32_16x16x32_bf16 v[100:103], v[160:163], v[184:187], v[100:103]
	v_mfma_f32_16x16x32_bf16 v[96:99], v[168:171], v[184:187], v[96:99]
	v_mfma_f32_16x16x32_bf16 v[84:87], v[160:163], v[230:233], v[84:87]
	v_mfma_f32_16x16x32_bf16 v[80:83], v[168:171], v[230:233], v[80:83]
	v_mfma_f32_16x16x32_bf16 v[68:71], v[160:163], v[238:241], v[68:71]
	v_mfma_f32_16x16x32_bf16 v[64:67], v[168:171], v[238:241], v[64:67]
	v_mfma_f32_16x16x32_bf16 v[118:121], v[164:167], v[180:183], v[118:121]
	v_mfma_f32_16x16x32_bf16 v[114:117], v[172:175], v[180:183], v[114:117]
	v_mfma_f32_16x16x32_bf16 v[100:103], v[164:167], v[208:211], v[100:103]
	v_mfma_f32_16x16x32_bf16 v[96:99], v[172:175], v[208:211], v[96:99]
	v_mfma_f32_16x16x32_bf16 v[84:87], v[164:167], v[234:237], v[84:87]
	v_mfma_f32_16x16x32_bf16 v[80:83], v[172:175], v[234:237], v[80:83]
	v_mfma_f32_16x16x32_bf16 v[68:71], v[164:167], v[242:245], v[68:71]
	v_mfma_f32_16x16x32_bf16 v[64:67], v[172:175], v[242:245], v[64:67]
	s_setprio 0
	s_barrier
	s_add_i32 s16, s51, s30
	s_mov_b32 m0, s16
	ds_read_b128 v[176:179], v147 offset:49152
	ds_read_b128 v[180:183], v147 offset:50176
	ds_read_b128 v[184:187], v147 offset:51200
	ds_read_b128 v[208:211], v147 offset:52224
	ds_read_b128 v[230:233], v147 offset:53248
	ds_read_b128 v[234:237], v147 offset:54272
	ds_read_b128 v[238:241], v147 offset:55296
	ds_read_b128 v[242:245], v147 offset:56320
	s_add_u32 s98, s20, 0x80
	s_addc_u32 s99, s21, 0
	global_load_lds_dwordx4 v112, s[98:99]
	s_add_i32 m0, s16, 0x2000
	s_add_u32 s16, s20, 0xb0080
	v_lshl_add_u64 v[188:189], v[212:213], 0, s[96:97]
	s_addc_u32 s17, s21, 0
	s_add_i32 s20, s52, s30
	global_load_lds_dwordx4 v[188:189], off
	s_mov_b32 m0, s20
	s_nop 0
	global_load_lds_dwordx4 v112, s[16:17]
	s_add_i32 m0, s20, 0x2000
	s_nop 0
	global_load_lds_dwordx4 v134, s[16:17]
	s_mov_b32 m0, s39
	s_nop 0
	s_add_u32 s98, s22, 0x80
	s_addc_u32 s99, s23, 0
	global_load_lds_dwordx4 v130, s[98:99]
	s_mov_b32 m0, s40
	s_nop 0
	s_add_u32 s98, s22, 0x80
	s_addc_u32 s99, s23, 0
	global_load_lds_dwordx4 v132, s[98:99]
	s_waitcnt vmcnt(8)
	s_waitcnt lgkmcnt(0)
	s_setprio 1
	s_barrier
	v_mfma_f32_16x16x32_bf16 v[60:63], v[140:143], v[176:179], v[60:63]
	v_mfma_f32_16x16x32_bf16 v[56:59], v[152:155], v[176:179], v[56:59]
	v_mfma_f32_16x16x32_bf16 v[44:47], v[140:143], v[184:187], v[44:47]
	v_mfma_f32_16x16x32_bf16 v[40:43], v[152:155], v[184:187], v[40:43]
	v_mfma_f32_16x16x32_bf16 v[28:31], v[140:143], v[230:233], v[28:31]
	v_mfma_f32_16x16x32_bf16 v[24:27], v[152:155], v[230:233], v[24:27]
	v_mfma_f32_16x16x32_bf16 v[12:15], v[140:143], v[238:241], v[12:15]
	v_mfma_f32_16x16x32_bf16 v[8:11], v[152:155], v[238:241], v[8:11]
	v_mfma_f32_16x16x32_bf16 v[60:63], v[148:151], v[180:183], v[60:63]
	v_mfma_f32_16x16x32_bf16 v[56:59], v[156:159], v[180:183], v[56:59]
	v_mfma_f32_16x16x32_bf16 v[44:47], v[148:151], v[208:211], v[44:47]
	v_mfma_f32_16x16x32_bf16 v[40:43], v[156:159], v[208:211], v[40:43]
	v_mfma_f32_16x16x32_bf16 v[28:31], v[148:151], v[234:237], v[28:31]
	v_mfma_f32_16x16x32_bf16 v[24:27], v[156:159], v[234:237], v[24:27]
	v_mfma_f32_16x16x32_bf16 v[12:15], v[148:151], v[242:245], v[12:15]
	v_mfma_f32_16x16x32_bf16 v[8:11], v[156:159], v[242:245], v[8:11]
	s_setprio 0
	s_setprio 1
	v_mfma_f32_16x16x32_bf16 v[52:55], v[160:163], v[176:179], v[52:55]
	v_mfma_f32_16x16x32_bf16 v[48:51], v[168:171], v[176:179], v[48:51]
	v_mfma_f32_16x16x32_bf16 v[36:39], v[160:163], v[184:187], v[36:39]
	v_mfma_f32_16x16x32_bf16 v[32:35], v[168:171], v[184:187], v[32:35]
	v_mfma_f32_16x16x32_bf16 v[20:23], v[160:163], v[230:233], v[20:23]
	v_mfma_f32_16x16x32_bf16 v[16:19], v[168:171], v[230:233], v[16:19]
	v_mfma_f32_16x16x32_bf16 v[4:7], v[160:163], v[238:241], v[4:7]
	v_mfma_f32_16x16x32_bf16 v[0:3], v[168:171], v[238:241], v[0:3]
	v_mfma_f32_16x16x32_bf16 v[52:55], v[164:167], v[180:183], v[52:55]
	v_mfma_f32_16x16x32_bf16 v[48:51], v[172:175], v[180:183], v[48:51]
	v_mfma_f32_16x16x32_bf16 v[36:39], v[164:167], v[208:211], v[36:39]
	v_mfma_f32_16x16x32_bf16 v[32:35], v[172:175], v[208:211], v[32:35]
	v_mfma_f32_16x16x32_bf16 v[20:23], v[164:167], v[234:237], v[20:23]
	v_mfma_f32_16x16x32_bf16 v[16:19], v[172:175], v[234:237], v[16:19]
	v_mfma_f32_16x16x32_bf16 v[4:7], v[164:167], v[242:245], v[4:7]
	v_mfma_f32_16x16x32_bf16 v[0:3], v[172:175], v[242:245], v[0:3]
	s_setprio 0
	s_barrier
	s_add_i32 s50, s50, 2
	s_add_u32 s48, s48, 0x100
	s_addc_u32 s49, s49, 0
	s_cmp_gt_u32 s50, 41
	s_mov_b64 s[16:17], s[18:19]
	s_cbranch_scc0 .LBB0_1137
	s_branch .Lpeel_exit_1137
.LBB0_1137:
	s_add_u32 s18, s16, 0x100
	s_addc_u32 s19, s17, 0
	s_add_i32 s51, 0, 0x10000
	s_cmp_eq_u32 s50, 40
	s_cselect_b32 s23, s1, s19
	s_cselect_b32 s22, s0, s18
	s_cselect_b32 s21, s15, s49
	s_cselect_b32 s20, s14, s48
	s_add_i32 s52, 0, 0x14000
	v_add_u32_e32 v156, s51, v145
	v_add_u32_e32 v172, s52, v145
	ds_read_b128 v[140:143], v156
	ds_read_b128 v[148:151], v156 offset:1024
	ds_read_b128 v[152:155], v156 offset:2048
	ds_read_b128 v[156:159], v156 offset:3072
	ds_read_b128 v[160:163], v172
	ds_read_b128 v[164:167], v172 offset:1024
	ds_read_b128 v[168:171], v172 offset:2048
	ds_read_b128 v[172:175], v172 offset:3072
	s_add_i32 m0, s31, 0xc000
	ds_read_b128 v[176:179], v147
	ds_read_b128 v[180:183], v147 offset:1024
	ds_read_b128 v[184:187], v147 offset:2048
	ds_read_b128 v[208:211], v147 offset:3072
	ds_read_b128 v[230:233], v147 offset:4096
	ds_read_b128 v[234:237], v147 offset:5120
	ds_read_b128 v[238:241], v147 offset:6144
	ds_read_b128 v[242:245], v147 offset:7168
	global_load_lds_dwordx4 v138, s[16:17]
	s_add_i32 m0, s31, 0xe000
	s_nop 0
	global_load_lds_dwordx4 v136, s[16:17]
	s_waitcnt vmcnt(8)
	s_waitcnt lgkmcnt(0)
	s_setprio 1
	s_barrier
	v_mfma_f32_16x16x32_bf16 v[126:129], v[140:143], v[176:179], v[126:129]
	v_mfma_f32_16x16x32_bf16 v[122:125], v[152:155], v[176:179], v[122:125]
	v_mfma_f32_16x16x32_bf16 v[108:111], v[140:143], v[184:187], v[108:111]
	v_mfma_f32_16x16x32_bf16 v[104:107], v[152:155], v[184:187], v[104:107]
	v_mfma_f32_16x16x32_bf16 v[92:95], v[140:143], v[230:233], v[92:95]
	v_mfma_f32_16x16x32_bf16 v[88:91], v[152:155], v[230:233], v[88:91]
	v_mfma_f32_16x16x32_bf16 v[76:79], v[140:143], v[238:241], v[76:79]
	v_mfma_f32_16x16x32_bf16 v[72:75], v[152:155], v[238:241], v[72:75]
	v_mfma_f32_16x16x32_bf16 v[126:129], v[148:151], v[180:183], v[126:129]
	v_mfma_f32_16x16x32_bf16 v[122:125], v[156:159], v[180:183], v[122:125]
	v_mfma_f32_16x16x32_bf16 v[108:111], v[148:151], v[208:211], v[108:111]
	v_mfma_f32_16x16x32_bf16 v[104:107], v[156:159], v[208:211], v[104:107]
	v_mfma_f32_16x16x32_bf16 v[92:95], v[148:151], v[234:237], v[92:95]
	v_mfma_f32_16x16x32_bf16 v[88:91], v[156:159], v[234:237], v[88:91]
	v_mfma_f32_16x16x32_bf16 v[76:79], v[148:151], v[242:245], v[76:79]
	v_mfma_f32_16x16x32_bf16 v[72:75], v[156:159], v[242:245], v[72:75]
	s_setprio 0
	s_setprio 1
	v_mfma_f32_16x16x32_bf16 v[118:121], v[160:163], v[176:179], v[118:121]
	v_mfma_f32_16x16x32_bf16 v[114:117], v[168:171], v[176:179], v[114:117]
	v_mfma_f32_16x16x32_bf16 v[100:103], v[160:163], v[184:187], v[100:103]
	v_mfma_f32_16x16x32_bf16 v[96:99], v[168:171], v[184:187], v[96:99]
	v_mfma_f32_16x16x32_bf16 v[84:87], v[160:163], v[230:233], v[84:87]
	v_mfma_f32_16x16x32_bf16 v[80:83], v[168:171], v[230:233], v[80:83]
	v_mfma_f32_16x16x32_bf16 v[68:71], v[160:163], v[238:241], v[68:71]
	v_mfma_f32_16x16x32_bf16 v[64:67], v[168:171], v[238:241], v[64:67]
	v_mfma_f32_16x16x32_bf16 v[118:121], v[164:167], v[180:183], v[118:121]
	v_mfma_f32_16x16x32_bf16 v[114:117], v[172:175], v[180:183], v[114:117]
	v_mfma_f32_16x16x32_bf16 v[100:103], v[164:167], v[208:211], v[100:103]
	v_mfma_f32_16x16x32_bf16 v[96:99], v[172:175], v[208:211], v[96:99]
	v_mfma_f32_16x16x32_bf16 v[84:87], v[164:167], v[234:237], v[84:87]
	v_mfma_f32_16x16x32_bf16 v[80:83], v[172:175], v[234:237], v[80:83]
	v_mfma_f32_16x16x32_bf16 v[68:71], v[164:167], v[242:245], v[68:71]
	v_mfma_f32_16x16x32_bf16 v[64:67], v[172:175], v[242:245], v[64:67]
	s_setprio 0
	s_barrier
	s_add_i32 s16, s51, s30
	s_mov_b32 m0, s16
	ds_read_b128 v[176:179], v147 offset:16384
	ds_read_b128 v[180:183], v147 offset:17408
	ds_read_b128 v[184:187], v147 offset:18432
	ds_read_b128 v[208:211], v147 offset:19456
	ds_read_b128 v[230:233], v147 offset:20480
	ds_read_b128 v[234:237], v147 offset:21504
	ds_read_b128 v[238:241], v147 offset:22528
	ds_read_b128 v[242:245], v147 offset:23552
	global_load_lds_dwordx4 v112, s[20:21]
	s_add_i32 m0, s16, 0x2000
	s_add_u32 s16, s20, 0xb0000
	v_lshl_add_u64 v[212:213], s[20:21], 0, v[134:135]
	s_addc_u32 s17, s21, 0
	s_add_i32 s51, s52, s30
	global_load_lds_dwordx4 v134, s[20:21]
	s_mov_b32 m0, s51
	s_nop 0
	global_load_lds_dwordx4 v112, s[16:17]
	s_add_i32 m0, s51, 0x2000
	s_nop 0
	global_load_lds_dwordx4 v134, s[16:17]
	s_mov_b32 m0, s31
	s_nop 0
	global_load_lds_dwordx4 v130, s[22:23]
	s_mov_b32 m0, s35
	s_nop 0
	global_load_lds_dwordx4 v132, s[22:23]
	s_waitcnt vmcnt(8)
	s_waitcnt lgkmcnt(0)
	s_setprio 1
	s_barrier
	v_mfma_f32_16x16x32_bf16 v[60:63], v[140:143], v[176:179], v[60:63]
	v_mfma_f32_16x16x32_bf16 v[56:59], v[152:155], v[176:179], v[56:59]
	v_mfma_f32_16x16x32_bf16 v[44:47], v[140:143], v[184:187], v[44:47]
	v_mfma_f32_16x16x32_bf16 v[40:43], v[152:155], v[184:187], v[40:43]
	v_mfma_f32_16x16x32_bf16 v[28:31], v[140:143], v[230:233], v[28:31]
	v_mfma_f32_16x16x32_bf16 v[24:27], v[152:155], v[230:233], v[24:27]
	v_mfma_f32_16x16x32_bf16 v[12:15], v[140:143], v[238:241], v[12:15]
	v_mfma_f32_16x16x32_bf16 v[8:11], v[152:155], v[238:241], v[8:11]
	v_mfma_f32_16x16x32_bf16 v[60:63], v[148:151], v[180:183], v[60:63]
	v_mfma_f32_16x16x32_bf16 v[56:59], v[156:159], v[180:183], v[56:59]
	v_mfma_f32_16x16x32_bf16 v[44:47], v[148:151], v[208:211], v[44:47]
	v_mfma_f32_16x16x32_bf16 v[40:43], v[156:159], v[208:211], v[40:43]
	v_mfma_f32_16x16x32_bf16 v[28:31], v[148:151], v[234:237], v[28:31]
	v_mfma_f32_16x16x32_bf16 v[24:27], v[156:159], v[234:237], v[24:27]
	v_mfma_f32_16x16x32_bf16 v[12:15], v[148:151], v[242:245], v[12:15]
	v_mfma_f32_16x16x32_bf16 v[8:11], v[156:159], v[242:245], v[8:11]
	s_setprio 0
	s_setprio 1
	v_mfma_f32_16x16x32_bf16 v[52:55], v[160:163], v[176:179], v[52:55]
	v_mfma_f32_16x16x32_bf16 v[48:51], v[168:171], v[176:179], v[48:51]
	v_mfma_f32_16x16x32_bf16 v[36:39], v[160:163], v[184:187], v[36:39]
	v_mfma_f32_16x16x32_bf16 v[32:35], v[168:171], v[184:187], v[32:35]
	v_mfma_f32_16x16x32_bf16 v[20:23], v[160:163], v[230:233], v[20:23]
	v_mfma_f32_16x16x32_bf16 v[16:19], v[168:171], v[230:233], v[16:19]
	v_mfma_f32_16x16x32_bf16 v[4:7], v[160:163], v[238:241], v[4:7]
	v_mfma_f32_16x16x32_bf16 v[0:3], v[168:171], v[238:241], v[0:3]
	v_mfma_f32_16x16x32_bf16 v[52:55], v[164:167], v[180:183], v[52:55]
	v_mfma_f32_16x16x32_bf16 v[48:51], v[172:175], v[180:183], v[48:51]
	v_mfma_f32_16x16x32_bf16 v[36:39], v[164:167], v[208:211], v[36:39]
	v_mfma_f32_16x16x32_bf16 v[32:35], v[172:175], v[208:211], v[32:35]
	v_mfma_f32_16x16x32_bf16 v[20:23], v[164:167], v[234:237], v[20:23]
	v_mfma_f32_16x16x32_bf16 v[16:19], v[172:175], v[234:237], v[16:19]
	v_mfma_f32_16x16x32_bf16 v[4:7], v[164:167], v[242:245], v[4:7]
	v_mfma_f32_16x16x32_bf16 v[0:3], v[172:175], v[242:245], v[0:3]
	s_setprio 0
	s_barrier
	s_add_i32 s51, 0, 0x18000
	s_add_i32 s52, 0, 0x1c000
	v_add_u32_e32 v156, s51, v145
	v_add_u32_e32 v172, s52, v145
	ds_read_b128 v[140:143], v156
	ds_read_b128 v[148:151], v156 offset:1024
	ds_read_b128 v[152:155], v156 offset:2048
	ds_read_b128 v[156:159], v156 offset:3072
	ds_read_b128 v[160:163], v172
	ds_read_b128 v[164:167], v172 offset:1024
	ds_read_b128 v[168:171], v172 offset:2048
	ds_read_b128 v[172:175], v172 offset:3072
	s_add_u32 s16, s22, 0xb0000
	s_addc_u32 s17, s23, 0
	s_mov_b32 m0, s36
	ds_read_b128 v[176:179], v147 offset:32768
	ds_read_b128 v[180:183], v147 offset:33792
	ds_read_b128 v[184:187], v147 offset:34816
	ds_read_b128 v[208:211], v147 offset:35840
	ds_read_b128 v[230:233], v147 offset:36864
	ds_read_b128 v[234:237], v147 offset:37888
	ds_read_b128 v[238:241], v147 offset:38912
	ds_read_b128 v[242:245], v147 offset:39936
	global_load_lds_dwordx4 v130, s[16:17]
	s_mov_b32 m0, s37
	s_nop 0
	global_load_lds_dwordx4 v132, s[16:17]
	s_waitcnt vmcnt(8)
	s_waitcnt lgkmcnt(0)
	s_setprio 1
	s_barrier
	v_mfma_f32_16x16x32_bf16 v[126:129], v[140:143], v[176:179], v[126:129]
	v_mfma_f32_16x16x32_bf16 v[122:125], v[152:155], v[176:179], v[122:125]
	v_mfma_f32_16x16x32_bf16 v[108:111], v[140:143], v[184:187], v[108:111]
	v_mfma_f32_16x16x32_bf16 v[104:107], v[152:155], v[184:187], v[104:107]
	v_mfma_f32_16x16x32_bf16 v[92:95], v[140:143], v[230:233], v[92:95]
	v_mfma_f32_16x16x32_bf16 v[88:91], v[152:155], v[230:233], v[88:91]
	v_mfma_f32_16x16x32_bf16 v[76:79], v[140:143], v[238:241], v[76:79]
	v_mfma_f32_16x16x32_bf16 v[72:75], v[152:155], v[238:241], v[72:75]
	v_mfma_f32_16x16x32_bf16 v[126:129], v[148:151], v[180:183], v[126:129]
	v_mfma_f32_16x16x32_bf16 v[122:125], v[156:159], v[180:183], v[122:125]
	v_mfma_f32_16x16x32_bf16 v[108:111], v[148:151], v[208:211], v[108:111]
	v_mfma_f32_16x16x32_bf16 v[104:107], v[156:159], v[208:211], v[104:107]
	v_mfma_f32_16x16x32_bf16 v[92:95], v[148:151], v[234:237], v[92:95]
	v_mfma_f32_16x16x32_bf16 v[88:91], v[156:159], v[234:237], v[88:91]
	v_mfma_f32_16x16x32_bf16 v[76:79], v[148:151], v[242:245], v[76:79]
	v_mfma_f32_16x16x32_bf16 v[72:75], v[156:159], v[242:245], v[72:75]
	s_setprio 0
	s_setprio 1
	v_mfma_f32_16x16x32_bf16 v[118:121], v[160:163], v[176:179], v[118:121]
	v_mfma_f32_16x16x32_bf16 v[114:117], v[168:171], v[176:179], v[114:117]
	v_mfma_f32_16x16x32_bf16 v[100:103], v[160:163], v[184:187], v[100:103]
	v_mfma_f32_16x16x32_bf16 v[96:99], v[168:171], v[184:187], v[96:99]
	v_mfma_f32_16x16x32_bf16 v[84:87], v[160:163], v[230:233], v[84:87]
	v_mfma_f32_16x16x32_bf16 v[80:83], v[168:171], v[230:233], v[80:83]
	v_mfma_f32_16x16x32_bf16 v[68:71], v[160:163], v[238:241], v[68:71]
	v_mfma_f32_16x16x32_bf16 v[64:67], v[168:171], v[238:241], v[64:67]
	v_mfma_f32_16x16x32_bf16 v[118:121], v[164:167], v[180:183], v[118:121]
	v_mfma_f32_16x16x32_bf16 v[114:117], v[172:175], v[180:183], v[114:117]
	v_mfma_f32_16x16x32_bf16 v[100:103], v[164:167], v[208:211], v[100:103]
	v_mfma_f32_16x16x32_bf16 v[96:99], v[172:175], v[208:211], v[96:99]
	v_mfma_f32_16x16x32_bf16 v[84:87], v[164:167], v[234:237], v[84:87]
	v_mfma_f32_16x16x32_bf16 v[80:83], v[172:175], v[234:237], v[80:83]
	v_mfma_f32_16x16x32_bf16 v[68:71], v[164:167], v[242:245], v[68:71]
	v_mfma_f32_16x16x32_bf16 v[64:67], v[172:175], v[242:245], v[64:67]
	s_setprio 0
	s_barrier
	s_add_i32 s16, s51, s30
	s_mov_b32 m0, s16
	ds_read_b128 v[176:179], v147 offset:49152
	ds_read_b128 v[180:183], v147 offset:50176
	ds_read_b128 v[184:187], v147 offset:51200
	ds_read_b128 v[208:211], v147 offset:52224
	ds_read_b128 v[230:233], v147 offset:53248
	ds_read_b128 v[234:237], v147 offset:54272
	ds_read_b128 v[238:241], v147 offset:55296
	ds_read_b128 v[242:245], v147 offset:56320
	s_add_u32 s98, s20, 0x80
	s_addc_u32 s99, s21, 0
	global_load_lds_dwordx4 v112, s[98:99]
	s_add_i32 m0, s16, 0x2000
	s_add_u32 s16, s20, 0xb0080
	v_lshl_add_u64 v[188:189], v[212:213], 0, s[96:97]
	s_addc_u32 s17, s21, 0
	s_add_i32 s20, s52, s30
	global_load_lds_dwordx4 v[188:189], off
	s_mov_b32 m0, s20
	s_nop 0
	global_load_lds_dwordx4 v112, s[16:17]
	s_add_i32 m0, s20, 0x2000
	s_nop 0
	global_load_lds_dwordx4 v134, s[16:17]
	s_mov_b32 m0, s39
	s_nop 0
	s_add_u32 s98, s22, 0x80
	s_addc_u32 s99, s23, 0
	global_load_lds_dwordx4 v130, s[98:99]
	s_mov_b32 m0, s40
	s_nop 0
	s_add_u32 s98, s22, 0x80
	s_addc_u32 s99, s23, 0
	global_load_lds_dwordx4 v132, s[98:99]
	s_waitcnt vmcnt(8)
	s_waitcnt lgkmcnt(0)
	s_setprio 1
	s_barrier
	v_mfma_f32_16x16x32_bf16 v[60:63], v[140:143], v[176:179], v[60:63]
	v_mfma_f32_16x16x32_bf16 v[56:59], v[152:155], v[176:179], v[56:59]
	v_mfma_f32_16x16x32_bf16 v[44:47], v[140:143], v[184:187], v[44:47]
	v_mfma_f32_16x16x32_bf16 v[40:43], v[152:155], v[184:187], v[40:43]
	v_mfma_f32_16x16x32_bf16 v[28:31], v[140:143], v[230:233], v[28:31]
	v_mfma_f32_16x16x32_bf16 v[24:27], v[152:155], v[230:233], v[24:27]
	v_mfma_f32_16x16x32_bf16 v[12:15], v[140:143], v[238:241], v[12:15]
	v_mfma_f32_16x16x32_bf16 v[8:11], v[152:155], v[238:241], v[8:11]
	v_mfma_f32_16x16x32_bf16 v[60:63], v[148:151], v[180:183], v[60:63]
	v_mfma_f32_16x16x32_bf16 v[56:59], v[156:159], v[180:183], v[56:59]
	v_mfma_f32_16x16x32_bf16 v[44:47], v[148:151], v[208:211], v[44:47]
	v_mfma_f32_16x16x32_bf16 v[40:43], v[156:159], v[208:211], v[40:43]
	v_mfma_f32_16x16x32_bf16 v[28:31], v[148:151], v[234:237], v[28:31]
	v_mfma_f32_16x16x32_bf16 v[24:27], v[156:159], v[234:237], v[24:27]
	v_mfma_f32_16x16x32_bf16 v[12:15], v[148:151], v[242:245], v[12:15]
	v_mfma_f32_16x16x32_bf16 v[8:11], v[156:159], v[242:245], v[8:11]
	s_setprio 0
	s_setprio 1
	v_mfma_f32_16x16x32_bf16 v[52:55], v[160:163], v[176:179], v[52:55]
	v_mfma_f32_16x16x32_bf16 v[48:51], v[168:171], v[176:179], v[48:51]
	v_mfma_f32_16x16x32_bf16 v[36:39], v[160:163], v[184:187], v[36:39]
	v_mfma_f32_16x16x32_bf16 v[32:35], v[168:171], v[184:187], v[32:35]
	v_mfma_f32_16x16x32_bf16 v[20:23], v[160:163], v[230:233], v[20:23]
	v_mfma_f32_16x16x32_bf16 v[16:19], v[168:171], v[230:233], v[16:19]
	v_mfma_f32_16x16x32_bf16 v[4:7], v[160:163], v[238:241], v[4:7]
	v_mfma_f32_16x16x32_bf16 v[0:3], v[168:171], v[238:241], v[0:3]
	v_mfma_f32_16x16x32_bf16 v[52:55], v[164:167], v[180:183], v[52:55]
	v_mfma_f32_16x16x32_bf16 v[48:51], v[172:175], v[180:183], v[48:51]
	v_mfma_f32_16x16x32_bf16 v[36:39], v[164:167], v[208:211], v[36:39]
	v_mfma_f32_16x16x32_bf16 v[32:35], v[172:175], v[208:211], v[32:35]
	v_mfma_f32_16x16x32_bf16 v[20:23], v[164:167], v[234:237], v[20:23]
	v_mfma_f32_16x16x32_bf16 v[16:19], v[172:175], v[234:237], v[16:19]
	v_mfma_f32_16x16x32_bf16 v[4:7], v[164:167], v[242:245], v[4:7]
	v_mfma_f32_16x16x32_bf16 v[0:3], v[172:175], v[242:245], v[0:3]
	s_setprio 0
	s_barrier
	s_add_i32 s50, s50, 2
	s_add_u32 s48, s48, 0x100
	s_addc_u32 s49, s49, 0
	s_cmp_gt_u32 s50, 41
	s_mov_b64 s[16:17], s[18:19]
	s_cbranch_scc0 .LBB0_1137

.LBB0_1951:
	s_ashr_i32 s17, s16, 31
	s_lshl_b64 s[18:19], s[16:17], 19
	s_add_u32 s18, s42, s18
	s_addc_u32 s19, s43, s19
	s_and_b64 s[20:21], s[2:3], exec
	s_cselect_b32 s5, s19, s27
	s_cselect_b32 s17, s18, s26
	s_ashr_i32 s15, s14, 31
	s_lshl_b64 s[20:21], s[14:15], 19
	s_add_u32 s20, s40, s20
	s_addc_u32 s21, s41, s21
	s_and_b64 s[28:29], s[2:3], exec
	s_cselect_b32 s15, s21, s25
	s_cselect_b32 s51, s20, s24
	s_add_u32 s52, s24, 0x100
	s_addc_u32 s53, s25, 0
	s_add_u32 s24, s26, 0x40080
	s_addc_u32 s25, s27, 0
	s_mov_b32 s54, -2
	s_add_u32 s26, s24, 0xfffc0080
	s_addc_u32 s27, s25, -1
	s_add_i32 s55, 0, 0x10000
	s_cmp_eq_u32 s54, 12
	s_cselect_b32 s29, s5, s27
	s_cselect_b32 s28, s17, s26
	v_add_u32_e32 v144, s55, v146
	s_cselect_b32 s27, s15, s53
	s_cselect_b32 s26, s51, s52
	s_add_i32 s58, 0, 0x14000
	ds_read_b128 v[140:143], v144
	ds_read_b128 v[150:153], v144 offset:1024
	ds_read_b128 v[154:157], v144 offset:2048
	ds_read_b128 v[158:161], v144 offset:3072
	v_add_u32_e32 v144, s58, v146
	ds_read_b128 v[162:165], v144
	ds_read_b128 v[166:169], v144 offset:1024
	ds_read_b128 v[170:173], v144 offset:2048
	ds_read_b128 v[174:177], v144 offset:3072
	s_add_i32 m0, s23, 0xc000
	ds_read_b128 v[178:181], v149
	ds_read_b128 v[182:185], v149 offset:1024
	ds_read_b128 v[186:189], v149 offset:2048
	ds_read_b128 v[208:211], v149 offset:3072
	ds_read_b128 v[230:233], v149 offset:4096
	ds_read_b128 v[234:237], v149 offset:5120
	ds_read_b128 v[238:241], v149 offset:6144
	ds_read_b128 v[242:245], v149 offset:7168
	global_load_lds_dwordx4 v138, s[24:25]
	s_add_i32 m0, s23, 0xe000
	s_nop 0
	global_load_lds_dwordx4 v136, s[24:25]
	s_waitcnt vmcnt(8)
	s_waitcnt lgkmcnt(0)
	s_setprio 1
	s_barrier
	v_mfma_f32_16x16x32_bf16 v[126:129], v[140:143], v[178:181], 0
	v_mfma_f32_16x16x32_bf16 v[118:121], v[154:157], v[178:181], 0
	v_mfma_f32_16x16x32_bf16 v[108:111], v[140:143], v[186:189], 0
	v_mfma_f32_16x16x32_bf16 v[100:103], v[154:157], v[186:189], 0
	v_mfma_f32_16x16x32_bf16 v[92:95], v[140:143], v[230:233], 0
	v_mfma_f32_16x16x32_bf16 v[84:87], v[154:157], v[230:233], 0
	v_mfma_f32_16x16x32_bf16 v[76:79], v[140:143], v[238:241], 0
	v_mfma_f32_16x16x32_bf16 v[68:71], v[154:157], v[238:241], 0
	v_mfma_f32_16x16x32_bf16 v[126:129], v[150:153], v[182:185], v[126:129]
	v_mfma_f32_16x16x32_bf16 v[118:121], v[158:161], v[182:185], v[118:121]
	v_mfma_f32_16x16x32_bf16 v[108:111], v[150:153], v[208:211], v[108:111]
	v_mfma_f32_16x16x32_bf16 v[100:103], v[158:161], v[208:211], v[100:103]
	v_mfma_f32_16x16x32_bf16 v[92:95], v[150:153], v[234:237], v[92:95]
	v_mfma_f32_16x16x32_bf16 v[84:87], v[158:161], v[234:237], v[84:87]
	v_mfma_f32_16x16x32_bf16 v[76:79], v[150:153], v[242:245], v[76:79]
	v_mfma_f32_16x16x32_bf16 v[68:71], v[158:161], v[242:245], v[68:71]
	s_setprio 0
	s_setprio 1
	v_mfma_f32_16x16x32_bf16 v[122:125], v[162:165], v[178:181], 0
	v_mfma_f32_16x16x32_bf16 v[114:117], v[170:173], v[178:181], 0
	v_mfma_f32_16x16x32_bf16 v[104:107], v[162:165], v[186:189], 0
	v_mfma_f32_16x16x32_bf16 v[96:99], v[170:173], v[186:189], 0
	v_mfma_f32_16x16x32_bf16 v[88:91], v[162:165], v[230:233], 0
	v_mfma_f32_16x16x32_bf16 v[80:83], v[170:173], v[230:233], 0
	v_mfma_f32_16x16x32_bf16 v[72:75], v[162:165], v[238:241], 0
	v_mfma_f32_16x16x32_bf16 v[64:67], v[170:173], v[238:241], 0
	v_mfma_f32_16x16x32_bf16 v[122:125], v[166:169], v[182:185], v[122:125]
	v_mfma_f32_16x16x32_bf16 v[114:117], v[174:177], v[182:185], v[114:117]
	v_mfma_f32_16x16x32_bf16 v[104:107], v[166:169], v[208:211], v[104:107]
	v_mfma_f32_16x16x32_bf16 v[96:99], v[174:177], v[208:211], v[96:99]
	v_mfma_f32_16x16x32_bf16 v[88:91], v[166:169], v[234:237], v[88:91]
	v_mfma_f32_16x16x32_bf16 v[80:83], v[174:177], v[234:237], v[80:83]
	v_mfma_f32_16x16x32_bf16 v[72:75], v[166:169], v[242:245], v[72:75]
	v_mfma_f32_16x16x32_bf16 v[64:67], v[174:177], v[242:245], v[64:67]
	s_setprio 0
	s_barrier
	s_add_i32 s55, s55, s35
	s_mov_b32 m0, s55
	ds_read_b128 v[178:181], v149 offset:16384
	ds_read_b128 v[182:185], v149 offset:17408
	ds_read_b128 v[186:189], v149 offset:18432
	ds_read_b128 v[208:211], v149 offset:19456
	ds_read_b128 v[230:233], v149 offset:20480
	ds_read_b128 v[234:237], v149 offset:21504
	ds_read_b128 v[238:241], v149 offset:22528
	ds_read_b128 v[242:245], v149 offset:23552
	global_load_lds_dwordx4 v112, s[26:27]
	s_add_i32 m0, s55, 0x2000
	s_add_u32 s56, s26, 0x40000
	v_lshl_add_u64 v[246:247], s[26:27], 0, v[134:135]
	s_addc_u32 s57, s27, 0
	s_add_i32 s55, s58, s35
	global_load_lds_dwordx4 v134, s[26:27]
	s_mov_b32 m0, s55
	v_lshl_add_u64 v[250:251], s[28:29], 0, v[132:133]
	global_load_lds_dwordx4 v112, s[56:57]
	s_add_i32 m0, s55, 0x2000
	s_nop 0
	global_load_lds_dwordx4 v134, s[56:57]
	v_lshl_add_u64 v[248:249], s[28:29], 0, v[130:131]
	s_mov_b32 m0, s23
	s_nop 0
	global_load_lds_dwordx4 v130, s[28:29]
	s_mov_b32 m0, s44
	s_nop 0
	global_load_lds_dwordx4 v132, s[28:29]
	s_waitcnt vmcnt(8)
	s_waitcnt lgkmcnt(0)
	s_setprio 1
	s_barrier
	v_mfma_f32_16x16x32_bf16 v[60:63], v[140:143], v[178:181], 0
	v_mfma_f32_16x16x32_bf16 v[52:55], v[154:157], v[178:181], 0
	v_mfma_f32_16x16x32_bf16 v[44:47], v[140:143], v[186:189], 0
	v_mfma_f32_16x16x32_bf16 v[36:39], v[154:157], v[186:189], 0
	v_mfma_f32_16x16x32_bf16 v[28:31], v[140:143], v[230:233], 0
	v_mfma_f32_16x16x32_bf16 v[20:23], v[154:157], v[230:233], 0
	v_mfma_f32_16x16x32_bf16 v[12:15], v[140:143], v[238:241], 0
	v_mfma_f32_16x16x32_bf16 v[4:7], v[154:157], v[238:241], 0
	v_mfma_f32_16x16x32_bf16 v[60:63], v[150:153], v[182:185], v[60:63]
	v_mfma_f32_16x16x32_bf16 v[52:55], v[158:161], v[182:185], v[52:55]
	v_mfma_f32_16x16x32_bf16 v[44:47], v[150:153], v[208:211], v[44:47]
	v_mfma_f32_16x16x32_bf16 v[36:39], v[158:161], v[208:211], v[36:39]
	v_mfma_f32_16x16x32_bf16 v[28:31], v[150:153], v[234:237], v[28:31]
	v_mfma_f32_16x16x32_bf16 v[20:23], v[158:161], v[234:237], v[20:23]
	v_mfma_f32_16x16x32_bf16 v[12:15], v[150:153], v[242:245], v[12:15]
	v_mfma_f32_16x16x32_bf16 v[4:7], v[158:161], v[242:245], v[4:7]
	s_setprio 0
	s_setprio 1
	v_mfma_f32_16x16x32_bf16 v[56:59], v[162:165], v[178:181], 0
	v_mfma_f32_16x16x32_bf16 v[48:51], v[170:173], v[178:181], 0
	v_mfma_f32_16x16x32_bf16 v[40:43], v[162:165], v[186:189], 0
	v_mfma_f32_16x16x32_bf16 v[32:35], v[170:173], v[186:189], 0
	v_mfma_f32_16x16x32_bf16 v[24:27], v[162:165], v[230:233], 0
	v_mfma_f32_16x16x32_bf16 v[16:19], v[170:173], v[230:233], 0
	v_mfma_f32_16x16x32_bf16 v[8:11], v[162:165], v[238:241], 0
	v_mfma_f32_16x16x32_bf16 v[0:3], v[170:173], v[238:241], 0
	v_mfma_f32_16x16x32_bf16 v[56:59], v[166:169], v[182:185], v[56:59]
	v_mfma_f32_16x16x32_bf16 v[48:51], v[174:177], v[182:185], v[48:51]
	v_mfma_f32_16x16x32_bf16 v[40:43], v[166:169], v[208:211], v[40:43]
	v_mfma_f32_16x16x32_bf16 v[32:35], v[174:177], v[208:211], v[32:35]
	v_mfma_f32_16x16x32_bf16 v[24:27], v[166:169], v[234:237], v[24:27]
	v_mfma_f32_16x16x32_bf16 v[16:19], v[174:177], v[234:237], v[16:19]
	v_mfma_f32_16x16x32_bf16 v[8:11], v[166:169], v[242:245], v[8:11]
	v_mfma_f32_16x16x32_bf16 v[0:3], v[174:177], v[242:245], v[0:3]
	s_setprio 0
	s_barrier
	s_add_i32 s55, 0, 0x18000
	v_add_u32_e32 v144, s55, v146
	s_add_i32 s56, 0, 0x1c000
	ds_read_b128 v[140:143], v144
	ds_read_b128 v[150:153], v144 offset:1024
	ds_read_b128 v[154:157], v144 offset:2048
	ds_read_b128 v[158:161], v144 offset:3072
	v_add_u32_e32 v144, s56, v146
	ds_read_b128 v[162:165], v144
	ds_read_b128 v[166:169], v144 offset:1024
	ds_read_b128 v[170:173], v144 offset:2048
	ds_read_b128 v[174:177], v144 offset:3072
	s_add_u32 s28, s28, 0x40000
	s_addc_u32 s29, s29, 0
	s_mov_b32 m0, s45
	ds_read_b128 v[178:181], v149 offset:32768
	ds_read_b128 v[182:185], v149 offset:33792
	ds_read_b128 v[186:189], v149 offset:34816
	ds_read_b128 v[208:211], v149 offset:35840
	ds_read_b128 v[230:233], v149 offset:36864
	ds_read_b128 v[234:237], v149 offset:37888
	ds_read_b128 v[238:241], v149 offset:38912
	ds_read_b128 v[242:245], v149 offset:39936
	global_load_lds_dwordx4 v130, s[28:29]
	s_mov_b32 m0, s46
	s_nop 0
	global_load_lds_dwordx4 v132, s[28:29]
	s_waitcnt vmcnt(8)
	s_waitcnt lgkmcnt(0)
	s_setprio 1
	s_barrier
	v_mfma_f32_16x16x32_bf16 v[126:129], v[140:143], v[178:181], v[126:129]
	v_mfma_f32_16x16x32_bf16 v[118:121], v[154:157], v[178:181], v[118:121]
	v_mfma_f32_16x16x32_bf16 v[108:111], v[140:143], v[186:189], v[108:111]
	v_mfma_f32_16x16x32_bf16 v[100:103], v[154:157], v[186:189], v[100:103]
	v_mfma_f32_16x16x32_bf16 v[92:95], v[140:143], v[230:233], v[92:95]
	v_mfma_f32_16x16x32_bf16 v[84:87], v[154:157], v[230:233], v[84:87]
	v_mfma_f32_16x16x32_bf16 v[76:79], v[140:143], v[238:241], v[76:79]
	v_mfma_f32_16x16x32_bf16 v[68:71], v[154:157], v[238:241], v[68:71]
	v_mfma_f32_16x16x32_bf16 v[126:129], v[150:153], v[182:185], v[126:129]
	v_mfma_f32_16x16x32_bf16 v[118:121], v[158:161], v[182:185], v[118:121]
	v_mfma_f32_16x16x32_bf16 v[108:111], v[150:153], v[208:211], v[108:111]
	v_mfma_f32_16x16x32_bf16 v[100:103], v[158:161], v[208:211], v[100:103]
	v_mfma_f32_16x16x32_bf16 v[92:95], v[150:153], v[234:237], v[92:95]
	v_mfma_f32_16x16x32_bf16 v[84:87], v[158:161], v[234:237], v[84:87]
	v_mfma_f32_16x16x32_bf16 v[76:79], v[150:153], v[242:245], v[76:79]
	v_mfma_f32_16x16x32_bf16 v[68:71], v[158:161], v[242:245], v[68:71]
	s_setprio 0
	s_setprio 1
	v_mfma_f32_16x16x32_bf16 v[122:125], v[162:165], v[178:181], v[122:125]
	v_mfma_f32_16x16x32_bf16 v[114:117], v[170:173], v[178:181], v[114:117]
	v_mfma_f32_16x16x32_bf16 v[104:107], v[162:165], v[186:189], v[104:107]
	v_mfma_f32_16x16x32_bf16 v[96:99], v[170:173], v[186:189], v[96:99]
	v_mfma_f32_16x16x32_bf16 v[88:91], v[162:165], v[230:233], v[88:91]
	v_mfma_f32_16x16x32_bf16 v[80:83], v[170:173], v[230:233], v[80:83]
	v_mfma_f32_16x16x32_bf16 v[72:75], v[162:165], v[238:241], v[72:75]
	v_mfma_f32_16x16x32_bf16 v[64:67], v[170:173], v[238:241], v[64:67]
	v_mfma_f32_16x16x32_bf16 v[122:125], v[166:169], v[182:185], v[122:125]
	v_mfma_f32_16x16x32_bf16 v[114:117], v[174:177], v[182:185], v[114:117]
	v_mfma_f32_16x16x32_bf16 v[104:107], v[166:169], v[208:211], v[104:107]
	v_mfma_f32_16x16x32_bf16 v[96:99], v[174:177], v[208:211], v[96:99]
	v_mfma_f32_16x16x32_bf16 v[88:91], v[166:169], v[234:237], v[88:91]
	v_mfma_f32_16x16x32_bf16 v[80:83], v[174:177], v[234:237], v[80:83]
	v_mfma_f32_16x16x32_bf16 v[72:75], v[166:169], v[242:245], v[72:75]
	v_mfma_f32_16x16x32_bf16 v[64:67], v[174:177], v[242:245], v[64:67]
	s_setprio 0
	s_barrier
	s_add_i32 s28, s55, s35
	s_mov_b32 m0, s28
	ds_read_b128 v[178:181], v149 offset:49152
	ds_read_b128 v[182:185], v149 offset:50176
	ds_read_b128 v[186:189], v149 offset:51200
	ds_read_b128 v[208:211], v149 offset:52224
	ds_read_b128 v[230:233], v149 offset:53248
	ds_read_b128 v[234:237], v149 offset:54272
	ds_read_b128 v[238:241], v149 offset:55296
	ds_read_b128 v[242:245], v149 offset:56320
	s_add_u32 s98, s26, 0x80
	s_addc_u32 s99, s27, 0
	global_load_lds_dwordx4 v112, s[98:99]
	s_add_i32 m0, s28, 0x2000
	s_add_u32 s26, s26, 0x40080
	v_lshl_add_u64 v[212:213], v[246:247], 0, s[96:97]
	s_addc_u32 s27, s27, 0
	s_add_i32 s28, s56, s35
	global_load_lds_dwordx4 v[212:213], off
	s_mov_b32 m0, s28
	s_nop 0
	global_load_lds_dwordx4 v112, s[26:27]
	s_add_i32 m0, s28, 0x2000
	s_nop 0
	global_load_lds_dwordx4 v134, s[26:27]
	v_lshl_add_u64 v[212:213], v[248:249], 0, s[96:97]
	s_mov_b32 m0, s47
	s_nop 0
	global_load_lds_dwordx4 v[212:213], off
	v_lshl_add_u64 v[212:213], v[250:251], 0, s[96:97]
	s_mov_b32 m0, s48
	s_nop 0
	global_load_lds_dwordx4 v[212:213], off
	s_waitcnt vmcnt(8)
	s_waitcnt lgkmcnt(0)
	s_setprio 1
	s_barrier
	v_mfma_f32_16x16x32_bf16 v[60:63], v[140:143], v[178:181], v[60:63]
	v_mfma_f32_16x16x32_bf16 v[52:55], v[154:157], v[178:181], v[52:55]
	v_mfma_f32_16x16x32_bf16 v[44:47], v[140:143], v[186:189], v[44:47]
	v_mfma_f32_16x16x32_bf16 v[36:39], v[154:157], v[186:189], v[36:39]
	v_mfma_f32_16x16x32_bf16 v[28:31], v[140:143], v[230:233], v[28:31]
	v_mfma_f32_16x16x32_bf16 v[20:23], v[154:157], v[230:233], v[20:23]
	v_mfma_f32_16x16x32_bf16 v[12:15], v[140:143], v[238:241], v[12:15]
	v_mfma_f32_16x16x32_bf16 v[4:7], v[154:157], v[238:241], v[4:7]
	v_mfma_f32_16x16x32_bf16 v[60:63], v[150:153], v[182:185], v[60:63]
	v_mfma_f32_16x16x32_bf16 v[52:55], v[158:161], v[182:185], v[52:55]
	v_mfma_f32_16x16x32_bf16 v[44:47], v[150:153], v[208:211], v[44:47]
	v_mfma_f32_16x16x32_bf16 v[36:39], v[158:161], v[208:211], v[36:39]
	v_mfma_f32_16x16x32_bf16 v[28:31], v[150:153], v[234:237], v[28:31]
	v_mfma_f32_16x16x32_bf16 v[20:23], v[158:161], v[234:237], v[20:23]
	v_mfma_f32_16x16x32_bf16 v[12:15], v[150:153], v[242:245], v[12:15]
	v_mfma_f32_16x16x32_bf16 v[4:7], v[158:161], v[242:245], v[4:7]
	s_setprio 0
	s_setprio 1
	v_mfma_f32_16x16x32_bf16 v[56:59], v[162:165], v[178:181], v[56:59]
	v_mfma_f32_16x16x32_bf16 v[48:51], v[170:173], v[178:181], v[48:51]
	v_mfma_f32_16x16x32_bf16 v[40:43], v[162:165], v[186:189], v[40:43]
	v_mfma_f32_16x16x32_bf16 v[32:35], v[170:173], v[186:189], v[32:35]
	v_mfma_f32_16x16x32_bf16 v[24:27], v[162:165], v[230:233], v[24:27]
	v_mfma_f32_16x16x32_bf16 v[16:19], v[170:173], v[230:233], v[16:19]
	v_mfma_f32_16x16x32_bf16 v[8:11], v[162:165], v[238:241], v[8:11]
	v_mfma_f32_16x16x32_bf16 v[0:3], v[170:173], v[238:241], v[0:3]
	v_mfma_f32_16x16x32_bf16 v[56:59], v[166:169], v[182:185], v[56:59]
	v_mfma_f32_16x16x32_bf16 v[48:51], v[174:177], v[182:185], v[48:51]
	v_mfma_f32_16x16x32_bf16 v[40:43], v[166:169], v[208:211], v[40:43]
	v_mfma_f32_16x16x32_bf16 v[32:35], v[174:177], v[208:211], v[32:35]
	v_mfma_f32_16x16x32_bf16 v[24:27], v[166:169], v[234:237], v[24:27]
	v_mfma_f32_16x16x32_bf16 v[16:19], v[174:177], v[234:237], v[16:19]
	v_mfma_f32_16x16x32_bf16 v[8:11], v[166:169], v[242:245], v[8:11]
	v_mfma_f32_16x16x32_bf16 v[0:3], v[174:177], v[242:245], v[0:3]
	s_setprio 0
	s_barrier
	s_add_i32 s54, s54, 2
	s_add_u32 s52, s52, 0x100
	s_addc_u32 s53, s53, 0
	s_add_u32 s24, s24, 0x100
	s_addc_u32 s25, s25, 0
	s_cmp_gt_u32 s54, 13
	s_cbranch_scc0 .LBB0_1952
	s_branch .Lpeel_exit_1952
.LBB0_1952:
	s_add_u32 s26, s24, 0xfffc0080
	s_addc_u32 s27, s25, -1
	s_add_i32 s55, 0, 0x10000
	s_cmp_eq_u32 s54, 12
	s_cselect_b32 s29, s5, s27
	s_cselect_b32 s28, s17, s26
	v_add_u32_e32 v144, s55, v146
	s_cselect_b32 s27, s15, s53
	s_cselect_b32 s26, s51, s52
	s_add_i32 s58, 0, 0x14000
	ds_read_b128 v[140:143], v144
	ds_read_b128 v[150:153], v144 offset:1024
	ds_read_b128 v[154:157], v144 offset:2048
	ds_read_b128 v[158:161], v144 offset:3072
	v_add_u32_e32 v144, s58, v146
	ds_read_b128 v[162:165], v144
	ds_read_b128 v[166:169], v144 offset:1024
	ds_read_b128 v[170:173], v144 offset:2048
	ds_read_b128 v[174:177], v144 offset:3072
	s_add_i32 m0, s23, 0xc000
	ds_read_b128 v[178:181], v149
	ds_read_b128 v[182:185], v149 offset:1024
	ds_read_b128 v[186:189], v149 offset:2048
	ds_read_b128 v[208:211], v149 offset:3072
	ds_read_b128 v[230:233], v149 offset:4096
	ds_read_b128 v[234:237], v149 offset:5120
	ds_read_b128 v[238:241], v149 offset:6144
	ds_read_b128 v[242:245], v149 offset:7168
	global_load_lds_dwordx4 v138, s[24:25]
	s_add_i32 m0, s23, 0xe000
	s_nop 0
	global_load_lds_dwordx4 v136, s[24:25]
	s_waitcnt vmcnt(8)
	s_waitcnt lgkmcnt(0)
	s_setprio 1
	s_barrier
	v_mfma_f32_16x16x32_bf16 v[126:129], v[140:143], v[178:181], v[126:129]
	v_mfma_f32_16x16x32_bf16 v[118:121], v[154:157], v[178:181], v[118:121]
	v_mfma_f32_16x16x32_bf16 v[108:111], v[140:143], v[186:189], v[108:111]
	v_mfma_f32_16x16x32_bf16 v[100:103], v[154:157], v[186:189], v[100:103]
	v_mfma_f32_16x16x32_bf16 v[92:95], v[140:143], v[230:233], v[92:95]
	v_mfma_f32_16x16x32_bf16 v[84:87], v[154:157], v[230:233], v[84:87]
	v_mfma_f32_16x16x32_bf16 v[76:79], v[140:143], v[238:241], v[76:79]
	v_mfma_f32_16x16x32_bf16 v[68:71], v[154:157], v[238:241], v[68:71]
	v_mfma_f32_16x16x32_bf16 v[126:129], v[150:153], v[182:185], v[126:129]
	v_mfma_f32_16x16x32_bf16 v[118:121], v[158:161], v[182:185], v[118:121]
	v_mfma_f32_16x16x32_bf16 v[108:111], v[150:153], v[208:211], v[108:111]
	v_mfma_f32_16x16x32_bf16 v[100:103], v[158:161], v[208:211], v[100:103]
	v_mfma_f32_16x16x32_bf16 v[92:95], v[150:153], v[234:237], v[92:95]
	v_mfma_f32_16x16x32_bf16 v[84:87], v[158:161], v[234:237], v[84:87]
	v_mfma_f32_16x16x32_bf16 v[76:79], v[150:153], v[242:245], v[76:79]
	v_mfma_f32_16x16x32_bf16 v[68:71], v[158:161], v[242:245], v[68:71]
	s_setprio 0
	s_setprio 1
	v_mfma_f32_16x16x32_bf16 v[122:125], v[162:165], v[178:181], v[122:125]
	v_mfma_f32_16x16x32_bf16 v[114:117], v[170:173], v[178:181], v[114:117]
	v_mfma_f32_16x16x32_bf16 v[104:107], v[162:165], v[186:189], v[104:107]
	v_mfma_f32_16x16x32_bf16 v[96:99], v[170:173], v[186:189], v[96:99]
	v_mfma_f32_16x16x32_bf16 v[88:91], v[162:165], v[230:233], v[88:91]
	v_mfma_f32_16x16x32_bf16 v[80:83], v[170:173], v[230:233], v[80:83]
	v_mfma_f32_16x16x32_bf16 v[72:75], v[162:165], v[238:241], v[72:75]
	v_mfma_f32_16x16x32_bf16 v[64:67], v[170:173], v[238:241], v[64:67]
	v_mfma_f32_16x16x32_bf16 v[122:125], v[166:169], v[182:185], v[122:125]
	v_mfma_f32_16x16x32_bf16 v[114:117], v[174:177], v[182:185], v[114:117]
	v_mfma_f32_16x16x32_bf16 v[104:107], v[166:169], v[208:211], v[104:107]
	v_mfma_f32_16x16x32_bf16 v[96:99], v[174:177], v[208:211], v[96:99]
	v_mfma_f32_16x16x32_bf16 v[88:91], v[166:169], v[234:237], v[88:91]
	v_mfma_f32_16x16x32_bf16 v[80:83], v[174:177], v[234:237], v[80:83]
	v_mfma_f32_16x16x32_bf16 v[72:75], v[166:169], v[242:245], v[72:75]
	v_mfma_f32_16x16x32_bf16 v[64:67], v[174:177], v[242:245], v[64:67]
	s_setprio 0
	s_barrier
	s_add_i32 s55, s55, s35
	s_mov_b32 m0, s55
	ds_read_b128 v[178:181], v149 offset:16384
	ds_read_b128 v[182:185], v149 offset:17408
	ds_read_b128 v[186:189], v149 offset:18432
	ds_read_b128 v[208:211], v149 offset:19456
	ds_read_b128 v[230:233], v149 offset:20480
	ds_read_b128 v[234:237], v149 offset:21504
	ds_read_b128 v[238:241], v149 offset:22528
	ds_read_b128 v[242:245], v149 offset:23552
	global_load_lds_dwordx4 v112, s[26:27]
	s_add_i32 m0, s55, 0x2000
	s_add_u32 s56, s26, 0x40000
	v_lshl_add_u64 v[246:247], s[26:27], 0, v[134:135]
	s_addc_u32 s57, s27, 0
	s_add_i32 s55, s58, s35
	global_load_lds_dwordx4 v134, s[26:27]
	s_mov_b32 m0, s55
	v_lshl_add_u64 v[250:251], s[28:29], 0, v[132:133]
	global_load_lds_dwordx4 v112, s[56:57]
	s_add_i32 m0, s55, 0x2000
	s_nop 0
	global_load_lds_dwordx4 v134, s[56:57]
	v_lshl_add_u64 v[248:249], s[28:29], 0, v[130:131]
	s_mov_b32 m0, s23
	s_nop 0
	global_load_lds_dwordx4 v130, s[28:29]
	s_mov_b32 m0, s44
	s_nop 0
	global_load_lds_dwordx4 v132, s[28:29]
	s_waitcnt vmcnt(8)
	s_waitcnt lgkmcnt(0)
	s_setprio 1
	s_barrier
	v_mfma_f32_16x16x32_bf16 v[60:63], v[140:143], v[178:181], v[60:63]
	v_mfma_f32_16x16x32_bf16 v[52:55], v[154:157], v[178:181], v[52:55]
	v_mfma_f32_16x16x32_bf16 v[44:47], v[140:143], v[186:189], v[44:47]
	v_mfma_f32_16x16x32_bf16 v[36:39], v[154:157], v[186:189], v[36:39]
	v_mfma_f32_16x16x32_bf16 v[28:31], v[140:143], v[230:233], v[28:31]
	v_mfma_f32_16x16x32_bf16 v[20:23], v[154:157], v[230:233], v[20:23]
	v_mfma_f32_16x16x32_bf16 v[12:15], v[140:143], v[238:241], v[12:15]
	v_mfma_f32_16x16x32_bf16 v[4:7], v[154:157], v[238:241], v[4:7]
	v_mfma_f32_16x16x32_bf16 v[60:63], v[150:153], v[182:185], v[60:63]
	v_mfma_f32_16x16x32_bf16 v[52:55], v[158:161], v[182:185], v[52:55]
	v_mfma_f32_16x16x32_bf16 v[44:47], v[150:153], v[208:211], v[44:47]
	v_mfma_f32_16x16x32_bf16 v[36:39], v[158:161], v[208:211], v[36:39]
	v_mfma_f32_16x16x32_bf16 v[28:31], v[150:153], v[234:237], v[28:31]
	v_mfma_f32_16x16x32_bf16 v[20:23], v[158:161], v[234:237], v[20:23]
	v_mfma_f32_16x16x32_bf16 v[12:15], v[150:153], v[242:245], v[12:15]
	v_mfma_f32_16x16x32_bf16 v[4:7], v[158:161], v[242:245], v[4:7]
	s_setprio 0
	s_setprio 1
	v_mfma_f32_16x16x32_bf16 v[56:59], v[162:165], v[178:181], v[56:59]
	v_mfma_f32_16x16x32_bf16 v[48:51], v[170:173], v[178:181], v[48:51]
	v_mfma_f32_16x16x32_bf16 v[40:43], v[162:165], v[186:189], v[40:43]
	v_mfma_f32_16x16x32_bf16 v[32:35], v[170:173], v[186:189], v[32:35]
	v_mfma_f32_16x16x32_bf16 v[24:27], v[162:165], v[230:233], v[24:27]
	v_mfma_f32_16x16x32_bf16 v[16:19], v[170:173], v[230:233], v[16:19]
	v_mfma_f32_16x16x32_bf16 v[8:11], v[162:165], v[238:241], v[8:11]
	v_mfma_f32_16x16x32_bf16 v[0:3], v[170:173], v[238:241], v[0:3]
	v_mfma_f32_16x16x32_bf16 v[56:59], v[166:169], v[182:185], v[56:59]
	v_mfma_f32_16x16x32_bf16 v[48:51], v[174:177], v[182:185], v[48:51]
	v_mfma_f32_16x16x32_bf16 v[40:43], v[166:169], v[208:211], v[40:43]
	v_mfma_f32_16x16x32_bf16 v[32:35], v[174:177], v[208:211], v[32:35]
	v_mfma_f32_16x16x32_bf16 v[24:27], v[166:169], v[234:237], v[24:27]
	v_mfma_f32_16x16x32_bf16 v[16:19], v[174:177], v[234:237], v[16:19]
	v_mfma_f32_16x16x32_bf16 v[8:11], v[166:169], v[242:245], v[8:11]
	v_mfma_f32_16x16x32_bf16 v[0:3], v[174:177], v[242:245], v[0:3]
	s_setprio 0
	s_barrier
	s_add_i32 s55, 0, 0x18000
	v_add_u32_e32 v144, s55, v146
	s_add_i32 s56, 0, 0x1c000
	ds_read_b128 v[140:143], v144
	ds_read_b128 v[150:153], v144 offset:1024
	ds_read_b128 v[154:157], v144 offset:2048
	ds_read_b128 v[158:161], v144 offset:3072
	v_add_u32_e32 v144, s56, v146
	ds_read_b128 v[162:165], v144
	ds_read_b128 v[166:169], v144 offset:1024
	ds_read_b128 v[170:173], v144 offset:2048
	ds_read_b128 v[174:177], v144 offset:3072
	s_add_u32 s28, s28, 0x40000
	s_addc_u32 s29, s29, 0
	s_mov_b32 m0, s45
	ds_read_b128 v[178:181], v149 offset:32768
	ds_read_b128 v[182:185], v149 offset:33792
	ds_read_b128 v[186:189], v149 offset:34816
	ds_read_b128 v[208:211], v149 offset:35840
	ds_read_b128 v[230:233], v149 offset:36864
	ds_read_b128 v[234:237], v149 offset:37888
	ds_read_b128 v[238:241], v149 offset:38912
	ds_read_b128 v[242:245], v149 offset:39936
	global_load_lds_dwordx4 v130, s[28:29]
	s_mov_b32 m0, s46
	s_nop 0
	global_load_lds_dwordx4 v132, s[28:29]
	s_waitcnt vmcnt(8)
	s_waitcnt lgkmcnt(0)
	s_setprio 1
	s_barrier
	v_mfma_f32_16x16x32_bf16 v[126:129], v[140:143], v[178:181], v[126:129]
	v_mfma_f32_16x16x32_bf16 v[118:121], v[154:157], v[178:181], v[118:121]
	v_mfma_f32_16x16x32_bf16 v[108:111], v[140:143], v[186:189], v[108:111]
	v_mfma_f32_16x16x32_bf16 v[100:103], v[154:157], v[186:189], v[100:103]
	v_mfma_f32_16x16x32_bf16 v[92:95], v[140:143], v[230:233], v[92:95]
	v_mfma_f32_16x16x32_bf16 v[84:87], v[154:157], v[230:233], v[84:87]
	v_mfma_f32_16x16x32_bf16 v[76:79], v[140:143], v[238:241], v[76:79]
	v_mfma_f32_16x16x32_bf16 v[68:71], v[154:157], v[238:241], v[68:71]
	v_mfma_f32_16x16x32_bf16 v[126:129], v[150:153], v[182:185], v[126:129]
	v_mfma_f32_16x16x32_bf16 v[118:121], v[158:161], v[182:185], v[118:121]
	v_mfma_f32_16x16x32_bf16 v[108:111], v[150:153], v[208:211], v[108:111]
	v_mfma_f32_16x16x32_bf16 v[100:103], v[158:161], v[208:211], v[100:103]
	v_mfma_f32_16x16x32_bf16 v[92:95], v[150:153], v[234:237], v[92:95]
	v_mfma_f32_16x16x32_bf16 v[84:87], v[158:161], v[234:237], v[84:87]
	v_mfma_f32_16x16x32_bf16 v[76:79], v[150:153], v[242:245], v[76:79]
	v_mfma_f32_16x16x32_bf16 v[68:71], v[158:161], v[242:245], v[68:71]
	s_setprio 0
	s_setprio 1
	v_mfma_f32_16x16x32_bf16 v[122:125], v[162:165], v[178:181], v[122:125]
	v_mfma_f32_16x16x32_bf16 v[114:117], v[170:173], v[178:181], v[114:117]
	v_mfma_f32_16x16x32_bf16 v[104:107], v[162:165], v[186:189], v[104:107]
	v_mfma_f32_16x16x32_bf16 v[96:99], v[170:173], v[186:189], v[96:99]
	v_mfma_f32_16x16x32_bf16 v[88:91], v[162:165], v[230:233], v[88:91]
	v_mfma_f32_16x16x32_bf16 v[80:83], v[170:173], v[230:233], v[80:83]
	v_mfma_f32_16x16x32_bf16 v[72:75], v[162:165], v[238:241], v[72:75]
	v_mfma_f32_16x16x32_bf16 v[64:67], v[170:173], v[238:241], v[64:67]
	v_mfma_f32_16x16x32_bf16 v[122:125], v[166:169], v[182:185], v[122:125]
	v_mfma_f32_16x16x32_bf16 v[114:117], v[174:177], v[182:185], v[114:117]
	v_mfma_f32_16x16x32_bf16 v[104:107], v[166:169], v[208:211], v[104:107]
	v_mfma_f32_16x16x32_bf16 v[96:99], v[174:177], v[208:211], v[96:99]
	v_mfma_f32_16x16x32_bf16 v[88:91], v[166:169], v[234:237], v[88:91]
	v_mfma_f32_16x16x32_bf16 v[80:83], v[174:177], v[234:237], v[80:83]
	v_mfma_f32_16x16x32_bf16 v[72:75], v[166:169], v[242:245], v[72:75]
	v_mfma_f32_16x16x32_bf16 v[64:67], v[174:177], v[242:245], v[64:67]
	s_setprio 0
	s_barrier
	s_add_i32 s28, s55, s35
	s_mov_b32 m0, s28
	ds_read_b128 v[178:181], v149 offset:49152
	ds_read_b128 v[182:185], v149 offset:50176
	ds_read_b128 v[186:189], v149 offset:51200
	ds_read_b128 v[208:211], v149 offset:52224
	ds_read_b128 v[230:233], v149 offset:53248
	ds_read_b128 v[234:237], v149 offset:54272
	ds_read_b128 v[238:241], v149 offset:55296
	ds_read_b128 v[242:245], v149 offset:56320
	s_add_u32 s98, s26, 0x80
	s_addc_u32 s99, s27, 0
	global_load_lds_dwordx4 v112, s[98:99]
	s_add_i32 m0, s28, 0x2000
	s_add_u32 s26, s26, 0x40080
	v_lshl_add_u64 v[212:213], v[246:247], 0, s[96:97]
	s_addc_u32 s27, s27, 0
	s_add_i32 s28, s56, s35
	global_load_lds_dwordx4 v[212:213], off
	s_mov_b32 m0, s28
	s_nop 0
	global_load_lds_dwordx4 v112, s[26:27]
	s_add_i32 m0, s28, 0x2000
	s_nop 0
	global_load_lds_dwordx4 v134, s[26:27]
	v_lshl_add_u64 v[212:213], v[248:249], 0, s[96:97]
	s_mov_b32 m0, s47
	s_nop 0
	global_load_lds_dwordx4 v[212:213], off
	v_lshl_add_u64 v[212:213], v[250:251], 0, s[96:97]
	s_mov_b32 m0, s48
	s_nop 0
	global_load_lds_dwordx4 v[212:213], off
	s_waitcnt vmcnt(8)
	s_waitcnt lgkmcnt(0)
	s_setprio 1
	s_barrier
	v_mfma_f32_16x16x32_bf16 v[60:63], v[140:143], v[178:181], v[60:63]
	v_mfma_f32_16x16x32_bf16 v[52:55], v[154:157], v[178:181], v[52:55]
	v_mfma_f32_16x16x32_bf16 v[44:47], v[140:143], v[186:189], v[44:47]
	v_mfma_f32_16x16x32_bf16 v[36:39], v[154:157], v[186:189], v[36:39]
	v_mfma_f32_16x16x32_bf16 v[28:31], v[140:143], v[230:233], v[28:31]
	v_mfma_f32_16x16x32_bf16 v[20:23], v[154:157], v[230:233], v[20:23]
	v_mfma_f32_16x16x32_bf16 v[12:15], v[140:143], v[238:241], v[12:15]
	v_mfma_f32_16x16x32_bf16 v[4:7], v[154:157], v[238:241], v[4:7]
	v_mfma_f32_16x16x32_bf16 v[60:63], v[150:153], v[182:185], v[60:63]
	v_mfma_f32_16x16x32_bf16 v[52:55], v[158:161], v[182:185], v[52:55]
	v_mfma_f32_16x16x32_bf16 v[44:47], v[150:153], v[208:211], v[44:47]
	v_mfma_f32_16x16x32_bf16 v[36:39], v[158:161], v[208:211], v[36:39]
	v_mfma_f32_16x16x32_bf16 v[28:31], v[150:153], v[234:237], v[28:31]
	v_mfma_f32_16x16x32_bf16 v[20:23], v[158:161], v[234:237], v[20:23]
	v_mfma_f32_16x16x32_bf16 v[12:15], v[150:153], v[242:245], v[12:15]
	v_mfma_f32_16x16x32_bf16 v[4:7], v[158:161], v[242:245], v[4:7]
	s_setprio 0
	s_setprio 1
	v_mfma_f32_16x16x32_bf16 v[56:59], v[162:165], v[178:181], v[56:59]
	v_mfma_f32_16x16x32_bf16 v[48:51], v[170:173], v[178:181], v[48:51]
	v_mfma_f32_16x16x32_bf16 v[40:43], v[162:165], v[186:189], v[40:43]
	v_mfma_f32_16x16x32_bf16 v[32:35], v[170:173], v[186:189], v[32:35]
	v_mfma_f32_16x16x32_bf16 v[24:27], v[162:165], v[230:233], v[24:27]
	v_mfma_f32_16x16x32_bf16 v[16:19], v[170:173], v[230:233], v[16:19]
	v_mfma_f32_16x16x32_bf16 v[8:11], v[162:165], v[238:241], v[8:11]
	v_mfma_f32_16x16x32_bf16 v[0:3], v[170:173], v[238:241], v[0:3]
	v_mfma_f32_16x16x32_bf16 v[56:59], v[166:169], v[182:185], v[56:59]
	v_mfma_f32_16x16x32_bf16 v[48:51], v[174:177], v[182:185], v[48:51]
	v_mfma_f32_16x16x32_bf16 v[40:43], v[166:169], v[208:211], v[40:43]
	v_mfma_f32_16x16x32_bf16 v[32:35], v[174:177], v[208:211], v[32:35]
	v_mfma_f32_16x16x32_bf16 v[24:27], v[166:169], v[234:237], v[24:27]
	v_mfma_f32_16x16x32_bf16 v[16:19], v[174:177], v[234:237], v[16:19]
	v_mfma_f32_16x16x32_bf16 v[8:11], v[166:169], v[242:245], v[8:11]
	v_mfma_f32_16x16x32_bf16 v[0:3], v[174:177], v[242:245], v[0:3]
	s_setprio 0
	s_barrier
	s_add_i32 s54, s54, 2
	s_add_u32 s52, s52, 0x100
	s_addc_u32 s53, s53, 0
	s_add_u32 s24, s24, 0x100
	s_addc_u32 s25, s25, 0
	s_cmp_gt_u32 s54, 13
	s_cbranch_scc0 .LBB0_1952

.LBB0_2150:
	s_ashr_i32 s29, s28, 31
	s_lshl_b64 s[30:31], s[28:29], 19
	s_add_u32 s30, s49, s30
	s_addc_u32 s31, s50, s31
	s_and_b64 s[40:41], s[6:7], exec
	s_cselect_b32 s11, s31, s39
	s_cselect_b32 s29, s30, s38
	s_ashr_i32 s27, s26, 31
	s_lshl_b64 s[40:41], s[26:27], 19
	s_add_u32 s46, s51, s40
	s_addc_u32 s47, s52, s41
	s_and_b64 s[40:41], s[6:7], exec
	s_cselect_b32 s27, s47, s9
	s_cselect_b32 s35, s46, s8
	s_add_u32 s42, s8, 0x100
	s_addc_u32 s43, s9, 0
	s_add_u32 s8, s38, 0x40080
	s_addc_u32 s9, s39, 0
	s_mov_b32 s44, -2
	s_add_u32 s38, s8, 0xfffc0080
	s_addc_u32 s39, s9, -1
	s_add_i32 s45, 0, 0x10000
	s_cmp_eq_u32 s44, 12
	s_cselect_b32 s41, s11, s39
	s_cselect_b32 s40, s29, s38
	v_add_u32_e32 v112, s45, v169
	s_cselect_b32 s39, s27, s43
	s_cselect_b32 s38, s35, s42
	s_add_i32 s68, 0, 0x14000
	ds_read_b128 v[130:133], v112
	ds_read_b128 v[134:137], v112 offset:1024
	ds_read_b128 v[150:153], v112 offset:2048
	ds_read_b128 v[154:157], v112 offset:3072
	v_add_u32_e32 v112, s68, v169
	ds_read_b128 v[158:161], v112
	ds_read_b128 v[162:165], v112 offset:1024
	ds_read_b128 v[174:177], v112 offset:2048
	ds_read_b128 v[178:181], v112 offset:3072
	s_add_i32 m0, s37, 0xc000
	ds_read_b128 v[182:185], v172
	ds_read_b128 v[186:189], v172 offset:1024
	ds_read_b128 v[208:211], v172 offset:2048
	ds_read_b128 v[230:233], v172 offset:3072
	ds_read_b128 v[234:237], v172 offset:4096
	ds_read_b128 v[238:241], v172 offset:5120
	ds_read_b128 v[242:245], v172 offset:6144
	ds_read_b128 v[246:249], v172 offset:7168
	global_load_lds_dwordx4 v148, s[8:9]
	s_add_i32 m0, s37, 0xe000
	s_nop 0
	global_load_lds_dwordx4 v146, s[8:9]
	s_waitcnt vmcnt(8)
	s_waitcnt lgkmcnt(0)
	s_setprio 1
	s_barrier
	v_mfma_f32_16x16x32_bf16 v[126:129], v[130:133], v[182:185], 0
	v_mfma_f32_16x16x32_bf16 v[122:125], v[150:153], v[182:185], 0
	v_mfma_f32_16x16x32_bf16 v[108:111], v[130:133], v[208:211], 0
	v_mfma_f32_16x16x32_bf16 v[104:107], v[150:153], v[208:211], 0
	v_mfma_f32_16x16x32_bf16 v[92:95], v[130:133], v[234:237], 0
	v_mfma_f32_16x16x32_bf16 v[88:91], v[150:153], v[234:237], 0
	v_mfma_f32_16x16x32_bf16 v[76:79], v[130:133], v[242:245], 0
	v_mfma_f32_16x16x32_bf16 v[72:75], v[150:153], v[242:245], 0
	v_mfma_f32_16x16x32_bf16 v[126:129], v[134:137], v[186:189], v[126:129]
	v_mfma_f32_16x16x32_bf16 v[122:125], v[154:157], v[186:189], v[122:125]
	v_mfma_f32_16x16x32_bf16 v[108:111], v[134:137], v[230:233], v[108:111]
	v_mfma_f32_16x16x32_bf16 v[104:107], v[154:157], v[230:233], v[104:107]
	v_mfma_f32_16x16x32_bf16 v[92:95], v[134:137], v[238:241], v[92:95]
	v_mfma_f32_16x16x32_bf16 v[88:91], v[154:157], v[238:241], v[88:91]
	v_mfma_f32_16x16x32_bf16 v[76:79], v[134:137], v[246:249], v[76:79]
	v_mfma_f32_16x16x32_bf16 v[72:75], v[154:157], v[246:249], v[72:75]
	s_setprio 0
	s_setprio 1
	v_mfma_f32_16x16x32_bf16 v[118:121], v[158:161], v[182:185], 0
	v_mfma_f32_16x16x32_bf16 v[114:117], v[174:177], v[182:185], 0
	v_mfma_f32_16x16x32_bf16 v[100:103], v[158:161], v[208:211], 0
	v_mfma_f32_16x16x32_bf16 v[96:99], v[174:177], v[208:211], 0
	v_mfma_f32_16x16x32_bf16 v[84:87], v[158:161], v[234:237], 0
	v_mfma_f32_16x16x32_bf16 v[80:83], v[174:177], v[234:237], 0
	v_mfma_f32_16x16x32_bf16 v[68:71], v[158:161], v[242:245], 0
	v_mfma_f32_16x16x32_bf16 v[64:67], v[174:177], v[242:245], 0
	v_mfma_f32_16x16x32_bf16 v[118:121], v[162:165], v[186:189], v[118:121]
	v_mfma_f32_16x16x32_bf16 v[114:117], v[178:181], v[186:189], v[114:117]
	v_mfma_f32_16x16x32_bf16 v[100:103], v[162:165], v[230:233], v[100:103]
	v_mfma_f32_16x16x32_bf16 v[96:99], v[178:181], v[230:233], v[96:99]
	v_mfma_f32_16x16x32_bf16 v[84:87], v[162:165], v[238:241], v[84:87]
	v_mfma_f32_16x16x32_bf16 v[80:83], v[178:181], v[238:241], v[80:83]
	v_mfma_f32_16x16x32_bf16 v[68:71], v[162:165], v[246:249], v[68:71]
	v_mfma_f32_16x16x32_bf16 v[64:67], v[178:181], v[246:249], v[64:67]
	s_setprio 0
	s_barrier
	s_add_i32 s45, s45, s58
	s_mov_b32 m0, s45
	ds_read_b128 v[182:185], v172 offset:16384
	ds_read_b128 v[186:189], v172 offset:17408
	ds_read_b128 v[208:211], v172 offset:18432
	ds_read_b128 v[230:233], v172 offset:19456
	ds_read_b128 v[234:237], v172 offset:20480
	ds_read_b128 v[238:241], v172 offset:21504
	ds_read_b128 v[242:245], v172 offset:22528
	ds_read_b128 v[246:249], v172 offset:23552
	global_load_lds_dwordx4 v140, s[38:39]
	s_add_i32 m0, s45, 0x2000
	s_add_u32 s66, s38, 0x40000
	v_lshl_add_u64 v[212:213], s[38:39], 0, v[144:145]
	s_addc_u32 s67, s39, 0
	s_add_i32 s45, s68, s58
	global_load_lds_dwordx4 v144, s[38:39]
	s_mov_b32 m0, s45
	v_lshl_add_u64 v[250:251], s[40:41], 0, v[142:143]
	global_load_lds_dwordx4 v140, s[66:67]
	s_add_i32 m0, s45, 0x2000
	s_nop 0
	global_load_lds_dwordx4 v144, s[66:67]
	v_lshl_add_u64 v[228:229], s[40:41], 0, v[138:139]
	s_mov_b32 m0, s37
	s_nop 0
	global_load_lds_dwordx4 v138, s[40:41]
	s_mov_b32 m0, s59
	s_nop 0
	global_load_lds_dwordx4 v142, s[40:41]
	s_waitcnt vmcnt(8)
	s_waitcnt lgkmcnt(0)
	s_setprio 1
	s_barrier
	v_mfma_f32_16x16x32_bf16 v[60:63], v[130:133], v[182:185], 0
	v_mfma_f32_16x16x32_bf16 v[56:59], v[150:153], v[182:185], 0
	v_mfma_f32_16x16x32_bf16 v[44:47], v[130:133], v[208:211], 0
	v_mfma_f32_16x16x32_bf16 v[40:43], v[150:153], v[208:211], 0
	v_mfma_f32_16x16x32_bf16 v[28:31], v[130:133], v[234:237], 0
	v_mfma_f32_16x16x32_bf16 v[24:27], v[150:153], v[234:237], 0
	v_mfma_f32_16x16x32_bf16 v[12:15], v[130:133], v[242:245], 0
	v_mfma_f32_16x16x32_bf16 v[8:11], v[150:153], v[242:245], 0
	v_mfma_f32_16x16x32_bf16 v[60:63], v[134:137], v[186:189], v[60:63]
	v_mfma_f32_16x16x32_bf16 v[56:59], v[154:157], v[186:189], v[56:59]
	v_mfma_f32_16x16x32_bf16 v[44:47], v[134:137], v[230:233], v[44:47]
	v_mfma_f32_16x16x32_bf16 v[40:43], v[154:157], v[230:233], v[40:43]
	v_mfma_f32_16x16x32_bf16 v[28:31], v[134:137], v[238:241], v[28:31]
	v_mfma_f32_16x16x32_bf16 v[24:27], v[154:157], v[238:241], v[24:27]
	v_mfma_f32_16x16x32_bf16 v[12:15], v[134:137], v[246:249], v[12:15]
	v_mfma_f32_16x16x32_bf16 v[8:11], v[154:157], v[246:249], v[8:11]
	s_setprio 0
	s_setprio 1
	v_mfma_f32_16x16x32_bf16 v[52:55], v[158:161], v[182:185], 0
	v_mfma_f32_16x16x32_bf16 v[48:51], v[174:177], v[182:185], 0
	v_mfma_f32_16x16x32_bf16 v[36:39], v[158:161], v[208:211], 0
	v_mfma_f32_16x16x32_bf16 v[32:35], v[174:177], v[208:211], 0
	v_mfma_f32_16x16x32_bf16 v[20:23], v[158:161], v[234:237], 0
	v_mfma_f32_16x16x32_bf16 v[16:19], v[174:177], v[234:237], 0
	v_mfma_f32_16x16x32_bf16 v[4:7], v[158:161], v[242:245], 0
	v_mfma_f32_16x16x32_bf16 v[0:3], v[174:177], v[242:245], 0
	v_mfma_f32_16x16x32_bf16 v[52:55], v[162:165], v[186:189], v[52:55]
	v_mfma_f32_16x16x32_bf16 v[48:51], v[178:181], v[186:189], v[48:51]
	v_mfma_f32_16x16x32_bf16 v[36:39], v[162:165], v[230:233], v[36:39]
	v_mfma_f32_16x16x32_bf16 v[32:35], v[178:181], v[230:233], v[32:35]
	v_mfma_f32_16x16x32_bf16 v[20:23], v[162:165], v[238:241], v[20:23]
	v_mfma_f32_16x16x32_bf16 v[16:19], v[178:181], v[238:241], v[16:19]
	v_mfma_f32_16x16x32_bf16 v[4:7], v[162:165], v[246:249], v[4:7]
	v_mfma_f32_16x16x32_bf16 v[0:3], v[178:181], v[246:249], v[0:3]
	s_setprio 0
	s_barrier
	s_add_i32 s45, 0, 0x18000
	v_add_u32_e32 v112, s45, v169
	s_add_i32 s66, 0, 0x1c000
	ds_read_b128 v[130:133], v112
	ds_read_b128 v[134:137], v112 offset:1024
	ds_read_b128 v[150:153], v112 offset:2048
	ds_read_b128 v[154:157], v112 offset:3072
	v_add_u32_e32 v112, s66, v169
	ds_read_b128 v[158:161], v112
	ds_read_b128 v[162:165], v112 offset:1024
	ds_read_b128 v[174:177], v112 offset:2048
	ds_read_b128 v[178:181], v112 offset:3072
	s_add_u32 s40, s40, 0x40000
	s_addc_u32 s41, s41, 0
	s_mov_b32 m0, s60
	ds_read_b128 v[182:185], v172 offset:32768
	ds_read_b128 v[186:189], v172 offset:33792
	ds_read_b128 v[208:211], v172 offset:34816
	ds_read_b128 v[230:233], v172 offset:35840
	ds_read_b128 v[234:237], v172 offset:36864
	ds_read_b128 v[238:241], v172 offset:37888
	ds_read_b128 v[242:245], v172 offset:38912
	ds_read_b128 v[246:249], v172 offset:39936
	global_load_lds_dwordx4 v138, s[40:41]
	s_mov_b32 m0, s61
	s_nop 0
	global_load_lds_dwordx4 v142, s[40:41]
	s_waitcnt vmcnt(8)
	s_waitcnt lgkmcnt(0)
	s_setprio 1
	s_barrier
	v_mfma_f32_16x16x32_bf16 v[126:129], v[130:133], v[182:185], v[126:129]
	v_mfma_f32_16x16x32_bf16 v[122:125], v[150:153], v[182:185], v[122:125]
	v_mfma_f32_16x16x32_bf16 v[108:111], v[130:133], v[208:211], v[108:111]
	v_mfma_f32_16x16x32_bf16 v[104:107], v[150:153], v[208:211], v[104:107]
	v_mfma_f32_16x16x32_bf16 v[92:95], v[130:133], v[234:237], v[92:95]
	v_mfma_f32_16x16x32_bf16 v[88:91], v[150:153], v[234:237], v[88:91]
	v_mfma_f32_16x16x32_bf16 v[76:79], v[130:133], v[242:245], v[76:79]
	v_mfma_f32_16x16x32_bf16 v[72:75], v[150:153], v[242:245], v[72:75]
	v_mfma_f32_16x16x32_bf16 v[126:129], v[134:137], v[186:189], v[126:129]
	v_mfma_f32_16x16x32_bf16 v[122:125], v[154:157], v[186:189], v[122:125]
	v_mfma_f32_16x16x32_bf16 v[108:111], v[134:137], v[230:233], v[108:111]
	v_mfma_f32_16x16x32_bf16 v[104:107], v[154:157], v[230:233], v[104:107]
	v_mfma_f32_16x16x32_bf16 v[92:95], v[134:137], v[238:241], v[92:95]
	v_mfma_f32_16x16x32_bf16 v[88:91], v[154:157], v[238:241], v[88:91]
	v_mfma_f32_16x16x32_bf16 v[76:79], v[134:137], v[246:249], v[76:79]
	v_mfma_f32_16x16x32_bf16 v[72:75], v[154:157], v[246:249], v[72:75]
	s_setprio 0
	s_setprio 1
	v_mfma_f32_16x16x32_bf16 v[118:121], v[158:161], v[182:185], v[118:121]
	v_mfma_f32_16x16x32_bf16 v[114:117], v[174:177], v[182:185], v[114:117]
	v_mfma_f32_16x16x32_bf16 v[100:103], v[158:161], v[208:211], v[100:103]
	v_mfma_f32_16x16x32_bf16 v[96:99], v[174:177], v[208:211], v[96:99]
	v_mfma_f32_16x16x32_bf16 v[84:87], v[158:161], v[234:237], v[84:87]
	v_mfma_f32_16x16x32_bf16 v[80:83], v[174:177], v[234:237], v[80:83]
	v_mfma_f32_16x16x32_bf16 v[68:71], v[158:161], v[242:245], v[68:71]
	v_mfma_f32_16x16x32_bf16 v[64:67], v[174:177], v[242:245], v[64:67]
	v_mfma_f32_16x16x32_bf16 v[118:121], v[162:165], v[186:189], v[118:121]
	v_mfma_f32_16x16x32_bf16 v[114:117], v[178:181], v[186:189], v[114:117]
	v_mfma_f32_16x16x32_bf16 v[100:103], v[162:165], v[230:233], v[100:103]
	v_mfma_f32_16x16x32_bf16 v[96:99], v[178:181], v[230:233], v[96:99]
	v_mfma_f32_16x16x32_bf16 v[84:87], v[162:165], v[238:241], v[84:87]
	v_mfma_f32_16x16x32_bf16 v[80:83], v[178:181], v[238:241], v[80:83]
	v_mfma_f32_16x16x32_bf16 v[68:71], v[162:165], v[246:249], v[68:71]
	v_mfma_f32_16x16x32_bf16 v[64:67], v[178:181], v[246:249], v[64:67]
	s_setprio 0
	s_barrier
	s_add_i32 s40, s45, s58
	s_mov_b32 m0, s40
	ds_read_b128 v[182:185], v172 offset:49152
	ds_read_b128 v[186:189], v172 offset:50176
	ds_read_b128 v[208:211], v172 offset:51200
	ds_read_b128 v[230:233], v172 offset:52224
	ds_read_b128 v[234:237], v172 offset:53248
	ds_read_b128 v[238:241], v172 offset:54272
	ds_read_b128 v[242:245], v172 offset:55296
	ds_read_b128 v[246:249], v172 offset:56320
	s_add_u32 s98, s38, 0x80
	s_addc_u32 s99, s39, 0
	global_load_lds_dwordx4 v140, s[98:99]
	s_add_i32 m0, s40, 0x2000
	s_add_u32 s38, s38, 0x40080
	v_lshl_add_u64 v[166:167], v[212:213], 0, s[96:97]
	s_addc_u32 s39, s39, 0
	s_add_i32 s40, s66, s58
	global_load_lds_dwordx4 v[166:167], off
	s_mov_b32 m0, s40
	s_nop 0
	global_load_lds_dwordx4 v140, s[38:39]
	s_add_i32 m0, s40, 0x2000
	s_nop 0
	global_load_lds_dwordx4 v144, s[38:39]
	v_lshl_add_u64 v[166:167], v[228:229], 0, s[96:97]
	s_mov_b32 m0, s62
	s_nop 0
	global_load_lds_dwordx4 v[166:167], off
	v_lshl_add_u64 v[166:167], v[250:251], 0, s[96:97]
	s_mov_b32 m0, s63
	s_nop 0
	global_load_lds_dwordx4 v[166:167], off
	s_waitcnt vmcnt(8)
	s_waitcnt lgkmcnt(0)
	s_setprio 1
	s_barrier
	v_mfma_f32_16x16x32_bf16 v[60:63], v[130:133], v[182:185], v[60:63]
	v_mfma_f32_16x16x32_bf16 v[56:59], v[150:153], v[182:185], v[56:59]
	v_mfma_f32_16x16x32_bf16 v[44:47], v[130:133], v[208:211], v[44:47]
	v_mfma_f32_16x16x32_bf16 v[40:43], v[150:153], v[208:211], v[40:43]
	v_mfma_f32_16x16x32_bf16 v[28:31], v[130:133], v[234:237], v[28:31]
	v_mfma_f32_16x16x32_bf16 v[24:27], v[150:153], v[234:237], v[24:27]
	v_mfma_f32_16x16x32_bf16 v[12:15], v[130:133], v[242:245], v[12:15]
	v_mfma_f32_16x16x32_bf16 v[8:11], v[150:153], v[242:245], v[8:11]
	v_mfma_f32_16x16x32_bf16 v[60:63], v[134:137], v[186:189], v[60:63]
	v_mfma_f32_16x16x32_bf16 v[56:59], v[154:157], v[186:189], v[56:59]
	v_mfma_f32_16x16x32_bf16 v[44:47], v[134:137], v[230:233], v[44:47]
	v_mfma_f32_16x16x32_bf16 v[40:43], v[154:157], v[230:233], v[40:43]
	v_mfma_f32_16x16x32_bf16 v[28:31], v[134:137], v[238:241], v[28:31]
	v_mfma_f32_16x16x32_bf16 v[24:27], v[154:157], v[238:241], v[24:27]
	v_mfma_f32_16x16x32_bf16 v[12:15], v[134:137], v[246:249], v[12:15]
	v_mfma_f32_16x16x32_bf16 v[8:11], v[154:157], v[246:249], v[8:11]
	s_setprio 0
	s_setprio 1
	v_mfma_f32_16x16x32_bf16 v[52:55], v[158:161], v[182:185], v[52:55]
	v_mfma_f32_16x16x32_bf16 v[48:51], v[174:177], v[182:185], v[48:51]
	v_mfma_f32_16x16x32_bf16 v[36:39], v[158:161], v[208:211], v[36:39]
	v_mfma_f32_16x16x32_bf16 v[32:35], v[174:177], v[208:211], v[32:35]
	v_mfma_f32_16x16x32_bf16 v[20:23], v[158:161], v[234:237], v[20:23]
	v_mfma_f32_16x16x32_bf16 v[16:19], v[174:177], v[234:237], v[16:19]
	v_mfma_f32_16x16x32_bf16 v[4:7], v[158:161], v[242:245], v[4:7]
	v_mfma_f32_16x16x32_bf16 v[0:3], v[174:177], v[242:245], v[0:3]
	v_mfma_f32_16x16x32_bf16 v[52:55], v[162:165], v[186:189], v[52:55]
	v_mfma_f32_16x16x32_bf16 v[48:51], v[178:181], v[186:189], v[48:51]
	v_mfma_f32_16x16x32_bf16 v[36:39], v[162:165], v[230:233], v[36:39]
	v_mfma_f32_16x16x32_bf16 v[32:35], v[178:181], v[230:233], v[32:35]
	v_mfma_f32_16x16x32_bf16 v[20:23], v[162:165], v[238:241], v[20:23]
	v_mfma_f32_16x16x32_bf16 v[16:19], v[178:181], v[238:241], v[16:19]
	v_mfma_f32_16x16x32_bf16 v[4:7], v[162:165], v[246:249], v[4:7]
	v_mfma_f32_16x16x32_bf16 v[0:3], v[178:181], v[246:249], v[0:3]
	s_setprio 0
	s_barrier
	s_add_i32 s44, s44, 2
	s_add_u32 s42, s42, 0x100
	s_addc_u32 s43, s43, 0
	s_add_u32 s8, s8, 0x100
	s_addc_u32 s9, s9, 0
	s_cmp_gt_u32 s44, 13
	s_cbranch_scc0 .LBB0_2151
	s_branch .Lpeel_exit_2151
.LBB0_2151:
	s_add_u32 s38, s8, 0xfffc0080
	s_addc_u32 s39, s9, -1
	s_add_i32 s45, 0, 0x10000
	s_cmp_eq_u32 s44, 12
	s_cselect_b32 s41, s11, s39
	s_cselect_b32 s40, s29, s38
	v_add_u32_e32 v112, s45, v169
	s_cselect_b32 s39, s27, s43
	s_cselect_b32 s38, s35, s42
	s_add_i32 s68, 0, 0x14000
	ds_read_b128 v[130:133], v112
	ds_read_b128 v[134:137], v112 offset:1024
	ds_read_b128 v[150:153], v112 offset:2048
	ds_read_b128 v[154:157], v112 offset:3072
	v_add_u32_e32 v112, s68, v169
	ds_read_b128 v[158:161], v112
	ds_read_b128 v[162:165], v112 offset:1024
	ds_read_b128 v[174:177], v112 offset:2048
	ds_read_b128 v[178:181], v112 offset:3072
	s_add_i32 m0, s37, 0xc000
	ds_read_b128 v[182:185], v172
	ds_read_b128 v[186:189], v172 offset:1024
	ds_read_b128 v[208:211], v172 offset:2048
	ds_read_b128 v[230:233], v172 offset:3072
	ds_read_b128 v[234:237], v172 offset:4096
	ds_read_b128 v[238:241], v172 offset:5120
	ds_read_b128 v[242:245], v172 offset:6144
	ds_read_b128 v[246:249], v172 offset:7168
	global_load_lds_dwordx4 v148, s[8:9]
	s_add_i32 m0, s37, 0xe000
	s_nop 0
	global_load_lds_dwordx4 v146, s[8:9]
	s_waitcnt vmcnt(8)
	s_waitcnt lgkmcnt(0)
	s_setprio 1
	s_barrier
	v_mfma_f32_16x16x32_bf16 v[126:129], v[130:133], v[182:185], v[126:129]
	v_mfma_f32_16x16x32_bf16 v[122:125], v[150:153], v[182:185], v[122:125]
	v_mfma_f32_16x16x32_bf16 v[108:111], v[130:133], v[208:211], v[108:111]
	v_mfma_f32_16x16x32_bf16 v[104:107], v[150:153], v[208:211], v[104:107]
	v_mfma_f32_16x16x32_bf16 v[92:95], v[130:133], v[234:237], v[92:95]
	v_mfma_f32_16x16x32_bf16 v[88:91], v[150:153], v[234:237], v[88:91]
	v_mfma_f32_16x16x32_bf16 v[76:79], v[130:133], v[242:245], v[76:79]
	v_mfma_f32_16x16x32_bf16 v[72:75], v[150:153], v[242:245], v[72:75]
	v_mfma_f32_16x16x32_bf16 v[126:129], v[134:137], v[186:189], v[126:129]
	v_mfma_f32_16x16x32_bf16 v[122:125], v[154:157], v[186:189], v[122:125]
	v_mfma_f32_16x16x32_bf16 v[108:111], v[134:137], v[230:233], v[108:111]
	v_mfma_f32_16x16x32_bf16 v[104:107], v[154:157], v[230:233], v[104:107]
	v_mfma_f32_16x16x32_bf16 v[92:95], v[134:137], v[238:241], v[92:95]
	v_mfma_f32_16x16x32_bf16 v[88:91], v[154:157], v[238:241], v[88:91]
	v_mfma_f32_16x16x32_bf16 v[76:79], v[134:137], v[246:249], v[76:79]
	v_mfma_f32_16x16x32_bf16 v[72:75], v[154:157], v[246:249], v[72:75]
	s_setprio 0
	s_setprio 1
	v_mfma_f32_16x16x32_bf16 v[118:121], v[158:161], v[182:185], v[118:121]
	v_mfma_f32_16x16x32_bf16 v[114:117], v[174:177], v[182:185], v[114:117]
	v_mfma_f32_16x16x32_bf16 v[100:103], v[158:161], v[208:211], v[100:103]
	v_mfma_f32_16x16x32_bf16 v[96:99], v[174:177], v[208:211], v[96:99]
	v_mfma_f32_16x16x32_bf16 v[84:87], v[158:161], v[234:237], v[84:87]
	v_mfma_f32_16x16x32_bf16 v[80:83], v[174:177], v[234:237], v[80:83]
	v_mfma_f32_16x16x32_bf16 v[68:71], v[158:161], v[242:245], v[68:71]
	v_mfma_f32_16x16x32_bf16 v[64:67], v[174:177], v[242:245], v[64:67]
	v_mfma_f32_16x16x32_bf16 v[118:121], v[162:165], v[186:189], v[118:121]
	v_mfma_f32_16x16x32_bf16 v[114:117], v[178:181], v[186:189], v[114:117]
	v_mfma_f32_16x16x32_bf16 v[100:103], v[162:165], v[230:233], v[100:103]
	v_mfma_f32_16x16x32_bf16 v[96:99], v[178:181], v[230:233], v[96:99]
	v_mfma_f32_16x16x32_bf16 v[84:87], v[162:165], v[238:241], v[84:87]
	v_mfma_f32_16x16x32_bf16 v[80:83], v[178:181], v[238:241], v[80:83]
	v_mfma_f32_16x16x32_bf16 v[68:71], v[162:165], v[246:249], v[68:71]
	v_mfma_f32_16x16x32_bf16 v[64:67], v[178:181], v[246:249], v[64:67]
	s_setprio 0
	s_barrier
	s_add_i32 s45, s45, s58
	s_mov_b32 m0, s45
	ds_read_b128 v[182:185], v172 offset:16384
	ds_read_b128 v[186:189], v172 offset:17408
	ds_read_b128 v[208:211], v172 offset:18432
	ds_read_b128 v[230:233], v172 offset:19456
	ds_read_b128 v[234:237], v172 offset:20480
	ds_read_b128 v[238:241], v172 offset:21504
	ds_read_b128 v[242:245], v172 offset:22528
	ds_read_b128 v[246:249], v172 offset:23552
	global_load_lds_dwordx4 v140, s[38:39]
	s_add_i32 m0, s45, 0x2000
	s_add_u32 s66, s38, 0x40000
	v_lshl_add_u64 v[212:213], s[38:39], 0, v[144:145]
	s_addc_u32 s67, s39, 0
	s_add_i32 s45, s68, s58
	global_load_lds_dwordx4 v144, s[38:39]
	s_mov_b32 m0, s45
	v_lshl_add_u64 v[250:251], s[40:41], 0, v[142:143]
	global_load_lds_dwordx4 v140, s[66:67]
	s_add_i32 m0, s45, 0x2000
	s_nop 0
	global_load_lds_dwordx4 v144, s[66:67]
	v_lshl_add_u64 v[228:229], s[40:41], 0, v[138:139]
	s_mov_b32 m0, s37
	s_nop 0
	global_load_lds_dwordx4 v138, s[40:41]
	s_mov_b32 m0, s59
	s_nop 0
	global_load_lds_dwordx4 v142, s[40:41]
	s_waitcnt vmcnt(8)
	s_waitcnt lgkmcnt(0)
	s_setprio 1
	s_barrier
	v_mfma_f32_16x16x32_bf16 v[60:63], v[130:133], v[182:185], v[60:63]
	v_mfma_f32_16x16x32_bf16 v[56:59], v[150:153], v[182:185], v[56:59]
	v_mfma_f32_16x16x32_bf16 v[44:47], v[130:133], v[208:211], v[44:47]
	v_mfma_f32_16x16x32_bf16 v[40:43], v[150:153], v[208:211], v[40:43]
	v_mfma_f32_16x16x32_bf16 v[28:31], v[130:133], v[234:237], v[28:31]
	v_mfma_f32_16x16x32_bf16 v[24:27], v[150:153], v[234:237], v[24:27]
	v_mfma_f32_16x16x32_bf16 v[12:15], v[130:133], v[242:245], v[12:15]
	v_mfma_f32_16x16x32_bf16 v[8:11], v[150:153], v[242:245], v[8:11]
	v_mfma_f32_16x16x32_bf16 v[60:63], v[134:137], v[186:189], v[60:63]
	v_mfma_f32_16x16x32_bf16 v[56:59], v[154:157], v[186:189], v[56:59]
	v_mfma_f32_16x16x32_bf16 v[44:47], v[134:137], v[230:233], v[44:47]
	v_mfma_f32_16x16x32_bf16 v[40:43], v[154:157], v[230:233], v[40:43]
	v_mfma_f32_16x16x32_bf16 v[28:31], v[134:137], v[238:241], v[28:31]
	v_mfma_f32_16x16x32_bf16 v[24:27], v[154:157], v[238:241], v[24:27]
	v_mfma_f32_16x16x32_bf16 v[12:15], v[134:137], v[246:249], v[12:15]
	v_mfma_f32_16x16x32_bf16 v[8:11], v[154:157], v[246:249], v[8:11]
	s_setprio 0
	s_setprio 1
	v_mfma_f32_16x16x32_bf16 v[52:55], v[158:161], v[182:185], v[52:55]
	v_mfma_f32_16x16x32_bf16 v[48:51], v[174:177], v[182:185], v[48:51]
	v_mfma_f32_16x16x32_bf16 v[36:39], v[158:161], v[208:211], v[36:39]
	v_mfma_f32_16x16x32_bf16 v[32:35], v[174:177], v[208:211], v[32:35]
	v_mfma_f32_16x16x32_bf16 v[20:23], v[158:161], v[234:237], v[20:23]
	v_mfma_f32_16x16x32_bf16 v[16:19], v[174:177], v[234:237], v[16:19]
	v_mfma_f32_16x16x32_bf16 v[4:7], v[158:161], v[242:245], v[4:7]
	v_mfma_f32_16x16x32_bf16 v[0:3], v[174:177], v[242:245], v[0:3]
	v_mfma_f32_16x16x32_bf16 v[52:55], v[162:165], v[186:189], v[52:55]
	v_mfma_f32_16x16x32_bf16 v[48:51], v[178:181], v[186:189], v[48:51]
	v_mfma_f32_16x16x32_bf16 v[36:39], v[162:165], v[230:233], v[36:39]
	v_mfma_f32_16x16x32_bf16 v[32:35], v[178:181], v[230:233], v[32:35]
	v_mfma_f32_16x16x32_bf16 v[20:23], v[162:165], v[238:241], v[20:23]
	v_mfma_f32_16x16x32_bf16 v[16:19], v[178:181], v[238:241], v[16:19]
	v_mfma_f32_16x16x32_bf16 v[4:7], v[162:165], v[246:249], v[4:7]
	v_mfma_f32_16x16x32_bf16 v[0:3], v[178:181], v[246:249], v[0:3]
	s_setprio 0
	s_barrier
	s_add_i32 s45, 0, 0x18000
	v_add_u32_e32 v112, s45, v169
	s_add_i32 s66, 0, 0x1c000
	ds_read_b128 v[130:133], v112
	ds_read_b128 v[134:137], v112 offset:1024
	ds_read_b128 v[150:153], v112 offset:2048
	ds_read_b128 v[154:157], v112 offset:3072
	v_add_u32_e32 v112, s66, v169
	ds_read_b128 v[158:161], v112
	ds_read_b128 v[162:165], v112 offset:1024
	ds_read_b128 v[174:177], v112 offset:2048
	ds_read_b128 v[178:181], v112 offset:3072
	s_add_u32 s40, s40, 0x40000
	s_addc_u32 s41, s41, 0
	s_mov_b32 m0, s60
	ds_read_b128 v[182:185], v172 offset:32768
	ds_read_b128 v[186:189], v172 offset:33792
	ds_read_b128 v[208:211], v172 offset:34816
	ds_read_b128 v[230:233], v172 offset:35840
	ds_read_b128 v[234:237], v172 offset:36864
	ds_read_b128 v[238:241], v172 offset:37888
	ds_read_b128 v[242:245], v172 offset:38912
	ds_read_b128 v[246:249], v172 offset:39936
	global_load_lds_dwordx4 v138, s[40:41]
	s_mov_b32 m0, s61
	s_nop 0
	global_load_lds_dwordx4 v142, s[40:41]
	s_waitcnt vmcnt(8)
	s_waitcnt lgkmcnt(0)
	s_setprio 1
	s_barrier
	v_mfma_f32_16x16x32_bf16 v[126:129], v[130:133], v[182:185], v[126:129]
	v_mfma_f32_16x16x32_bf16 v[122:125], v[150:153], v[182:185], v[122:125]
	v_mfma_f32_16x16x32_bf16 v[108:111], v[130:133], v[208:211], v[108:111]
	v_mfma_f32_16x16x32_bf16 v[104:107], v[150:153], v[208:211], v[104:107]
	v_mfma_f32_16x16x32_bf16 v[92:95], v[130:133], v[234:237], v[92:95]
	v_mfma_f32_16x16x32_bf16 v[88:91], v[150:153], v[234:237], v[88:91]
	v_mfma_f32_16x16x32_bf16 v[76:79], v[130:133], v[242:245], v[76:79]
	v_mfma_f32_16x16x32_bf16 v[72:75], v[150:153], v[242:245], v[72:75]
	v_mfma_f32_16x16x32_bf16 v[126:129], v[134:137], v[186:189], v[126:129]
	v_mfma_f32_16x16x32_bf16 v[122:125], v[154:157], v[186:189], v[122:125]
	v_mfma_f32_16x16x32_bf16 v[108:111], v[134:137], v[230:233], v[108:111]
	v_mfma_f32_16x16x32_bf16 v[104:107], v[154:157], v[230:233], v[104:107]
	v_mfma_f32_16x16x32_bf16 v[92:95], v[134:137], v[238:241], v[92:95]
	v_mfma_f32_16x16x32_bf16 v[88:91], v[154:157], v[238:241], v[88:91]
	v_mfma_f32_16x16x32_bf16 v[76:79], v[134:137], v[246:249], v[76:79]
	v_mfma_f32_16x16x32_bf16 v[72:75], v[154:157], v[246:249], v[72:75]
	s_setprio 0
	s_setprio 1
	v_mfma_f32_16x16x32_bf16 v[118:121], v[158:161], v[182:185], v[118:121]
	v_mfma_f32_16x16x32_bf16 v[114:117], v[174:177], v[182:185], v[114:117]
	v_mfma_f32_16x16x32_bf16 v[100:103], v[158:161], v[208:211], v[100:103]
	v_mfma_f32_16x16x32_bf16 v[96:99], v[174:177], v[208:211], v[96:99]
	v_mfma_f32_16x16x32_bf16 v[84:87], v[158:161], v[234:237], v[84:87]
	v_mfma_f32_16x16x32_bf16 v[80:83], v[174:177], v[234:237], v[80:83]
	v_mfma_f32_16x16x32_bf16 v[68:71], v[158:161], v[242:245], v[68:71]
	v_mfma_f32_16x16x32_bf16 v[64:67], v[174:177], v[242:245], v[64:67]
	v_mfma_f32_16x16x32_bf16 v[118:121], v[162:165], v[186:189], v[118:121]
	v_mfma_f32_16x16x32_bf16 v[114:117], v[178:181], v[186:189], v[114:117]
	v_mfma_f32_16x16x32_bf16 v[100:103], v[162:165], v[230:233], v[100:103]
	v_mfma_f32_16x16x32_bf16 v[96:99], v[178:181], v[230:233], v[96:99]
	v_mfma_f32_16x16x32_bf16 v[84:87], v[162:165], v[238:241], v[84:87]
	v_mfma_f32_16x16x32_bf16 v[80:83], v[178:181], v[238:241], v[80:83]
	v_mfma_f32_16x16x32_bf16 v[68:71], v[162:165], v[246:249], v[68:71]
	v_mfma_f32_16x16x32_bf16 v[64:67], v[178:181], v[246:249], v[64:67]
	s_setprio 0
	s_barrier
	s_add_i32 s40, s45, s58
	s_mov_b32 m0, s40
	ds_read_b128 v[182:185], v172 offset:49152
	ds_read_b128 v[186:189], v172 offset:50176
	ds_read_b128 v[208:211], v172 offset:51200
	ds_read_b128 v[230:233], v172 offset:52224
	ds_read_b128 v[234:237], v172 offset:53248
	ds_read_b128 v[238:241], v172 offset:54272
	ds_read_b128 v[242:245], v172 offset:55296
	ds_read_b128 v[246:249], v172 offset:56320
	s_add_u32 s98, s38, 0x80
	s_addc_u32 s99, s39, 0
	global_load_lds_dwordx4 v140, s[98:99]
	s_add_i32 m0, s40, 0x2000
	s_add_u32 s38, s38, 0x40080
	v_lshl_add_u64 v[166:167], v[212:213], 0, s[96:97]
	s_addc_u32 s39, s39, 0
	s_add_i32 s40, s66, s58
	global_load_lds_dwordx4 v[166:167], off
	s_mov_b32 m0, s40
	s_nop 0
	global_load_lds_dwordx4 v140, s[38:39]
	s_add_i32 m0, s40, 0x2000
	s_nop 0
	global_load_lds_dwordx4 v144, s[38:39]
	v_lshl_add_u64 v[166:167], v[228:229], 0, s[96:97]
	s_mov_b32 m0, s62
	s_nop 0
	global_load_lds_dwordx4 v[166:167], off
	v_lshl_add_u64 v[166:167], v[250:251], 0, s[96:97]
	s_mov_b32 m0, s63
	s_nop 0
	global_load_lds_dwordx4 v[166:167], off
	s_waitcnt vmcnt(8)
	s_waitcnt lgkmcnt(0)
	s_setprio 1
	s_barrier
	v_mfma_f32_16x16x32_bf16 v[60:63], v[130:133], v[182:185], v[60:63]
	v_mfma_f32_16x16x32_bf16 v[56:59], v[150:153], v[182:185], v[56:59]
	v_mfma_f32_16x16x32_bf16 v[44:47], v[130:133], v[208:211], v[44:47]
	v_mfma_f32_16x16x32_bf16 v[40:43], v[150:153], v[208:211], v[40:43]
	v_mfma_f32_16x16x32_bf16 v[28:31], v[130:133], v[234:237], v[28:31]
	v_mfma_f32_16x16x32_bf16 v[24:27], v[150:153], v[234:237], v[24:27]
	v_mfma_f32_16x16x32_bf16 v[12:15], v[130:133], v[242:245], v[12:15]
	v_mfma_f32_16x16x32_bf16 v[8:11], v[150:153], v[242:245], v[8:11]
	v_mfma_f32_16x16x32_bf16 v[60:63], v[134:137], v[186:189], v[60:63]
	v_mfma_f32_16x16x32_bf16 v[56:59], v[154:157], v[186:189], v[56:59]
	v_mfma_f32_16x16x32_bf16 v[44:47], v[134:137], v[230:233], v[44:47]
	v_mfma_f32_16x16x32_bf16 v[40:43], v[154:157], v[230:233], v[40:43]
	v_mfma_f32_16x16x32_bf16 v[28:31], v[134:137], v[238:241], v[28:31]
	v_mfma_f32_16x16x32_bf16 v[24:27], v[154:157], v[238:241], v[24:27]
	v_mfma_f32_16x16x32_bf16 v[12:15], v[134:137], v[246:249], v[12:15]
	v_mfma_f32_16x16x32_bf16 v[8:11], v[154:157], v[246:249], v[8:11]
	s_setprio 0
	s_setprio 1
	v_mfma_f32_16x16x32_bf16 v[52:55], v[158:161], v[182:185], v[52:55]
	v_mfma_f32_16x16x32_bf16 v[48:51], v[174:177], v[182:185], v[48:51]
	v_mfma_f32_16x16x32_bf16 v[36:39], v[158:161], v[208:211], v[36:39]
	v_mfma_f32_16x16x32_bf16 v[32:35], v[174:177], v[208:211], v[32:35]
	v_mfma_f32_16x16x32_bf16 v[20:23], v[158:161], v[234:237], v[20:23]
	v_mfma_f32_16x16x32_bf16 v[16:19], v[174:177], v[234:237], v[16:19]
	v_mfma_f32_16x16x32_bf16 v[4:7], v[158:161], v[242:245], v[4:7]
	v_mfma_f32_16x16x32_bf16 v[0:3], v[174:177], v[242:245], v[0:3]
	v_mfma_f32_16x16x32_bf16 v[52:55], v[162:165], v[186:189], v[52:55]
	v_mfma_f32_16x16x32_bf16 v[48:51], v[178:181], v[186:189], v[48:51]
	v_mfma_f32_16x16x32_bf16 v[36:39], v[162:165], v[230:233], v[36:39]
	v_mfma_f32_16x16x32_bf16 v[32:35], v[178:181], v[230:233], v[32:35]
	v_mfma_f32_16x16x32_bf16 v[20:23], v[162:165], v[238:241], v[20:23]
	v_mfma_f32_16x16x32_bf16 v[16:19], v[178:181], v[238:241], v[16:19]
	v_mfma_f32_16x16x32_bf16 v[4:7], v[162:165], v[246:249], v[4:7]
	v_mfma_f32_16x16x32_bf16 v[0:3], v[178:181], v[246:249], v[0:3]
	s_setprio 0
	s_barrier
	s_add_i32 s44, s44, 2
	s_add_u32 s42, s42, 0x100
	s_addc_u32 s43, s43, 0
	s_add_u32 s8, s8, 0x100
	s_addc_u32 s9, s9, 0
	s_cmp_gt_u32 s44, 13
	s_cbranch_scc0 .LBB0_2151

.LBB0_2368:
	s_ashr_i32 s23, s22, 31
	s_lshl_b64 s[24:25], s[22:23], 19
	s_add_u32 s24, s49, s24
	s_addc_u32 s25, s50, s25
	s_and_b64 s[26:27], s[2:3], exec
	s_cselect_b32 s5, s25, s29
	s_cselect_b32 s23, s24, s28
	s_ashr_i32 s15, s14, 31
	s_lshl_b64 s[26:27], s[14:15], 19
	s_add_u32 s26, s51, s26
	s_addc_u32 s27, s52, s27
	s_and_b64 s[30:31], s[2:3], exec
	s_cselect_b32 s15, s27, s7
	s_cselect_b32 s47, s26, s6
	s_add_u32 s54, s6, 0x100
	s_addc_u32 s55, s7, 0
	s_add_u32 s6, s28, 0x40080
	s_addc_u32 s7, s29, 0
	s_mov_b32 s56, -2
	s_waitcnt lgkmcnt(0)
	s_add_u32 s28, s6, 0xfffc0080
	s_addc_u32 s29, s7, -1
	s_add_i32 s57, 0, 0x10000
	s_cmp_eq_u32 s56, 12
	s_cselect_b32 s31, s5, s29
	s_cselect_b32 s30, s23, s28
	v_add_u32_e32 v146, s57, v148
	s_cselect_b32 s29, s15, s55
	s_cselect_b32 s28, s47, s54
	s_add_i32 s60, 0, 0x14000
	ds_read_b128 v[142:145], v146
	ds_read_b128 v[152:155], v146 offset:1024
	ds_read_b128 v[156:159], v146 offset:2048
	ds_read_b128 v[160:163], v146 offset:3072
	v_add_u32_e32 v146, s60, v148
	ds_read_b128 v[164:167], v146
	ds_read_b128 v[168:171], v146 offset:1024
	ds_read_b128 v[172:175], v146 offset:2048
	ds_read_b128 v[176:179], v146 offset:3072
	s_add_i32 m0, s21, 0xc000
	ds_read_b128 v[180:183], v151
	ds_read_b128 v[184:187], v151 offset:1024
	ds_read_b128 v[208:211], v151 offset:2048
	ds_read_b128 v[230:233], v151 offset:3072
	ds_read_b128 v[234:237], v151 offset:4096
	ds_read_b128 v[238:241], v151 offset:5120
	ds_read_b128 v[242:245], v151 offset:6144
	ds_read_b128 v[246:249], v151 offset:7168
	global_load_lds_dwordx4 v140, s[6:7]
	s_add_i32 m0, s21, 0xe000
	s_nop 0
	global_load_lds_dwordx4 v138, s[6:7]
	s_waitcnt vmcnt(8)
	s_waitcnt lgkmcnt(0)
	s_setprio 1
	s_barrier
	v_mfma_f32_16x16x32_bf16 v[126:129], v[142:145], v[180:183], 0
	v_mfma_f32_16x16x32_bf16 v[122:125], v[156:159], v[180:183], 0
	v_mfma_f32_16x16x32_bf16 v[108:111], v[142:145], v[208:211], 0
	v_mfma_f32_16x16x32_bf16 v[104:107], v[156:159], v[208:211], 0
	v_mfma_f32_16x16x32_bf16 v[92:95], v[142:145], v[234:237], 0
	v_mfma_f32_16x16x32_bf16 v[88:91], v[156:159], v[234:237], 0
	v_mfma_f32_16x16x32_bf16 v[76:79], v[142:145], v[242:245], 0
	v_mfma_f32_16x16x32_bf16 v[72:75], v[156:159], v[242:245], 0
	v_mfma_f32_16x16x32_bf16 v[126:129], v[152:155], v[184:187], v[126:129]
	v_mfma_f32_16x16x32_bf16 v[122:125], v[160:163], v[184:187], v[122:125]
	v_mfma_f32_16x16x32_bf16 v[108:111], v[152:155], v[230:233], v[108:111]
	v_mfma_f32_16x16x32_bf16 v[104:107], v[160:163], v[230:233], v[104:107]
	v_mfma_f32_16x16x32_bf16 v[92:95], v[152:155], v[238:241], v[92:95]
	v_mfma_f32_16x16x32_bf16 v[88:91], v[160:163], v[238:241], v[88:91]
	v_mfma_f32_16x16x32_bf16 v[76:79], v[152:155], v[246:249], v[76:79]
	v_mfma_f32_16x16x32_bf16 v[72:75], v[160:163], v[246:249], v[72:75]
	s_setprio 0
	s_setprio 1
	v_mfma_f32_16x16x32_bf16 v[118:121], v[164:167], v[180:183], 0
	v_mfma_f32_16x16x32_bf16 v[114:117], v[172:175], v[180:183], 0
	v_mfma_f32_16x16x32_bf16 v[100:103], v[164:167], v[208:211], 0
	v_mfma_f32_16x16x32_bf16 v[96:99], v[172:175], v[208:211], 0
	v_mfma_f32_16x16x32_bf16 v[84:87], v[164:167], v[234:237], 0
	v_mfma_f32_16x16x32_bf16 v[80:83], v[172:175], v[234:237], 0
	v_mfma_f32_16x16x32_bf16 v[68:71], v[164:167], v[242:245], 0
	v_mfma_f32_16x16x32_bf16 v[64:67], v[172:175], v[242:245], 0
	v_mfma_f32_16x16x32_bf16 v[118:121], v[168:171], v[184:187], v[118:121]
	v_mfma_f32_16x16x32_bf16 v[114:117], v[176:179], v[184:187], v[114:117]
	v_mfma_f32_16x16x32_bf16 v[100:103], v[168:171], v[230:233], v[100:103]
	v_mfma_f32_16x16x32_bf16 v[96:99], v[176:179], v[230:233], v[96:99]
	v_mfma_f32_16x16x32_bf16 v[84:87], v[168:171], v[238:241], v[84:87]
	v_mfma_f32_16x16x32_bf16 v[80:83], v[176:179], v[238:241], v[80:83]
	v_mfma_f32_16x16x32_bf16 v[68:71], v[168:171], v[246:249], v[68:71]
	v_mfma_f32_16x16x32_bf16 v[64:67], v[176:179], v[246:249], v[64:67]
	s_setprio 0
	s_barrier
	s_add_i32 s57, s57, s39
	s_mov_b32 m0, s57
	ds_read_b128 v[180:183], v151 offset:16384
	ds_read_b128 v[184:187], v151 offset:17408
	ds_read_b128 v[208:211], v151 offset:18432
	ds_read_b128 v[230:233], v151 offset:19456
	ds_read_b128 v[234:237], v151 offset:20480
	ds_read_b128 v[238:241], v151 offset:21504
	ds_read_b128 v[242:245], v151 offset:22528
	ds_read_b128 v[246:249], v151 offset:23552
	global_load_lds_dwordx4 v112, s[28:29]
	s_add_i32 m0, s57, 0x2000
	s_add_u32 s58, s28, 0x40000
	v_lshl_add_u64 v[212:213], s[28:29], 0, v[134:135]
	s_addc_u32 s59, s29, 0
	s_add_i32 s57, s60, s39
	global_load_lds_dwordx4 v134, s[28:29]
	s_mov_b32 m0, s57
	v_lshl_add_u64 v[252:253], s[30:31], 0, v[132:133]
	global_load_lds_dwordx4 v112, s[58:59]
	s_add_i32 m0, s57, 0x2000
	s_nop 0
	global_load_lds_dwordx4 v134, s[58:59]
	v_lshl_add_u64 v[250:251], s[30:31], 0, v[130:131]
	s_mov_b32 m0, s21
	s_nop 0
	global_load_lds_dwordx4 v130, s[30:31]
	s_mov_b32 m0, s40
	s_nop 0
	global_load_lds_dwordx4 v132, s[30:31]
	s_waitcnt vmcnt(8)
	s_waitcnt lgkmcnt(0)
	s_setprio 1
	s_barrier
	v_mfma_f32_16x16x32_bf16 v[60:63], v[142:145], v[180:183], 0
	v_mfma_f32_16x16x32_bf16 v[56:59], v[156:159], v[180:183], 0
	v_mfma_f32_16x16x32_bf16 v[44:47], v[142:145], v[208:211], 0
	v_mfma_f32_16x16x32_bf16 v[40:43], v[156:159], v[208:211], 0
	v_mfma_f32_16x16x32_bf16 v[28:31], v[142:145], v[234:237], 0
	v_mfma_f32_16x16x32_bf16 v[24:27], v[156:159], v[234:237], 0
	v_mfma_f32_16x16x32_bf16 v[12:15], v[142:145], v[242:245], 0
	v_mfma_f32_16x16x32_bf16 v[8:11], v[156:159], v[242:245], 0
	v_mfma_f32_16x16x32_bf16 v[60:63], v[152:155], v[184:187], v[60:63]
	v_mfma_f32_16x16x32_bf16 v[56:59], v[160:163], v[184:187], v[56:59]
	v_mfma_f32_16x16x32_bf16 v[44:47], v[152:155], v[230:233], v[44:47]
	v_mfma_f32_16x16x32_bf16 v[40:43], v[160:163], v[230:233], v[40:43]
	v_mfma_f32_16x16x32_bf16 v[28:31], v[152:155], v[238:241], v[28:31]
	v_mfma_f32_16x16x32_bf16 v[24:27], v[160:163], v[238:241], v[24:27]
	v_mfma_f32_16x16x32_bf16 v[12:15], v[152:155], v[246:249], v[12:15]
	v_mfma_f32_16x16x32_bf16 v[8:11], v[160:163], v[246:249], v[8:11]
	s_setprio 0
	s_setprio 1
	v_mfma_f32_16x16x32_bf16 v[52:55], v[164:167], v[180:183], 0
	v_mfma_f32_16x16x32_bf16 v[48:51], v[172:175], v[180:183], 0
	v_mfma_f32_16x16x32_bf16 v[36:39], v[164:167], v[208:211], 0
	v_mfma_f32_16x16x32_bf16 v[32:35], v[172:175], v[208:211], 0
	v_mfma_f32_16x16x32_bf16 v[20:23], v[164:167], v[234:237], 0
	v_mfma_f32_16x16x32_bf16 v[16:19], v[172:175], v[234:237], 0
	v_mfma_f32_16x16x32_bf16 v[4:7], v[164:167], v[242:245], 0
	v_mfma_f32_16x16x32_bf16 v[0:3], v[172:175], v[242:245], 0
	v_mfma_f32_16x16x32_bf16 v[52:55], v[168:171], v[184:187], v[52:55]
	v_mfma_f32_16x16x32_bf16 v[48:51], v[176:179], v[184:187], v[48:51]
	v_mfma_f32_16x16x32_bf16 v[36:39], v[168:171], v[230:233], v[36:39]
	v_mfma_f32_16x16x32_bf16 v[32:35], v[176:179], v[230:233], v[32:35]
	v_mfma_f32_16x16x32_bf16 v[20:23], v[168:171], v[238:241], v[20:23]
	v_mfma_f32_16x16x32_bf16 v[16:19], v[176:179], v[238:241], v[16:19]
	v_mfma_f32_16x16x32_bf16 v[4:7], v[168:171], v[246:249], v[4:7]
	v_mfma_f32_16x16x32_bf16 v[0:3], v[176:179], v[246:249], v[0:3]
	s_setprio 0
	s_barrier
	s_add_i32 s57, 0, 0x18000
	v_add_u32_e32 v146, s57, v148
	s_add_i32 s58, 0, 0x1c000
	ds_read_b128 v[142:145], v146
	ds_read_b128 v[152:155], v146 offset:1024
	ds_read_b128 v[156:159], v146 offset:2048
	ds_read_b128 v[160:163], v146 offset:3072
	v_add_u32_e32 v146, s58, v148
	ds_read_b128 v[164:167], v146
	ds_read_b128 v[168:171], v146 offset:1024
	ds_read_b128 v[172:175], v146 offset:2048
	ds_read_b128 v[176:179], v146 offset:3072
	s_add_u32 s30, s30, 0x40000
	s_addc_u32 s31, s31, 0
	s_mov_b32 m0, s41
	ds_read_b128 v[180:183], v151 offset:32768
	ds_read_b128 v[184:187], v151 offset:33792
	ds_read_b128 v[208:211], v151 offset:34816
	ds_read_b128 v[230:233], v151 offset:35840
	ds_read_b128 v[234:237], v151 offset:36864
	ds_read_b128 v[238:241], v151 offset:37888
	ds_read_b128 v[242:245], v151 offset:38912
	ds_read_b128 v[246:249], v151 offset:39936
	global_load_lds_dwordx4 v130, s[30:31]
	s_mov_b32 m0, s42
	s_nop 0
	global_load_lds_dwordx4 v132, s[30:31]
	s_waitcnt vmcnt(8)
	s_waitcnt lgkmcnt(0)
	s_setprio 1
	s_barrier
	v_mfma_f32_16x16x32_bf16 v[126:129], v[142:145], v[180:183], v[126:129]
	v_mfma_f32_16x16x32_bf16 v[122:125], v[156:159], v[180:183], v[122:125]
	v_mfma_f32_16x16x32_bf16 v[108:111], v[142:145], v[208:211], v[108:111]
	v_mfma_f32_16x16x32_bf16 v[104:107], v[156:159], v[208:211], v[104:107]
	v_mfma_f32_16x16x32_bf16 v[92:95], v[142:145], v[234:237], v[92:95]
	v_mfma_f32_16x16x32_bf16 v[88:91], v[156:159], v[234:237], v[88:91]
	v_mfma_f32_16x16x32_bf16 v[76:79], v[142:145], v[242:245], v[76:79]
	v_mfma_f32_16x16x32_bf16 v[72:75], v[156:159], v[242:245], v[72:75]
	v_mfma_f32_16x16x32_bf16 v[126:129], v[152:155], v[184:187], v[126:129]
	v_mfma_f32_16x16x32_bf16 v[122:125], v[160:163], v[184:187], v[122:125]
	v_mfma_f32_16x16x32_bf16 v[108:111], v[152:155], v[230:233], v[108:111]
	v_mfma_f32_16x16x32_bf16 v[104:107], v[160:163], v[230:233], v[104:107]
	v_mfma_f32_16x16x32_bf16 v[92:95], v[152:155], v[238:241], v[92:95]
	v_mfma_f32_16x16x32_bf16 v[88:91], v[160:163], v[238:241], v[88:91]
	v_mfma_f32_16x16x32_bf16 v[76:79], v[152:155], v[246:249], v[76:79]
	v_mfma_f32_16x16x32_bf16 v[72:75], v[160:163], v[246:249], v[72:75]
	s_setprio 0
	s_setprio 1
	v_mfma_f32_16x16x32_bf16 v[118:121], v[164:167], v[180:183], v[118:121]
	v_mfma_f32_16x16x32_bf16 v[114:117], v[172:175], v[180:183], v[114:117]
	v_mfma_f32_16x16x32_bf16 v[100:103], v[164:167], v[208:211], v[100:103]
	v_mfma_f32_16x16x32_bf16 v[96:99], v[172:175], v[208:211], v[96:99]
	v_mfma_f32_16x16x32_bf16 v[84:87], v[164:167], v[234:237], v[84:87]
	v_mfma_f32_16x16x32_bf16 v[80:83], v[172:175], v[234:237], v[80:83]
	v_mfma_f32_16x16x32_bf16 v[68:71], v[164:167], v[242:245], v[68:71]
	v_mfma_f32_16x16x32_bf16 v[64:67], v[172:175], v[242:245], v[64:67]
	v_mfma_f32_16x16x32_bf16 v[118:121], v[168:171], v[184:187], v[118:121]
	v_mfma_f32_16x16x32_bf16 v[114:117], v[176:179], v[184:187], v[114:117]
	v_mfma_f32_16x16x32_bf16 v[100:103], v[168:171], v[230:233], v[100:103]
	v_mfma_f32_16x16x32_bf16 v[96:99], v[176:179], v[230:233], v[96:99]
	v_mfma_f32_16x16x32_bf16 v[84:87], v[168:171], v[238:241], v[84:87]
	v_mfma_f32_16x16x32_bf16 v[80:83], v[176:179], v[238:241], v[80:83]
	v_mfma_f32_16x16x32_bf16 v[68:71], v[168:171], v[246:249], v[68:71]
	v_mfma_f32_16x16x32_bf16 v[64:67], v[176:179], v[246:249], v[64:67]
	s_setprio 0
	s_barrier
	s_add_i32 s30, s57, s39
	s_mov_b32 m0, s30
	ds_read_b128 v[180:183], v151 offset:49152
	ds_read_b128 v[184:187], v151 offset:50176
	ds_read_b128 v[208:211], v151 offset:51200
	ds_read_b128 v[230:233], v151 offset:52224
	ds_read_b128 v[234:237], v151 offset:53248
	ds_read_b128 v[238:241], v151 offset:54272
	ds_read_b128 v[242:245], v151 offset:55296
	ds_read_b128 v[246:249], v151 offset:56320
	s_add_u32 s98, s28, 0x80
	s_addc_u32 s99, s29, 0
	global_load_lds_dwordx4 v112, s[98:99]
	s_add_i32 m0, s30, 0x2000
	s_add_u32 s28, s28, 0x40080
	v_lshl_add_u64 v[188:189], v[212:213], 0, s[96:97]
	s_addc_u32 s29, s29, 0
	s_add_i32 s30, s58, s39
	global_load_lds_dwordx4 v[188:189], off
	s_mov_b32 m0, s30
	s_nop 0
	global_load_lds_dwordx4 v112, s[28:29]
	s_add_i32 m0, s30, 0x2000
	s_nop 0
	global_load_lds_dwordx4 v134, s[28:29]
	v_lshl_add_u64 v[188:189], v[250:251], 0, s[96:97]
	s_mov_b32 m0, s43
	s_nop 0
	global_load_lds_dwordx4 v[188:189], off
	v_lshl_add_u64 v[188:189], v[252:253], 0, s[96:97]
	s_mov_b32 m0, s44
	s_nop 0
	global_load_lds_dwordx4 v[188:189], off
	s_waitcnt vmcnt(8)
	s_waitcnt lgkmcnt(0)
	s_setprio 1
	s_barrier
	v_mfma_f32_16x16x32_bf16 v[60:63], v[142:145], v[180:183], v[60:63]
	v_mfma_f32_16x16x32_bf16 v[56:59], v[156:159], v[180:183], v[56:59]
	v_mfma_f32_16x16x32_bf16 v[44:47], v[142:145], v[208:211], v[44:47]
	v_mfma_f32_16x16x32_bf16 v[40:43], v[156:159], v[208:211], v[40:43]
	v_mfma_f32_16x16x32_bf16 v[28:31], v[142:145], v[234:237], v[28:31]
	v_mfma_f32_16x16x32_bf16 v[24:27], v[156:159], v[234:237], v[24:27]
	v_mfma_f32_16x16x32_bf16 v[12:15], v[142:145], v[242:245], v[12:15]
	v_mfma_f32_16x16x32_bf16 v[8:11], v[156:159], v[242:245], v[8:11]
	v_mfma_f32_16x16x32_bf16 v[60:63], v[152:155], v[184:187], v[60:63]
	v_mfma_f32_16x16x32_bf16 v[56:59], v[160:163], v[184:187], v[56:59]
	v_mfma_f32_16x16x32_bf16 v[44:47], v[152:155], v[230:233], v[44:47]
	v_mfma_f32_16x16x32_bf16 v[40:43], v[160:163], v[230:233], v[40:43]
	v_mfma_f32_16x16x32_bf16 v[28:31], v[152:155], v[238:241], v[28:31]
	v_mfma_f32_16x16x32_bf16 v[24:27], v[160:163], v[238:241], v[24:27]
	v_mfma_f32_16x16x32_bf16 v[12:15], v[152:155], v[246:249], v[12:15]
	v_mfma_f32_16x16x32_bf16 v[8:11], v[160:163], v[246:249], v[8:11]
	s_setprio 0
	s_setprio 1
	v_mfma_f32_16x16x32_bf16 v[52:55], v[164:167], v[180:183], v[52:55]
	v_mfma_f32_16x16x32_bf16 v[48:51], v[172:175], v[180:183], v[48:51]
	v_mfma_f32_16x16x32_bf16 v[36:39], v[164:167], v[208:211], v[36:39]
	v_mfma_f32_16x16x32_bf16 v[32:35], v[172:175], v[208:211], v[32:35]
	v_mfma_f32_16x16x32_bf16 v[20:23], v[164:167], v[234:237], v[20:23]
	v_mfma_f32_16x16x32_bf16 v[16:19], v[172:175], v[234:237], v[16:19]
	v_mfma_f32_16x16x32_bf16 v[4:7], v[164:167], v[242:245], v[4:7]
	v_mfma_f32_16x16x32_bf16 v[0:3], v[172:175], v[242:245], v[0:3]
	v_mfma_f32_16x16x32_bf16 v[52:55], v[168:171], v[184:187], v[52:55]
	v_mfma_f32_16x16x32_bf16 v[48:51], v[176:179], v[184:187], v[48:51]
	v_mfma_f32_16x16x32_bf16 v[36:39], v[168:171], v[230:233], v[36:39]
	v_mfma_f32_16x16x32_bf16 v[32:35], v[176:179], v[230:233], v[32:35]
	v_mfma_f32_16x16x32_bf16 v[20:23], v[168:171], v[238:241], v[20:23]
	v_mfma_f32_16x16x32_bf16 v[16:19], v[176:179], v[238:241], v[16:19]
	v_mfma_f32_16x16x32_bf16 v[4:7], v[168:171], v[246:249], v[4:7]
	v_mfma_f32_16x16x32_bf16 v[0:3], v[176:179], v[246:249], v[0:3]
	s_setprio 0
	s_barrier
	s_add_i32 s56, s56, 2
	s_add_u32 s54, s54, 0x100
	s_addc_u32 s55, s55, 0
	s_add_u32 s6, s6, 0x100
	s_addc_u32 s7, s7, 0
	s_cmp_gt_u32 s56, 13
	s_cbranch_scc0 .LBB0_2369
	s_branch .Lpeel_exit_2369
.LBB0_2369:
	s_add_u32 s28, s6, 0xfffc0080
	s_addc_u32 s29, s7, -1
	s_add_i32 s57, 0, 0x10000
	s_cmp_eq_u32 s56, 12
	s_cselect_b32 s31, s5, s29
	s_cselect_b32 s30, s23, s28
	v_add_u32_e32 v146, s57, v148
	s_cselect_b32 s29, s15, s55
	s_cselect_b32 s28, s47, s54
	s_add_i32 s60, 0, 0x14000
	ds_read_b128 v[142:145], v146
	ds_read_b128 v[152:155], v146 offset:1024
	ds_read_b128 v[156:159], v146 offset:2048
	ds_read_b128 v[160:163], v146 offset:3072
	v_add_u32_e32 v146, s60, v148
	ds_read_b128 v[164:167], v146
	ds_read_b128 v[168:171], v146 offset:1024
	ds_read_b128 v[172:175], v146 offset:2048
	ds_read_b128 v[176:179], v146 offset:3072
	s_add_i32 m0, s21, 0xc000
	ds_read_b128 v[180:183], v151
	ds_read_b128 v[184:187], v151 offset:1024
	ds_read_b128 v[208:211], v151 offset:2048
	ds_read_b128 v[230:233], v151 offset:3072
	ds_read_b128 v[234:237], v151 offset:4096
	ds_read_b128 v[238:241], v151 offset:5120
	ds_read_b128 v[242:245], v151 offset:6144
	ds_read_b128 v[246:249], v151 offset:7168
	global_load_lds_dwordx4 v140, s[6:7]
	s_add_i32 m0, s21, 0xe000
	s_nop 0
	global_load_lds_dwordx4 v138, s[6:7]
	s_waitcnt vmcnt(8)
	s_waitcnt lgkmcnt(0)
	s_setprio 1
	s_barrier
	v_mfma_f32_16x16x32_bf16 v[126:129], v[142:145], v[180:183], v[126:129]
	v_mfma_f32_16x16x32_bf16 v[122:125], v[156:159], v[180:183], v[122:125]
	v_mfma_f32_16x16x32_bf16 v[108:111], v[142:145], v[208:211], v[108:111]
	v_mfma_f32_16x16x32_bf16 v[104:107], v[156:159], v[208:211], v[104:107]
	v_mfma_f32_16x16x32_bf16 v[92:95], v[142:145], v[234:237], v[92:95]
	v_mfma_f32_16x16x32_bf16 v[88:91], v[156:159], v[234:237], v[88:91]
	v_mfma_f32_16x16x32_bf16 v[76:79], v[142:145], v[242:245], v[76:79]
	v_mfma_f32_16x16x32_bf16 v[72:75], v[156:159], v[242:245], v[72:75]
	v_mfma_f32_16x16x32_bf16 v[126:129], v[152:155], v[184:187], v[126:129]
	v_mfma_f32_16x16x32_bf16 v[122:125], v[160:163], v[184:187], v[122:125]
	v_mfma_f32_16x16x32_bf16 v[108:111], v[152:155], v[230:233], v[108:111]
	v_mfma_f32_16x16x32_bf16 v[104:107], v[160:163], v[230:233], v[104:107]
	v_mfma_f32_16x16x32_bf16 v[92:95], v[152:155], v[238:241], v[92:95]
	v_mfma_f32_16x16x32_bf16 v[88:91], v[160:163], v[238:241], v[88:91]
	v_mfma_f32_16x16x32_bf16 v[76:79], v[152:155], v[246:249], v[76:79]
	v_mfma_f32_16x16x32_bf16 v[72:75], v[160:163], v[246:249], v[72:75]
	s_setprio 0
	s_setprio 1
	v_mfma_f32_16x16x32_bf16 v[118:121], v[164:167], v[180:183], v[118:121]
	v_mfma_f32_16x16x32_bf16 v[114:117], v[172:175], v[180:183], v[114:117]
	v_mfma_f32_16x16x32_bf16 v[100:103], v[164:167], v[208:211], v[100:103]
	v_mfma_f32_16x16x32_bf16 v[96:99], v[172:175], v[208:211], v[96:99]
	v_mfma_f32_16x16x32_bf16 v[84:87], v[164:167], v[234:237], v[84:87]
	v_mfma_f32_16x16x32_bf16 v[80:83], v[172:175], v[234:237], v[80:83]
	v_mfma_f32_16x16x32_bf16 v[68:71], v[164:167], v[242:245], v[68:71]
	v_mfma_f32_16x16x32_bf16 v[64:67], v[172:175], v[242:245], v[64:67]
	v_mfma_f32_16x16x32_bf16 v[118:121], v[168:171], v[184:187], v[118:121]
	v_mfma_f32_16x16x32_bf16 v[114:117], v[176:179], v[184:187], v[114:117]
	v_mfma_f32_16x16x32_bf16 v[100:103], v[168:171], v[230:233], v[100:103]
	v_mfma_f32_16x16x32_bf16 v[96:99], v[176:179], v[230:233], v[96:99]
	v_mfma_f32_16x16x32_bf16 v[84:87], v[168:171], v[238:241], v[84:87]
	v_mfma_f32_16x16x32_bf16 v[80:83], v[176:179], v[238:241], v[80:83]
	v_mfma_f32_16x16x32_bf16 v[68:71], v[168:171], v[246:249], v[68:71]
	v_mfma_f32_16x16x32_bf16 v[64:67], v[176:179], v[246:249], v[64:67]
	s_setprio 0
	s_barrier
	s_add_i32 s57, s57, s39
	s_mov_b32 m0, s57
	ds_read_b128 v[180:183], v151 offset:16384
	ds_read_b128 v[184:187], v151 offset:17408
	ds_read_b128 v[208:211], v151 offset:18432
	ds_read_b128 v[230:233], v151 offset:19456
	ds_read_b128 v[234:237], v151 offset:20480
	ds_read_b128 v[238:241], v151 offset:21504
	ds_read_b128 v[242:245], v151 offset:22528
	ds_read_b128 v[246:249], v151 offset:23552
	global_load_lds_dwordx4 v112, s[28:29]
	s_add_i32 m0, s57, 0x2000
	s_add_u32 s58, s28, 0x40000
	v_lshl_add_u64 v[212:213], s[28:29], 0, v[134:135]
	s_addc_u32 s59, s29, 0
	s_add_i32 s57, s60, s39
	global_load_lds_dwordx4 v134, s[28:29]
	s_mov_b32 m0, s57
	v_lshl_add_u64 v[252:253], s[30:31], 0, v[132:133]
	global_load_lds_dwordx4 v112, s[58:59]
	s_add_i32 m0, s57, 0x2000
	s_nop 0
	global_load_lds_dwordx4 v134, s[58:59]
	v_lshl_add_u64 v[250:251], s[30:31], 0, v[130:131]
	s_mov_b32 m0, s21
	s_nop 0
	global_load_lds_dwordx4 v130, s[30:31]
	s_mov_b32 m0, s40
	s_nop 0
	global_load_lds_dwordx4 v132, s[30:31]
	s_waitcnt vmcnt(8)
	s_waitcnt lgkmcnt(0)
	s_setprio 1
	s_barrier
	v_mfma_f32_16x16x32_bf16 v[60:63], v[142:145], v[180:183], v[60:63]
	v_mfma_f32_16x16x32_bf16 v[56:59], v[156:159], v[180:183], v[56:59]
	v_mfma_f32_16x16x32_bf16 v[44:47], v[142:145], v[208:211], v[44:47]
	v_mfma_f32_16x16x32_bf16 v[40:43], v[156:159], v[208:211], v[40:43]
	v_mfma_f32_16x16x32_bf16 v[28:31], v[142:145], v[234:237], v[28:31]
	v_mfma_f32_16x16x32_bf16 v[24:27], v[156:159], v[234:237], v[24:27]
	v_mfma_f32_16x16x32_bf16 v[12:15], v[142:145], v[242:245], v[12:15]
	v_mfma_f32_16x16x32_bf16 v[8:11], v[156:159], v[242:245], v[8:11]
	v_mfma_f32_16x16x32_bf16 v[60:63], v[152:155], v[184:187], v[60:63]
	v_mfma_f32_16x16x32_bf16 v[56:59], v[160:163], v[184:187], v[56:59]
	v_mfma_f32_16x16x32_bf16 v[44:47], v[152:155], v[230:233], v[44:47]
	v_mfma_f32_16x16x32_bf16 v[40:43], v[160:163], v[230:233], v[40:43]
	v_mfma_f32_16x16x32_bf16 v[28:31], v[152:155], v[238:241], v[28:31]
	v_mfma_f32_16x16x32_bf16 v[24:27], v[160:163], v[238:241], v[24:27]
	v_mfma_f32_16x16x32_bf16 v[12:15], v[152:155], v[246:249], v[12:15]
	v_mfma_f32_16x16x32_bf16 v[8:11], v[160:163], v[246:249], v[8:11]
	s_setprio 0
	s_setprio 1
	v_mfma_f32_16x16x32_bf16 v[52:55], v[164:167], v[180:183], v[52:55]
	v_mfma_f32_16x16x32_bf16 v[48:51], v[172:175], v[180:183], v[48:51]
	v_mfma_f32_16x16x32_bf16 v[36:39], v[164:167], v[208:211], v[36:39]
	v_mfma_f32_16x16x32_bf16 v[32:35], v[172:175], v[208:211], v[32:35]
	v_mfma_f32_16x16x32_bf16 v[20:23], v[164:167], v[234:237], v[20:23]
	v_mfma_f32_16x16x32_bf16 v[16:19], v[172:175], v[234:237], v[16:19]
	v_mfma_f32_16x16x32_bf16 v[4:7], v[164:167], v[242:245], v[4:7]
	v_mfma_f32_16x16x32_bf16 v[0:3], v[172:175], v[242:245], v[0:3]
	v_mfma_f32_16x16x32_bf16 v[52:55], v[168:171], v[184:187], v[52:55]
	v_mfma_f32_16x16x32_bf16 v[48:51], v[176:179], v[184:187], v[48:51]
	v_mfma_f32_16x16x32_bf16 v[36:39], v[168:171], v[230:233], v[36:39]
	v_mfma_f32_16x16x32_bf16 v[32:35], v[176:179], v[230:233], v[32:35]
	v_mfma_f32_16x16x32_bf16 v[20:23], v[168:171], v[238:241], v[20:23]
	v_mfma_f32_16x16x32_bf16 v[16:19], v[176:179], v[238:241], v[16:19]
	v_mfma_f32_16x16x32_bf16 v[4:7], v[168:171], v[246:249], v[4:7]
	v_mfma_f32_16x16x32_bf16 v[0:3], v[176:179], v[246:249], v[0:3]
	s_setprio 0
	s_barrier
	s_add_i32 s57, 0, 0x18000
	v_add_u32_e32 v146, s57, v148
	s_add_i32 s58, 0, 0x1c000
	ds_read_b128 v[142:145], v146
	ds_read_b128 v[152:155], v146 offset:1024
	ds_read_b128 v[156:159], v146 offset:2048
	ds_read_b128 v[160:163], v146 offset:3072
	v_add_u32_e32 v146, s58, v148
	ds_read_b128 v[164:167], v146
	ds_read_b128 v[168:171], v146 offset:1024
	ds_read_b128 v[172:175], v146 offset:2048
	ds_read_b128 v[176:179], v146 offset:3072
	s_add_u32 s30, s30, 0x40000
	s_addc_u32 s31, s31, 0
	s_mov_b32 m0, s41
	ds_read_b128 v[180:183], v151 offset:32768
	ds_read_b128 v[184:187], v151 offset:33792
	ds_read_b128 v[208:211], v151 offset:34816
	ds_read_b128 v[230:233], v151 offset:35840
	ds_read_b128 v[234:237], v151 offset:36864
	ds_read_b128 v[238:241], v151 offset:37888
	ds_read_b128 v[242:245], v151 offset:38912
	ds_read_b128 v[246:249], v151 offset:39936
	global_load_lds_dwordx4 v130, s[30:31]
	s_mov_b32 m0, s42
	s_nop 0
	global_load_lds_dwordx4 v132, s[30:31]
	s_waitcnt vmcnt(8)
	s_waitcnt lgkmcnt(0)
	s_setprio 1
	s_barrier
	v_mfma_f32_16x16x32_bf16 v[126:129], v[142:145], v[180:183], v[126:129]
	v_mfma_f32_16x16x32_bf16 v[122:125], v[156:159], v[180:183], v[122:125]
	v_mfma_f32_16x16x32_bf16 v[108:111], v[142:145], v[208:211], v[108:111]
	v_mfma_f32_16x16x32_bf16 v[104:107], v[156:159], v[208:211], v[104:107]
	v_mfma_f32_16x16x32_bf16 v[92:95], v[142:145], v[234:237], v[92:95]
	v_mfma_f32_16x16x32_bf16 v[88:91], v[156:159], v[234:237], v[88:91]
	v_mfma_f32_16x16x32_bf16 v[76:79], v[142:145], v[242:245], v[76:79]
	v_mfma_f32_16x16x32_bf16 v[72:75], v[156:159], v[242:245], v[72:75]
	v_mfma_f32_16x16x32_bf16 v[126:129], v[152:155], v[184:187], v[126:129]
	v_mfma_f32_16x16x32_bf16 v[122:125], v[160:163], v[184:187], v[122:125]
	v_mfma_f32_16x16x32_bf16 v[108:111], v[152:155], v[230:233], v[108:111]
	v_mfma_f32_16x16x32_bf16 v[104:107], v[160:163], v[230:233], v[104:107]
	v_mfma_f32_16x16x32_bf16 v[92:95], v[152:155], v[238:241], v[92:95]
	v_mfma_f32_16x16x32_bf16 v[88:91], v[160:163], v[238:241], v[88:91]
	v_mfma_f32_16x16x32_bf16 v[76:79], v[152:155], v[246:249], v[76:79]
	v_mfma_f32_16x16x32_bf16 v[72:75], v[160:163], v[246:249], v[72:75]
	s_setprio 0
	s_setprio 1
	v_mfma_f32_16x16x32_bf16 v[118:121], v[164:167], v[180:183], v[118:121]
	v_mfma_f32_16x16x32_bf16 v[114:117], v[172:175], v[180:183], v[114:117]
	v_mfma_f32_16x16x32_bf16 v[100:103], v[164:167], v[208:211], v[100:103]
	v_mfma_f32_16x16x32_bf16 v[96:99], v[172:175], v[208:211], v[96:99]
	v_mfma_f32_16x16x32_bf16 v[84:87], v[164:167], v[234:237], v[84:87]
	v_mfma_f32_16x16x32_bf16 v[80:83], v[172:175], v[234:237], v[80:83]
	v_mfma_f32_16x16x32_bf16 v[68:71], v[164:167], v[242:245], v[68:71]
	v_mfma_f32_16x16x32_bf16 v[64:67], v[172:175], v[242:245], v[64:67]
	v_mfma_f32_16x16x32_bf16 v[118:121], v[168:171], v[184:187], v[118:121]
	v_mfma_f32_16x16x32_bf16 v[114:117], v[176:179], v[184:187], v[114:117]
	v_mfma_f32_16x16x32_bf16 v[100:103], v[168:171], v[230:233], v[100:103]
	v_mfma_f32_16x16x32_bf16 v[96:99], v[176:179], v[230:233], v[96:99]
	v_mfma_f32_16x16x32_bf16 v[84:87], v[168:171], v[238:241], v[84:87]
	v_mfma_f32_16x16x32_bf16 v[80:83], v[176:179], v[238:241], v[80:83]
	v_mfma_f32_16x16x32_bf16 v[68:71], v[168:171], v[246:249], v[68:71]
	v_mfma_f32_16x16x32_bf16 v[64:67], v[176:179], v[246:249], v[64:67]
	s_setprio 0
	s_barrier
	s_add_i32 s30, s57, s39
	s_mov_b32 m0, s30
	ds_read_b128 v[180:183], v151 offset:49152
	ds_read_b128 v[184:187], v151 offset:50176
	ds_read_b128 v[208:211], v151 offset:51200
	ds_read_b128 v[230:233], v151 offset:52224
	ds_read_b128 v[234:237], v151 offset:53248
	ds_read_b128 v[238:241], v151 offset:54272
	ds_read_b128 v[242:245], v151 offset:55296
	ds_read_b128 v[246:249], v151 offset:56320
	s_add_u32 s98, s28, 0x80
	s_addc_u32 s99, s29, 0
	global_load_lds_dwordx4 v112, s[98:99]
	s_add_i32 m0, s30, 0x2000
	s_add_u32 s28, s28, 0x40080
	v_lshl_add_u64 v[188:189], v[212:213], 0, s[96:97]
	s_addc_u32 s29, s29, 0
	s_add_i32 s30, s58, s39
	global_load_lds_dwordx4 v[188:189], off
	s_mov_b32 m0, s30
	s_nop 0
	global_load_lds_dwordx4 v112, s[28:29]
	s_add_i32 m0, s30, 0x2000
	s_nop 0
	global_load_lds_dwordx4 v134, s[28:29]
	v_lshl_add_u64 v[188:189], v[250:251], 0, s[96:97]
	s_mov_b32 m0, s43
	s_nop 0
	global_load_lds_dwordx4 v[188:189], off
	v_lshl_add_u64 v[188:189], v[252:253], 0, s[96:97]
	s_mov_b32 m0, s44
	s_nop 0
	global_load_lds_dwordx4 v[188:189], off
	s_waitcnt vmcnt(8)
	s_waitcnt lgkmcnt(0)
	s_setprio 1
	s_barrier
	v_mfma_f32_16x16x32_bf16 v[60:63], v[142:145], v[180:183], v[60:63]
	v_mfma_f32_16x16x32_bf16 v[56:59], v[156:159], v[180:183], v[56:59]
	v_mfma_f32_16x16x32_bf16 v[44:47], v[142:145], v[208:211], v[44:47]
	v_mfma_f32_16x16x32_bf16 v[40:43], v[156:159], v[208:211], v[40:43]
	v_mfma_f32_16x16x32_bf16 v[28:31], v[142:145], v[234:237], v[28:31]
	v_mfma_f32_16x16x32_bf16 v[24:27], v[156:159], v[234:237], v[24:27]
	v_mfma_f32_16x16x32_bf16 v[12:15], v[142:145], v[242:245], v[12:15]
	v_mfma_f32_16x16x32_bf16 v[8:11], v[156:159], v[242:245], v[8:11]
	v_mfma_f32_16x16x32_bf16 v[60:63], v[152:155], v[184:187], v[60:63]
	v_mfma_f32_16x16x32_bf16 v[56:59], v[160:163], v[184:187], v[56:59]
	v_mfma_f32_16x16x32_bf16 v[44:47], v[152:155], v[230:233], v[44:47]
	v_mfma_f32_16x16x32_bf16 v[40:43], v[160:163], v[230:233], v[40:43]
	v_mfma_f32_16x16x32_bf16 v[28:31], v[152:155], v[238:241], v[28:31]
	v_mfma_f32_16x16x32_bf16 v[24:27], v[160:163], v[238:241], v[24:27]
	v_mfma_f32_16x16x32_bf16 v[12:15], v[152:155], v[246:249], v[12:15]
	v_mfma_f32_16x16x32_bf16 v[8:11], v[160:163], v[246:249], v[8:11]
	s_setprio 0
	s_setprio 1
	v_mfma_f32_16x16x32_bf16 v[52:55], v[164:167], v[180:183], v[52:55]
	v_mfma_f32_16x16x32_bf16 v[48:51], v[172:175], v[180:183], v[48:51]
	v_mfma_f32_16x16x32_bf16 v[36:39], v[164:167], v[208:211], v[36:39]
	v_mfma_f32_16x16x32_bf16 v[32:35], v[172:175], v[208:211], v[32:35]
	v_mfma_f32_16x16x32_bf16 v[20:23], v[164:167], v[234:237], v[20:23]
	v_mfma_f32_16x16x32_bf16 v[16:19], v[172:175], v[234:237], v[16:19]
	v_mfma_f32_16x16x32_bf16 v[4:7], v[164:167], v[242:245], v[4:7]
	v_mfma_f32_16x16x32_bf16 v[0:3], v[172:175], v[242:245], v[0:3]
	v_mfma_f32_16x16x32_bf16 v[52:55], v[168:171], v[184:187], v[52:55]
	v_mfma_f32_16x16x32_bf16 v[48:51], v[176:179], v[184:187], v[48:51]
	v_mfma_f32_16x16x32_bf16 v[36:39], v[168:171], v[230:233], v[36:39]
	v_mfma_f32_16x16x32_bf16 v[32:35], v[176:179], v[230:233], v[32:35]
	v_mfma_f32_16x16x32_bf16 v[20:23], v[168:171], v[238:241], v[20:23]
	v_mfma_f32_16x16x32_bf16 v[16:19], v[176:179], v[238:241], v[16:19]
	v_mfma_f32_16x16x32_bf16 v[4:7], v[168:171], v[246:249], v[4:7]
	v_mfma_f32_16x16x32_bf16 v[0:3], v[176:179], v[246:249], v[0:3]
	s_setprio 0
	s_barrier
	s_add_i32 s56, s56, 2
	s_add_u32 s54, s54, 0x100
	s_addc_u32 s55, s55, 0
	s_add_u32 s6, s6, 0x100
	s_addc_u32 s7, s7, 0
	s_cmp_gt_u32 s56, 13
	s_cbranch_scc0 .LBB0_2369
